# first load segment's 16 ds_read_b128 hoisted above the tile-scheduler scalar code in every GEMM phase
# speedup vs baseline: 1.0023x; 1.0023x over previous
;     __device__ __forceinline__ bool next(int i, pg8::Unit& u) const { if (!base.next(i >> 2, u)) return false; u.sub = i & 3; return true; }
;     __host__ __device__ bool next(int i, Unit& u) const {
;         const long L = (long)i * G + c; if (L >= nwg) return false;
;         int wgid = (int)L; { const int q = nwg / NXCD, r = nwg % NXCD, xcd = wgid % NXCD, off = wgid / NXCD; wgid = (xcd < r ? xcd * (q + 1) : r * (q + 1) + (xcd - r) * q) + off; }
;         const int nig = WGM * nN, gid = wgid / nig, fm = gid * WGM, gsz = (nM - fm) < WGM ? (nM - fm) : WGM;
;         u.pm = fm + ((wgid % nig) % gsz); u.pn = (wgid % nig) / gsz; u.sub = 0; return true;
; template <class Epi, class Sched, bool ALIGN_EPI = false, bool SP2 = false>
; __device__ __forceinline__ void gemm_phase(PG8_LAS unsigned char* lds, const Gemm g, const Sched& S, const Epi& E, const int tid) {
;     ...
;         const bool has_next = S.next(ui + 1, nxt);
.LBB0_332:
	ds_read_b128 v[150:153], v161
	ds_read_b128 v[172:175], v161 offset:1024
	ds_read_b128 v[176:179], v161 offset:2048
	ds_read_b128 v[180:183], v161 offset:3072
	ds_read_b128 v[184:187], v163
	ds_read_b128 v[192:195], v163 offset:1024
	ds_read_b128 v[196:199], v163 offset:2048
	ds_read_b128 v[200:203], v163 offset:3072
	ds_read_b128 v[204:207], v167
	ds_read_b128 v[208:211], v167 offset:1024
	ds_read_b128 v[212:215], v167 offset:2048
	ds_read_b128 v[216:219], v167 offset:3072
	ds_read_b128 v[220:223], v167 offset:4096
	ds_read_b128 v[224:227], v167 offset:5120
	ds_read_b128 v[228:231], v167 offset:6144
	ds_read_b128 v[232:235], v167 offset:7168
	v_lshl_add_u32 v10, s36, 8, v1
	v_mov_b32_e32 v11, 0
	v_lshlrev_b32_e32 v10, 6, v10
	v_mov_b32_e32 v14, 0x2000
	v_mov_b32_e32 v15, 0
	v_lshl_add_u64 v[12:13], v[140:141], 0, v[10:11]
	v_lshl_add_u64 v[14:15], v[12:13], 0, v[14:15]
	global_load_dwordx4 v[6:9], v[12:13], off
	global_load_dwordx4 v[18:21], v[12:13], off offset:1024
	global_load_dwordx4 v[22:25], v[12:13], off offset:2048
	global_load_dwordx4 v[34:37], v[12:13], off offset:3072
	global_load_dwordx4 v[38:41], v[14:15], off
	global_load_dwordx4 v[50:53], v[14:15], off offset:1024
	global_load_dwordx4 v[54:57], v[14:15], off offset:2048
	global_load_dwordx4 v[58:61], v[14:15], off offset:3072
	s_add_i32 s61, s61, 1
	s_mul_i32 s2, s61, s57
	s_mul_hi_u32 s3, s61, s44
	s_add_i32 s3, s3, s2
	s_mul_i32 s2, s61, s44
	s_add_u32 s30, s2, s25
	s_addc_u32 s31, s3, s45
	v_cmp_gt_i64_e32 vcc, s[30:31], v[148:149]
	v_cmp_lt_i64_e64 s[2:3], s[30:31], v[146:147]
	s_cbranch_vccnz .LBB0_338
	s_ashr_i32 s15, s30, 31
	s_lshr_b32 s15, s15, 29
	s_add_i32 s15, s30, s15
	s_and_b32 s18, s15, -8
	s_sub_i32 s18, s30, s18
	s_cmp_gt_i32 s18, 3
	s_mov_b64 s[26:27], -1
	s_cbranch_scc0 .LBB0_335
	s_mul_i32 s19, s18, 0x215
	s_add_i32 s19, s19, 4
	s_mov_b64 s[26:27], 0

; #define PG8_STAGE(bufoff, gbase, voff) do { _Pragma("unroll") for (int _i = 0; _i < 2; ++_i) \
;         __builtin_amdgcn_global_load_lds((const unsigned*)((const char*)(gbase) + (voff)[_i]), (PG8_LAS unsigned*)(lds + (bufoff) + ldsw + _i * 8192), 16, 0, 0); } while (0)
; #define PG8_LDA(dst, b, h) do { _Pragma("unroll") for (int m = 0; m < 4; ++m) _Pragma("unroll") for (int k = 0; k < 2; ++k) dst[m][k] = *(const PG8_LAS bf16x8*)(lds + PG8_SA(b, h) + aoff + m * 2048 + k * 1024); } while (0)
; #define PG8_LDB(dst, b, h) do { _Pragma("unroll") for (int n = 0; n < 2; ++n) _Pragma("unroll") for (int k = 0; k < 2; ++k) dst[n][k] = *(const PG8_LAS bf16x8*)(lds + PG8_SB(b, h) + boff + n * 2048 + k * 1024); } while (0)
; #define PG8_WAIT_V(n) asm volatile("s_waitcnt vmcnt(" #n ")" ::: "memory")
; #define PG8_WAIT_L(n) asm volatile("s_waitcnt lgkmcnt(" #n ")" ::: "memory")
; #define PG8_BAR __builtin_amdgcn_s_barrier()
; #define PG8_SCHED __builtin_amdgcn_sched_barrier(0)
; template <class Epi, class Sched, bool ALIGN_EPI = false, bool SP2 = false>
; __device__ __forceinline__ void gemm_phase(PG8_LAS unsigned char* lds, const Gemm g, const Sched& S, const Epi& E, const int tid) {
;     ...
;         const bool has_next = S.next(ui + 1, nxt);
;         const char* nA = has_next ? S.aptr(nxt) : cA; const char* nB = has_next ? S.bptr(nxt) : cB;
;         for (int t = 0; t < nt; t += 2) {
;             const bool last = (t == nt - 2);
;             const char* a1 = cA + (size_t)(t + 1) * kstep;
;             const char* a2 = last ? nA : cA + (size_t)(t + 2) * kstep; const char* b2 = last ? nB : cB + (size_t)(t + 2) * kstep;
;             const char* a3 = a2 + kstep; const char* b3 = b2 + kstep;
;             if (last && has_next) S.a_ready(nxt);
;             if constexpr (SP2) {
;             PG8_LDB(B0, 0, 0); PG8_LDB(B1, 0, 1); PG8_SCHED; PG8_LDA(At, 0, 0); PG8_STAGE(PG8_SA(1, 1), a1 + hstep, voffA);
;             PG8_WAIT_V(8); PG8_WAIT_L(0); PG8_BAR; PG8_MMA(0, 0, At, B0); PG8_MMA(0, 1, At, B1); PG8_BAR; PG8_SCHED;
;             PG8_LDA(At, 0, 1); PG8_STAGE(PG8_SB(0, 0), b2, voffB); PG8_STAGE(PG8_SB(0, 1), b2 + hstep, voffB); PG8_STAGE(PG8_SA(0, 0), a2, voffA);
;             PG8_WAIT_V(8); PG8_WAIT_L(0); PG8_BAR; PG8_MMA(1, 0, At, B0); PG8_MMA(1, 1, At, B1); PG8_BAR; PG8_SCHED;
.LBB0_338:
	s_ashr_i32 s29, s28, 31
	s_lshl_b64 s[18:19], s[28:29], 19
	s_add_u32 s30, s46, s18
	s_addc_u32 s31, s47, s19
	s_and_b64 s[18:19], s[2:3], exec
	s_cselect_b32 s29, s31, s41
	s_cselect_b32 s62, s30, s40
	s_ashr_i32 s27, s26, 31
	s_lshl_b64 s[18:19], s[26:27], 19
	s_add_u32 s34, s48, s18
	s_addc_u32 s35, s49, s19
	s_and_b64 s[18:19], s[2:3], exec
	s_cselect_b32 s27, s35, s39
	s_cselect_b32 s63, s34, s38
	s_add_u32 s64, s38, 0x100
	s_addc_u32 s65, s39, 0
	s_add_u32 s38, s40, 0x40080
	s_addc_u32 s39, s41, 0
	s_mov_b32 s66, -2
	s_add_u32 s15, s38, 0xfffc0080
	s_addc_u32 s18, s39, -1
	s_cmp_eq_u32 s66, 12
	s_cselect_b32 s43, s29, s18
	s_cselect_b32 s42, s62, s15
	s_cselect_b32 s41, s27, s65
	s_cselect_b32 s40, s63, s64
	v_lshl_add_u64 v[154:155], s[38:39], 0, v[144:145]
	s_add_i32 m0, s51, 0xc000
	global_load_lds_dwordx4 v[154:155], off
	v_lshl_add_u64 v[154:155], s[38:39], 0, v[142:143]
	s_add_i32 m0, s51, 0xe000
	s_nop 0
	global_load_lds_dwordx4 v[154:155], off
	s_waitcnt vmcnt(16)
	s_waitcnt lgkmcnt(0)
	s_barrier
	s_setprio 1
	s_waitcnt lgkmcnt(0)
	v_mfma_f32_16x16x32_bf16 v[126:129], v[150:153], v[204:207], 0
	v_mfma_f32_16x16x32_bf16 v[122:125], v[176:179], v[204:207], 0
	v_mfma_f32_16x16x32_bf16 v[110:113], v[150:153], v[212:215], 0
	v_mfma_f32_16x16x32_bf16 v[106:109], v[176:179], v[212:215], 0
	v_mfma_f32_16x16x32_bf16 v[94:97], v[150:153], v[220:223], 0
	v_mfma_f32_16x16x32_bf16 v[90:93], v[176:179], v[220:223], 0
	v_mfma_f32_16x16x32_bf16 v[78:81], v[150:153], v[228:231], 0
	v_mfma_f32_16x16x32_bf16 v[74:77], v[176:179], v[228:231], 0
	v_mfma_f32_16x16x32_bf16 v[126:129], v[172:175], v[208:211], v[126:129]
	v_mfma_f32_16x16x32_bf16 v[122:125], v[180:183], v[208:211], v[122:125]
	v_mfma_f32_16x16x32_bf16 v[110:113], v[172:175], v[216:219], v[110:113]
	v_mfma_f32_16x16x32_bf16 v[106:109], v[180:183], v[216:219], v[106:109]
	v_mfma_f32_16x16x32_bf16 v[94:97], v[172:175], v[224:227], v[94:97]
	v_mfma_f32_16x16x32_bf16 v[90:93], v[180:183], v[224:227], v[90:93]
	v_mfma_f32_16x16x32_bf16 v[78:81], v[172:175], v[232:235], v[78:81]
	v_mfma_f32_16x16x32_bf16 v[74:77], v[180:183], v[232:235], v[74:77]
	s_setprio 0
	s_setprio 1
	v_mfma_f32_16x16x32_bf16 v[118:121], v[184:187], v[204:207], 0
	v_mfma_f32_16x16x32_bf16 v[114:117], v[196:199], v[204:207], 0
	v_mfma_f32_16x16x32_bf16 v[102:105], v[184:187], v[212:215], 0
	v_mfma_f32_16x16x32_bf16 v[98:101], v[196:199], v[212:215], 0
	v_mfma_f32_16x16x32_bf16 v[86:89], v[184:187], v[220:223], 0
	v_mfma_f32_16x16x32_bf16 v[82:85], v[196:199], v[220:223], 0
	v_mfma_f32_16x16x32_bf16 v[70:73], v[184:187], v[228:231], 0
	v_mfma_f32_16x16x32_bf16 v[66:69], v[196:199], v[228:231], 0
	v_mfma_f32_16x16x32_bf16 v[118:121], v[192:195], v[208:211], v[118:121]
	v_mfma_f32_16x16x32_bf16 v[114:117], v[200:203], v[208:211], v[114:117]
	v_mfma_f32_16x16x32_bf16 v[102:105], v[192:195], v[216:219], v[102:105]
	v_mfma_f32_16x16x32_bf16 v[98:101], v[200:203], v[216:219], v[98:101]
	v_mfma_f32_16x16x32_bf16 v[86:89], v[192:195], v[224:227], v[86:89]
	v_mfma_f32_16x16x32_bf16 v[82:85], v[200:203], v[224:227], v[82:85]
	v_mfma_f32_16x16x32_bf16 v[70:73], v[192:195], v[232:235], v[70:73]
	v_mfma_f32_16x16x32_bf16 v[66:69], v[200:203], v[232:235], v[66:69]
	s_setprio 0
	s_barrier
	s_add_i32 s15, s58, s50
	v_lshl_add_u64 v[154:155], s[40:41], 0, v[132:133]
	s_mov_b32 m0, s15
	ds_read_b128 v[204:207], v167 offset:16384
	ds_read_b128 v[208:211], v167 offset:17408
	ds_read_b128 v[212:215], v167 offset:18432
	ds_read_b128 v[216:219], v167 offset:19456
	ds_read_b128 v[220:223], v167 offset:20480
	ds_read_b128 v[224:227], v167 offset:21504
	ds_read_b128 v[228:231], v167 offset:22528
	ds_read_b128 v[232:235], v167 offset:23552
	global_load_lds_dwordx4 v[154:155], off
	s_add_i32 m0, s15, 0x2000
	s_add_u32 s18, s40, 0x40000
	v_lshl_add_u64 v[158:159], s[40:41], 0, v[136:137]
	s_addc_u32 s19, s41, 0
	s_add_i32 s15, s59, s50
	global_load_lds_dwordx4 v[158:159], off
	v_lshl_add_u64 v[164:165], s[18:19], 0, v[132:133]
	s_mov_b32 m0, s15
	v_lshl_add_u64 v[168:169], s[42:43], 0, v[134:135]
	global_load_lds_dwordx4 v[164:165], off
	v_lshl_add_u64 v[164:165], s[18:19], 0, v[136:137]
	s_add_i32 m0, s15, 0x2000
	s_nop 0
	global_load_lds_dwordx4 v[164:165], off
	v_lshl_add_u64 v[164:165], s[42:43], 0, v[130:131]
	s_mov_b32 m0, s51
	s_nop 0
	global_load_lds_dwordx4 v[164:165], off
	s_mov_b32 m0, s52
	s_nop 0
	global_load_lds_dwordx4 v[168:169], off
	s_waitcnt vmcnt(8)
; #define PG8_STAGE(bufoff, gbase, voff) do { _Pragma("unroll") for (int _i = 0; _i < 2; ++_i) \
;         __builtin_amdgcn_global_load_lds((const unsigned*)((const char*)(gbase) + (voff)[_i]), (PG8_LAS unsigned*)(lds + (bufoff) + ldsw + _i * 8192), 16, 0, 0); } while (0)
; #define PG8_LDA(dst, b, h) do { _Pragma("unroll") for (int m = 0; m < 4; ++m) _Pragma("unroll") for (int k = 0; k < 2; ++k) dst[m][k] = *(const PG8_LAS bf16x8*)(lds + PG8_SA(b, h) + aoff + m * 2048 + k * 1024); } while (0)
; #define PG8_LDB(dst, b, h) do { _Pragma("unroll") for (int n = 0; n < 2; ++n) _Pragma("unroll") for (int k = 0; k < 2; ++k) dst[n][k] = *(const PG8_LAS bf16x8*)(lds + PG8_SB(b, h) + boff + n * 2048 + k * 1024); } while (0)
; #define PG8_MMA(ai, bj, At, Bt) do { __builtin_amdgcn_s_setprio(1); _Pragma("unroll") for (int m = 0; m < 4; ++m) _Pragma("unroll") for (int n = 0; n < 2; ++n) _Pragma("unroll") for (int k = 0; k < 2; ++k) \
;         acc[ai][bj][m][n] = __builtin_amdgcn_mfma_f32_16x16x32_bf16(Bt[n][k], At[m][k], acc[ai][bj][m][n], 0, 0, 0); __builtin_amdgcn_s_setprio(0); } while (0)
; #define PG8_WAIT_V(n) asm volatile("s_waitcnt vmcnt(" #n ")" ::: "memory")
; #define PG8_WAIT_L(n) asm volatile("s_waitcnt lgkmcnt(" #n ")" ::: "memory")
; #define PG8_BAR __builtin_amdgcn_s_barrier()
; #define PG8_SCHED __builtin_amdgcn_sched_barrier(0)
; template <class Epi, class Sched, bool ALIGN_EPI = false, bool SP2 = false>
; __device__ __forceinline__ void gemm_phase(PG8_LAS unsigned char* lds, const Gemm g, const Sched& S, const Epi& E, const int tid) {
;     ...
;             PG8_WAIT_V(8); PG8_WAIT_L(0); PG8_BAR; PG8_MMA(1, 0, At, B0); PG8_MMA(1, 1, At, B1); PG8_BAR; PG8_SCHED;
;             PG8_LDB(B0, 1, 0); PG8_LDB(B1, 1, 1); PG8_SCHED; PG8_LDA(At, 1, 0); PG8_STAGE(PG8_SA(0, 1), a2 + hstep, voffA);
;             PG8_WAIT_V(8); PG8_WAIT_L(0); PG8_BAR; PG8_MMA(0, 0, At, B0); PG8_MMA(0, 1, At, B1); PG8_BAR; PG8_SCHED;
; __device__ __forceinline__ void rstd8(const float* ssq, int row0, int fq, float (&rs)[8]) {
;     f32x4 pr[8];
; #pragma unroll
;     for (int i = 0; i < 8; ++i) pr[i] = *(const f32x4*)(ssq + (size_t)(row0 + (i >> 2) * 128 + (i & 3) * 16) * 16 + 4 * fq);
; #pragma unroll
;     for (int i = 0; i < 8; ++i) { float s = (pr[i][0] + pr[i][1]) + (pr[i][2] + pr[i][3]); s = xsum16(s); s = xsum32(s); rs[i] = __builtin_amdgcn_rsqf(s * (1.0f / DM) + NORM_EPS); }
; }
	v_add_f32_e32 v6, v6, v7
	v_add_f32_e32 v18, v18, v19
	v_add_f32_e32 v22, v22, v23
	v_add_f32_e32 v34, v34, v35
	v_add_f32_e32 v38, v38, v39
	v_add_f32_e32 v50, v50, v51
	v_add_f32_e32 v54, v54, v55
	v_add_f32_e32 v58, v58, v59
	v_add_f32_e32 v8, v8, v9
	v_add_f32_e32 v20, v20, v21
	v_add_f32_e32 v24, v24, v25
	v_add_f32_e32 v36, v36, v37
	v_add_f32_e32 v40, v40, v41
	v_add_f32_e32 v52, v52, v53
	v_add_f32_e32 v56, v56, v57
	v_add_f32_e32 v60, v60, v61
	v_add_f32_e32 v243, v6, v8
	v_add_f32_e32 v244, v18, v20
	v_add_f32_e32 v245, v22, v24
	v_add_f32_e32 v246, v34, v36
	v_add_f32_e32 v247, v38, v40
	v_add_f32_e32 v248, v50, v52
	v_add_f32_e32 v249, v54, v56
	v_add_f32_e32 v250, v58, v60
	v_mov_b32_e32 v6, v243
	v_mov_b32_e32 v18, v244
	v_mov_b32_e32 v22, v245
	v_mov_b32_e32 v34, v246
	v_mov_b32_e32 v38, v247
	v_mov_b32_e32 v50, v248
	v_mov_b32_e32 v54, v249
	v_mov_b32_e32 v58, v250
	v_permlane16_swap_b32_e32 v243, v6
	v_permlane16_swap_b32_e32 v244, v18
	v_permlane16_swap_b32_e32 v245, v22
	v_permlane16_swap_b32_e32 v246, v34
	v_permlane16_swap_b32_e32 v247, v38
	v_permlane16_swap_b32_e32 v248, v50
	v_permlane16_swap_b32_e32 v249, v54
	v_permlane16_swap_b32_e32 v250, v58
	v_add_f32_e32 v243, v243, v6
	v_add_f32_e32 v244, v244, v18
	v_add_f32_e32 v245, v245, v22
	v_add_f32_e32 v246, v246, v34
	v_add_f32_e32 v247, v247, v38
	v_add_f32_e32 v248, v248, v50
	v_add_f32_e32 v249, v249, v54
	v_add_f32_e32 v250, v250, v58
	v_mov_b32_e32 v6, v243
	v_mov_b32_e32 v18, v244
	v_mov_b32_e32 v22, v245
	v_mov_b32_e32 v34, v246
	v_mov_b32_e32 v38, v247
	v_mov_b32_e32 v50, v248
	v_mov_b32_e32 v54, v249
	v_mov_b32_e32 v58, v250
	v_permlane32_swap_b32_e32 v243, v6
	v_permlane32_swap_b32_e32 v244, v18
	v_permlane32_swap_b32_e32 v245, v22
	v_permlane32_swap_b32_e32 v246, v34
	v_permlane32_swap_b32_e32 v247, v38
	v_permlane32_swap_b32_e32 v248, v50
	v_permlane32_swap_b32_e32 v249, v54
	v_permlane32_swap_b32_e32 v250, v58
	v_add_f32_e32 v243, v243, v6
	v_add_f32_e32 v244, v244, v18
	v_add_f32_e32 v245, v245, v22
	v_add_f32_e32 v246, v246, v34
	v_add_f32_e32 v247, v247, v38
	v_add_f32_e32 v248, v248, v50
	v_add_f32_e32 v249, v249, v54
	v_add_f32_e32 v250, v250, v58
	v_fmamk_f32 v243, v243, 0x3a800000, v171
	v_fmamk_f32 v244, v244, 0x3a800000, v171
	v_fmamk_f32 v245, v245, 0x3a800000, v171
	v_fmamk_f32 v246, v246, 0x3a800000, v171
	v_fmamk_f32 v247, v247, 0x3a800000, v171
	v_fmamk_f32 v248, v248, 0x3a800000, v171
	v_fmamk_f32 v249, v249, 0x3a800000, v171
	v_fmamk_f32 v250, v250, 0x3a800000, v171
	v_rsq_f32_e32 v243, v243
	v_rsq_f32_e32 v244, v244
	v_rsq_f32_e32 v245, v245
	v_rsq_f32_e32 v246, v246
	v_rsq_f32_e32 v247, v247
	v_rsq_f32_e32 v248, v248
	v_rsq_f32_e32 v249, v249
	v_rsq_f32_e32 v250, v250
	s_waitcnt lgkmcnt(0)
	s_barrier
	s_setprio 1
	s_waitcnt lgkmcnt(0)
	v_mfma_f32_16x16x32_bf16 v[62:65], v[150:153], v[204:207], 0
	v_mfma_f32_16x16x32_bf16 v[58:61], v[176:179], v[204:207], 0
	v_mfma_f32_16x16x32_bf16 v[46:49], v[150:153], v[212:215], 0
	v_mfma_f32_16x16x32_bf16 v[42:45], v[176:179], v[212:215], 0
	v_mfma_f32_16x16x32_bf16 v[30:33], v[150:153], v[220:223], 0
	v_mfma_f32_16x16x32_bf16 v[26:29], v[176:179], v[220:223], 0
	v_mfma_f32_16x16x32_bf16 v[14:17], v[150:153], v[228:231], 0
	v_mfma_f32_16x16x32_bf16 v[10:13], v[176:179], v[228:231], 0
	v_mfma_f32_16x16x32_bf16 v[62:65], v[172:175], v[208:211], v[62:65]
	v_mfma_f32_16x16x32_bf16 v[58:61], v[180:183], v[208:211], v[58:61]
	v_mfma_f32_16x16x32_bf16 v[46:49], v[172:175], v[216:219], v[46:49]
	v_mfma_f32_16x16x32_bf16 v[42:45], v[180:183], v[216:219], v[42:45]
	v_mfma_f32_16x16x32_bf16 v[30:33], v[172:175], v[224:227], v[30:33]
	v_mfma_f32_16x16x32_bf16 v[26:29], v[180:183], v[224:227], v[26:29]
	v_mfma_f32_16x16x32_bf16 v[14:17], v[172:175], v[232:235], v[14:17]
	v_mfma_f32_16x16x32_bf16 v[10:13], v[180:183], v[232:235], v[10:13]
	s_setprio 0
	s_setprio 1
	v_mfma_f32_16x16x32_bf16 v[54:57], v[184:187], v[204:207], 0
	v_mfma_f32_16x16x32_bf16 v[50:53], v[196:199], v[204:207], 0
	v_mfma_f32_16x16x32_bf16 v[38:41], v[184:187], v[212:215], 0
	v_mfma_f32_16x16x32_bf16 v[34:37], v[196:199], v[212:215], 0
	v_mfma_f32_16x16x32_bf16 v[22:25], v[184:187], v[220:223], 0
	v_mfma_f32_16x16x32_bf16 v[18:21], v[196:199], v[220:223], 0
	v_mfma_f32_16x16x32_bf16 v[6:9], v[184:187], v[228:231], 0
	v_mfma_f32_16x16x32_bf16 v[2:5], v[196:199], v[228:231], 0
	v_mfma_f32_16x16x32_bf16 v[54:57], v[192:195], v[208:211], v[54:57]
	v_mfma_f32_16x16x32_bf16 v[50:53], v[200:203], v[208:211], v[50:53]
	v_mfma_f32_16x16x32_bf16 v[38:41], v[192:195], v[216:219], v[38:41]
	v_mfma_f32_16x16x32_bf16 v[34:37], v[200:203], v[216:219], v[34:37]
	v_mfma_f32_16x16x32_bf16 v[22:25], v[192:195], v[224:227], v[22:25]
	v_mfma_f32_16x16x32_bf16 v[18:21], v[200:203], v[224:227], v[18:21]
	v_mfma_f32_16x16x32_bf16 v[6:9], v[192:195], v[232:235], v[6:9]
	v_mfma_f32_16x16x32_bf16 v[2:5], v[200:203], v[232:235], v[2:5]
	s_setprio 0
	s_barrier
	s_add_i32 s15, 0, 0x18000
	v_add_u32_e32 v156, s15, v157
	s_add_i32 s67, 0, 0x1c000
	ds_read_b128 v[150:153], v156
	ds_read_b128 v[172:175], v156 offset:1024
	ds_read_b128 v[176:179], v156 offset:2048
	ds_read_b128 v[180:183], v156 offset:3072
	v_add_u32_e32 v156, s67, v157
	ds_read_b128 v[184:187], v156
	ds_read_b128 v[192:195], v156 offset:1024
	ds_read_b128 v[196:199], v156 offset:2048
	ds_read_b128 v[200:203], v156 offset:3072
	s_add_u32 s18, s42, 0x40000
	s_addc_u32 s19, s43, 0
	s_mov_b32 m0, s53
	v_lshl_add_u64 v[188:189], s[18:19], 0, v[130:131]
	ds_read_b128 v[204:207], v167 offset:32768
	ds_read_b128 v[208:211], v167 offset:33792
	ds_read_b128 v[212:215], v167 offset:34816
	ds_read_b128 v[216:219], v167 offset:35840
	ds_read_b128 v[220:223], v167 offset:36864
	ds_read_b128 v[224:227], v167 offset:37888
	ds_read_b128 v[228:231], v167 offset:38912
	ds_read_b128 v[232:235], v167 offset:39936
	global_load_lds_dwordx4 v[188:189], off
	v_lshl_add_u64 v[188:189], s[18:19], 0, v[134:135]
	s_mov_b32 m0, s54
	s_nop 0
	global_load_lds_dwordx4 v[188:189], off
	s_waitcnt vmcnt(8)
	s_waitcnt lgkmcnt(0)
	s_barrier
; #define PG8_STAGE(bufoff, gbase, voff) do { _Pragma("unroll") for (int _i = 0; _i < 2; ++_i) \
;         __builtin_amdgcn_global_load_lds((const unsigned*)((const char*)(gbase) + (voff)[_i]), (PG8_LAS unsigned*)(lds + (bufoff) + ldsw + _i * 8192), 16, 0, 0); } while (0)
; #define PG8_LDA(dst, b, h) do { _Pragma("unroll") for (int m = 0; m < 4; ++m) _Pragma("unroll") for (int k = 0; k < 2; ++k) dst[m][k] = *(const PG8_LAS bf16x8*)(lds + PG8_SA(b, h) + aoff + m * 2048 + k * 1024); } while (0)
; #define PG8_MMA(ai, bj, At, Bt) do { __builtin_amdgcn_s_setprio(1); _Pragma("unroll") for (int m = 0; m < 4; ++m) _Pragma("unroll") for (int n = 0; n < 2; ++n) _Pragma("unroll") for (int k = 0; k < 2; ++k) \
;         acc[ai][bj][m][n] = __builtin_amdgcn_mfma_f32_16x16x32_bf16(Bt[n][k], At[m][k], acc[ai][bj][m][n], 0, 0, 0); __builtin_amdgcn_s_setprio(0); } while (0)
; #define PG8_WAIT_V(n) asm volatile("s_waitcnt vmcnt(" #n ")" ::: "memory")
; #define PG8_WAIT_L(n) asm volatile("s_waitcnt lgkmcnt(" #n ")" ::: "memory")
; #define PG8_BAR __builtin_amdgcn_s_barrier()
; #define PG8_SCHED __builtin_amdgcn_sched_barrier(0)
; template <class Epi, class Sched, bool ALIGN_EPI = false, bool SP2 = false>
; __device__ __forceinline__ void gemm_phase(PG8_LAS unsigned char* lds, const Gemm g, const Sched& S, const Epi& E, const int tid) {
;     ...
;             PG8_WAIT_V(8); PG8_WAIT_L(0); PG8_BAR; PG8_MMA(0, 0, At, B0); PG8_MMA(0, 1, At, B1); PG8_BAR; PG8_SCHED;
;             PG8_LDA(At, 1, 1); PG8_STAGE(PG8_SB(1, 0), b3, voffB); PG8_STAGE(PG8_SB(1, 1), b3 + hstep, voffB); PG8_STAGE(PG8_SA(1, 0), a3, voffA);
;             PG8_WAIT_V(8); PG8_WAIT_L(0); PG8_BAR; PG8_MMA(1, 0, At, B0); PG8_MMA(1, 1, At, B1); PG8_BAR; PG8_SCHED;
	s_setprio 1
	s_waitcnt lgkmcnt(0)
	v_mfma_f32_16x16x32_bf16 v[126:129], v[150:153], v[204:207], v[126:129]
	v_mfma_f32_16x16x32_bf16 v[122:125], v[176:179], v[204:207], v[122:125]
	v_mfma_f32_16x16x32_bf16 v[110:113], v[150:153], v[212:215], v[110:113]
	v_mfma_f32_16x16x32_bf16 v[106:109], v[176:179], v[212:215], v[106:109]
	v_mfma_f32_16x16x32_bf16 v[94:97], v[150:153], v[220:223], v[94:97]
	v_mfma_f32_16x16x32_bf16 v[90:93], v[176:179], v[220:223], v[90:93]
	v_mfma_f32_16x16x32_bf16 v[78:81], v[150:153], v[228:231], v[78:81]
	v_mfma_f32_16x16x32_bf16 v[74:77], v[176:179], v[228:231], v[74:77]
	v_mfma_f32_16x16x32_bf16 v[126:129], v[172:175], v[208:211], v[126:129]
	v_mfma_f32_16x16x32_bf16 v[122:125], v[180:183], v[208:211], v[122:125]
	v_mfma_f32_16x16x32_bf16 v[110:113], v[172:175], v[216:219], v[110:113]
	v_mfma_f32_16x16x32_bf16 v[106:109], v[180:183], v[216:219], v[106:109]
	v_mfma_f32_16x16x32_bf16 v[94:97], v[172:175], v[224:227], v[94:97]
	v_mfma_f32_16x16x32_bf16 v[90:93], v[180:183], v[224:227], v[90:93]
	v_mfma_f32_16x16x32_bf16 v[78:81], v[172:175], v[232:235], v[78:81]
	v_mfma_f32_16x16x32_bf16 v[74:77], v[180:183], v[232:235], v[74:77]
	s_setprio 0
	s_setprio 1
	v_mfma_f32_16x16x32_bf16 v[118:121], v[184:187], v[204:207], v[118:121]
	v_mfma_f32_16x16x32_bf16 v[114:117], v[196:199], v[204:207], v[114:117]
	v_mfma_f32_16x16x32_bf16 v[102:105], v[184:187], v[212:215], v[102:105]
	v_mfma_f32_16x16x32_bf16 v[98:101], v[196:199], v[212:215], v[98:101]
	v_mfma_f32_16x16x32_bf16 v[86:89], v[184:187], v[220:223], v[86:89]
	v_mfma_f32_16x16x32_bf16 v[82:85], v[196:199], v[220:223], v[82:85]
	v_mfma_f32_16x16x32_bf16 v[70:73], v[184:187], v[228:231], v[70:73]
	v_mfma_f32_16x16x32_bf16 v[66:69], v[196:199], v[228:231], v[66:69]
	v_mfma_f32_16x16x32_bf16 v[118:121], v[192:195], v[208:211], v[118:121]
	v_mfma_f32_16x16x32_bf16 v[114:117], v[200:203], v[208:211], v[114:117]
	v_mfma_f32_16x16x32_bf16 v[102:105], v[192:195], v[216:219], v[102:105]
	v_mfma_f32_16x16x32_bf16 v[98:101], v[200:203], v[216:219], v[98:101]
	v_mfma_f32_16x16x32_bf16 v[86:89], v[192:195], v[224:227], v[86:89]
	v_mfma_f32_16x16x32_bf16 v[82:85], v[200:203], v[224:227], v[82:85]
	v_mfma_f32_16x16x32_bf16 v[70:73], v[192:195], v[232:235], v[70:73]
	v_mfma_f32_16x16x32_bf16 v[66:69], v[200:203], v[232:235], v[66:69]
	s_setprio 0
	s_barrier
	s_add_i32 s15, s15, s50
	v_lshl_add_u64 v[154:155], v[154:155], 0, s[8:9]
	s_mov_b32 m0, s15
	ds_read_b128 v[204:207], v167 offset:49152
	ds_read_b128 v[208:211], v167 offset:50176
	ds_read_b128 v[212:215], v167 offset:51200
	ds_read_b128 v[216:219], v167 offset:52224
	ds_read_b128 v[220:223], v167 offset:53248
	ds_read_b128 v[224:227], v167 offset:54272
	ds_read_b128 v[228:231], v167 offset:55296
	ds_read_b128 v[232:235], v167 offset:56320
	global_load_lds_dwordx4 v[154:155], off
	s_add_i32 m0, s15, 0x2000
	s_add_u32 s18, s40, 0x40080
	v_lshl_add_u64 v[154:155], v[158:159], 0, s[8:9]
	s_addc_u32 s19, s41, 0
	s_add_i32 s15, s67, s50
	global_load_lds_dwordx4 v[154:155], off
	v_lshl_add_u64 v[154:155], s[18:19], 0, v[132:133]
	s_mov_b32 m0, s15
	s_nop 0
	global_load_lds_dwordx4 v[154:155], off
	v_lshl_add_u64 v[154:155], s[18:19], 0, v[136:137]
	s_add_i32 m0, s15, 0x2000
	s_nop 0
	global_load_lds_dwordx4 v[154:155], off
	v_lshl_add_u64 v[154:155], v[164:165], 0, s[8:9]
	s_mov_b32 m0, s55
	s_nop 0
	global_load_lds_dwordx4 v[154:155], off
	v_lshl_add_u64 v[154:155], v[168:169], 0, s[8:9]
	s_mov_b32 m0, s56
	s_nop 0
	global_load_lds_dwordx4 v[154:155], off
	s_waitcnt vmcnt(8)
	s_waitcnt lgkmcnt(0)
	s_barrier
	s_setprio 1
	s_waitcnt lgkmcnt(0)
	v_mfma_f32_16x16x32_bf16 v[62:65], v[150:153], v[204:207], v[62:65]
	v_mfma_f32_16x16x32_bf16 v[58:61], v[176:179], v[204:207], v[58:61]
	v_mfma_f32_16x16x32_bf16 v[46:49], v[150:153], v[212:215], v[46:49]
	v_mfma_f32_16x16x32_bf16 v[42:45], v[176:179], v[212:215], v[42:45]
	v_mfma_f32_16x16x32_bf16 v[30:33], v[150:153], v[220:223], v[30:33]
	v_mfma_f32_16x16x32_bf16 v[26:29], v[176:179], v[220:223], v[26:29]
	v_mfma_f32_16x16x32_bf16 v[14:17], v[150:153], v[228:231], v[14:17]
	v_mfma_f32_16x16x32_bf16 v[10:13], v[176:179], v[228:231], v[10:13]
	v_mfma_f32_16x16x32_bf16 v[62:65], v[172:175], v[208:211], v[62:65]
	v_mfma_f32_16x16x32_bf16 v[58:61], v[180:183], v[208:211], v[58:61]
	v_mfma_f32_16x16x32_bf16 v[46:49], v[172:175], v[216:219], v[46:49]
	v_mfma_f32_16x16x32_bf16 v[42:45], v[180:183], v[216:219], v[42:45]
	v_mfma_f32_16x16x32_bf16 v[30:33], v[172:175], v[224:227], v[30:33]
	v_mfma_f32_16x16x32_bf16 v[26:29], v[180:183], v[224:227], v[26:29]
	v_mfma_f32_16x16x32_bf16 v[14:17], v[172:175], v[232:235], v[14:17]
	v_mfma_f32_16x16x32_bf16 v[10:13], v[180:183], v[232:235], v[10:13]
	s_setprio 0
	s_setprio 1
	v_mfma_f32_16x16x32_bf16 v[54:57], v[184:187], v[204:207], v[54:57]
	v_mfma_f32_16x16x32_bf16 v[50:53], v[196:199], v[204:207], v[50:53]
	v_mfma_f32_16x16x32_bf16 v[38:41], v[184:187], v[212:215], v[38:41]
	v_mfma_f32_16x16x32_bf16 v[34:37], v[196:199], v[212:215], v[34:37]
	v_mfma_f32_16x16x32_bf16 v[22:25], v[184:187], v[220:223], v[22:25]
	v_mfma_f32_16x16x32_bf16 v[18:21], v[196:199], v[220:223], v[18:21]
	v_mfma_f32_16x16x32_bf16 v[6:9], v[184:187], v[228:231], v[6:9]
	v_mfma_f32_16x16x32_bf16 v[2:5], v[196:199], v[228:231], v[2:5]
	v_mfma_f32_16x16x32_bf16 v[54:57], v[192:195], v[208:211], v[54:57]
	v_mfma_f32_16x16x32_bf16 v[50:53], v[200:203], v[208:211], v[50:53]
	v_mfma_f32_16x16x32_bf16 v[38:41], v[192:195], v[216:219], v[38:41]
	v_mfma_f32_16x16x32_bf16 v[34:37], v[200:203], v[216:219], v[34:37]
	v_mfma_f32_16x16x32_bf16 v[22:25], v[192:195], v[224:227], v[22:25]
	v_mfma_f32_16x16x32_bf16 v[18:21], v[200:203], v[224:227], v[18:21]
	v_mfma_f32_16x16x32_bf16 v[6:9], v[192:195], v[232:235], v[6:9]
	v_mfma_f32_16x16x32_bf16 v[2:5], v[200:203], v[232:235], v[2:5]
	s_setprio 0
	s_barrier
	s_add_i32 s66, s66, 2
	s_add_u32 s64, s64, 0x100
	s_addc_u32 s65, s65, 0
	s_add_u32 s38, s38, 0x100
	s_addc_u32 s39, s39, 0

;     __device__ __forceinline__ bool next(int i, pg8::Unit& u) const { if (!base.next(i >> 2, u)) return false; u.sub = i & 3; return true; }
;     __host__ __device__ bool next(int i, Unit& u) const {
;         const long L = (long)i * G + c; if (L >= nwg) return false;
;         int wgid = (int)L; { const int q = nwg / NXCD, r = nwg % NXCD, xcd = wgid % NXCD, off = wgid / NXCD; wgid = (xcd < r ? xcd * (q + 1) : r * (q + 1) + (xcd - r) * q) + off; }
;         const int nig = WGM * nN, gid = wgid / nig, fm = gid * WGM, gsz = (nM - fm) < WGM ? (nM - fm) : WGM;
;         u.pm = fm + ((wgid % nig) % gsz); u.pn = (wgid % nig) / gsz; u.sub = 0; return true;
; template <class Epi, class Sched, bool ALIGN_EPI = false, bool SP2 = false>
; __device__ __forceinline__ void gemm_phase(PG8_LAS unsigned char* lds, const Gemm g, const Sched& S, const Epi& E, const int tid) {
;     ...
;         const bool has_next = S.next(ui + 1, nxt);
.LBB0_416:
	ds_read_b128 v[130:133], v205
	ds_read_b128 v[134:137], v205 offset:1024
	ds_read_b128 v[138:141], v205 offset:2048
	ds_read_b128 v[142:145], v205 offset:3072
	ds_read_b128 v[146:149], v206
	ds_read_b128 v[150:153], v206 offset:1024
	ds_read_b128 v[154:157], v206 offset:2048
	ds_read_b128 v[158:161], v206 offset:3072
	ds_read_b128 v[182:185], v207
	ds_read_b128 v[186:189], v207 offset:1024
	ds_read_b128 v[192:195], v207 offset:2048
	ds_read_b128 v[196:199], v207 offset:3072
	ds_read_b128 v[200:203], v207 offset:4096
	ds_read_b128 v[208:211], v207 offset:5120
	ds_read_b128 v[212:215], v207 offset:6144
	ds_read_b128 v[216:219], v207 offset:7168
	s_add_i32 s74, s74, 1
	s_mul_i32 s0, s74, s63
	s_mul_hi_u32 s1, s74, s49
	s_add_i32 s1, s1, s0
	s_mul_i32 s0, s74, s49
	s_add_u32 s4, s0, s48
	s_addc_u32 s5, s1, s64
	v_cmp_gt_i64_e32 vcc, s[4:5], v[180:181]
	v_cmp_lt_i64_e64 s[0:1], s[4:5], v[178:179]
	s_cbranch_vccnz .LBB0_418
	s_ashr_i32 s5, s4, 31
	s_lshr_b32 s5, s5, 29
	s_add_i32 s5, s4, s5
	s_ashr_i32 s10, s5, 3
	s_and_b32 s5, s5, -8
	s_sub_i32 s4, s4, s5
	s_cmp_lt_i32 s4, 0
	s_cselect_b32 s5, s65, 0x61
	s_mul_i32 s4, s5, s4
	s_add_i32 s4, s4, s10
	s_ashr_i32 s5, s4, 31
	s_lshr_b32 s5, s5, 27
	s_add_i32 s5, s4, s5
	s_ashr_i32 s10, s5, 5
	s_lshl_b32 s10, s10, 3
	s_sub_i32 s11, 0xc2, s10
	s_min_i32 s11, s11, 8
	s_abs_i32 s15, s11
	v_cvt_f32_u32_e32 v2, s15
	s_sub_i32 s19, 0, s15
	s_andn2_b32 s5, s5, 31
	s_sub_i32 s4, s4, s5
	v_rcp_iflag_f32_e32 v2, v2
	s_abs_i32 s5, s4
	s_xor_b32 s18, s4, s11
	s_ashr_i32 s18, s18, 31
	v_mul_f32_e32 v2, 0x4f7ffffe, v2
	v_cvt_u32_f32_e32 v2, v2
	s_nop 0
	v_readfirstlane_b32 s40, v2
	s_mul_i32 s19, s19, s40
	s_mul_hi_u32 s19, s40, s19
	s_add_i32 s40, s40, s19
	s_mul_hi_u32 s19, s5, s40
	s_mul_i32 s40, s19, s15
	s_sub_i32 s5, s5, s40
	s_add_i32 s41, s19, 1
	s_sub_i32 s40, s5, s15
	s_cmp_ge_u32 s5, s15
	s_cselect_b32 s19, s41, s19
	s_cselect_b32 s5, s40, s5
	s_add_i32 s40, s19, 1
	s_cmp_ge_u32 s5, s15
	s_cselect_b32 s5, s40, s19
	s_xor_b32 s5, s5, s18
	s_sub_i32 s75, s5, s18
	s_mul_i32 s5, s75, s11
	s_sub_i32 s4, s4, s5
	s_add_i32 s76, s4, s10

; #define PG8_STAGE(bufoff, gbase, voff) do { _Pragma("unroll") for (int _i = 0; _i < 2; ++_i) \
;         __builtin_amdgcn_global_load_lds((const unsigned*)((const char*)(gbase) + (voff)[_i]), (PG8_LAS unsigned*)(lds + (bufoff) + ldsw + _i * 8192), 16, 0, 0); } while (0)
; #define PG8_LDA(dst, b, h) do { _Pragma("unroll") for (int m = 0; m < 4; ++m) _Pragma("unroll") for (int k = 0; k < 2; ++k) dst[m][k] = *(const PG8_LAS bf16x8*)(lds + PG8_SA(b, h) + aoff + m * 2048 + k * 1024); } while (0)
; #define PG8_LDB(dst, b, h) do { _Pragma("unroll") for (int n = 0; n < 2; ++n) _Pragma("unroll") for (int k = 0; k < 2; ++k) dst[n][k] = *(const PG8_LAS bf16x8*)(lds + PG8_SB(b, h) + boff + n * 2048 + k * 1024); } while (0)
; #define PG8_MMA(ai, bj, At, Bt) do { __builtin_amdgcn_s_setprio(1); _Pragma("unroll") for (int m = 0; m < 4; ++m) _Pragma("unroll") for (int n = 0; n < 2; ++n) _Pragma("unroll") for (int k = 0; k < 2; ++k) \
;         acc[ai][bj][m][n] = __builtin_amdgcn_mfma_f32_16x16x32_bf16(Bt[n][k], At[m][k], acc[ai][bj][m][n], 0, 0, 0); __builtin_amdgcn_s_setprio(0); } while (0)
; #define PG8_WAIT_V(n) asm volatile("s_waitcnt vmcnt(" #n ")" ::: "memory")
; #define PG8_BAR __builtin_amdgcn_s_barrier()
; template <class Epi, class Sched, bool ALIGN_EPI = false, bool SP2 = false>
; __device__ __forceinline__ void gemm_phase(PG8_LAS unsigned char* lds, const Gemm g, const Sched& S, const Epi& E, const int tid) {
;     ...
;         for (int t = 0; t < nt; t += 2) {
;             const bool last = (t == nt - 2);
;             const char* a1 = cA + (size_t)(t + 1) * kstep;
;             const char* a2 = last ? nA : cA + (size_t)(t + 2) * kstep; const char* b2 = last ? nB : cB + (size_t)(t + 2) * kstep;
;             const char* a3 = a2 + kstep; const char* b3 = b2 + kstep;
;             if (last && has_next) S.a_ready(nxt);
;             if constexpr (SP2) {
;             PG8_LDB(B0, 0, 0); PG8_LDB(B1, 0, 1); PG8_SCHED; PG8_LDA(At, 0, 0); PG8_STAGE(PG8_SA(1, 1), a1 + hstep, voffA);
;             PG8_WAIT_V(8); PG8_WAIT_L(0); PG8_BAR; PG8_MMA(0, 0, At, B0); PG8_MMA(0, 1, At, B1); PG8_BAR; PG8_SCHED;
;             PG8_LDA(At, 0, 1); PG8_STAGE(PG8_SB(0, 0), b2, voffB); PG8_STAGE(PG8_SB(0, 1), b2 + hstep, voffB); PG8_STAGE(PG8_SA(0, 0), a2, voffA);
;             PG8_WAIT_V(8); PG8_WAIT_L(0); PG8_BAR; PG8_MMA(1, 0, At, B0); PG8_MMA(1, 1, At, B1); PG8_BAR; PG8_SCHED;
.LBB0_422:
	s_add_u32 s45, s8, 0x100
	s_addc_u32 s47, s9, 0
	s_mov_b32 s77, -2
	s_add_u32 s8, s6, 0x100
	s_addc_u32 s9, s7, 0
	s_cmp_eq_u32 s77, 40
	s_cselect_b32 s43, s1, s9
	s_cselect_b32 s42, s0, s8
	s_cselect_b32 s11, s41, s47
	s_cselect_b32 s10, s40, s45
	v_lshl_add_u64 v[220:221], s[6:7], 0, v[176:177]
	s_add_i32 m0, s56, 0xc000
	global_load_lds_dwordx4 v[220:221], off
	v_lshl_add_u64 v[220:221], s[6:7], 0, v[174:175]
	s_add_i32 m0, s56, 0xe000
	s_nop 0
	global_load_lds_dwordx4 v[220:221], off
	s_waitcnt vmcnt(8)
	s_waitcnt lgkmcnt(0)
	s_barrier
	s_setprio 1
	s_waitcnt lgkmcnt(0)
	v_mfma_f32_16x16x32_bf16 v[126:129], v[130:133], v[182:185], 0
	v_mfma_f32_16x16x32_bf16 v[122:125], v[138:141], v[182:185], 0
	v_mfma_f32_16x16x32_bf16 v[110:113], v[130:133], v[192:195], 0
	v_mfma_f32_16x16x32_bf16 v[106:109], v[138:141], v[192:195], 0
	v_mfma_f32_16x16x32_bf16 v[94:97], v[130:133], v[200:203], 0
	v_mfma_f32_16x16x32_bf16 v[90:93], v[138:141], v[200:203], 0
	v_mfma_f32_16x16x32_bf16 v[78:81], v[130:133], v[212:215], 0
	v_mfma_f32_16x16x32_bf16 v[74:77], v[138:141], v[212:215], 0
	v_mfma_f32_16x16x32_bf16 v[126:129], v[134:137], v[186:189], v[126:129]
	v_mfma_f32_16x16x32_bf16 v[122:125], v[142:145], v[186:189], v[122:125]
	v_mfma_f32_16x16x32_bf16 v[110:113], v[134:137], v[196:199], v[110:113]
	v_mfma_f32_16x16x32_bf16 v[106:109], v[142:145], v[196:199], v[106:109]
	v_mfma_f32_16x16x32_bf16 v[94:97], v[134:137], v[208:211], v[94:97]
	v_mfma_f32_16x16x32_bf16 v[90:93], v[142:145], v[208:211], v[90:93]
	v_mfma_f32_16x16x32_bf16 v[78:81], v[134:137], v[216:219], v[78:81]
	v_mfma_f32_16x16x32_bf16 v[74:77], v[142:145], v[216:219], v[74:77]
	s_setprio 0
	s_setprio 1
	v_mfma_f32_16x16x32_bf16 v[118:121], v[146:149], v[182:185], 0
	v_mfma_f32_16x16x32_bf16 v[114:117], v[154:157], v[182:185], 0
	v_mfma_f32_16x16x32_bf16 v[102:105], v[146:149], v[192:195], 0
	v_mfma_f32_16x16x32_bf16 v[98:101], v[154:157], v[192:195], 0
	v_mfma_f32_16x16x32_bf16 v[86:89], v[146:149], v[200:203], 0
	v_mfma_f32_16x16x32_bf16 v[82:85], v[154:157], v[200:203], 0
	v_mfma_f32_16x16x32_bf16 v[70:73], v[146:149], v[212:215], 0
	v_mfma_f32_16x16x32_bf16 v[66:69], v[154:157], v[212:215], 0
	v_mfma_f32_16x16x32_bf16 v[118:121], v[150:153], v[186:189], v[118:121]
	v_mfma_f32_16x16x32_bf16 v[114:117], v[158:161], v[186:189], v[114:117]
	v_mfma_f32_16x16x32_bf16 v[102:105], v[150:153], v[196:199], v[102:105]
	v_mfma_f32_16x16x32_bf16 v[98:101], v[158:161], v[196:199], v[98:101]
	v_mfma_f32_16x16x32_bf16 v[86:89], v[150:153], v[208:211], v[86:89]
	v_mfma_f32_16x16x32_bf16 v[82:85], v[158:161], v[208:211], v[82:85]
	v_mfma_f32_16x16x32_bf16 v[70:73], v[150:153], v[216:219], v[70:73]
	v_mfma_f32_16x16x32_bf16 v[66:69], v[158:161], v[216:219], v[66:69]
	s_setprio 0
	s_barrier
	s_add_i32 s6, s66, s55
	v_lshl_add_u64 v[220:221], s[10:11], 0, v[164:165]
	s_mov_b32 m0, s6
	ds_read_b128 v[182:185], v207 offset:16384
	ds_read_b128 v[186:189], v207 offset:17408
	ds_read_b128 v[192:195], v207 offset:18432
	ds_read_b128 v[196:199], v207 offset:19456
	ds_read_b128 v[200:203], v207 offset:20480
	ds_read_b128 v[208:211], v207 offset:21504
	ds_read_b128 v[212:215], v207 offset:22528
	ds_read_b128 v[216:219], v207 offset:23552
	global_load_lds_dwordx4 v[220:221], off
	s_add_i32 m0, s6, 0x2000
	s_add_u32 s6, s10, 0xb0000
	v_lshl_add_u64 v[222:223], s[10:11], 0, v[168:169]
	s_addc_u32 s7, s11, 0
	s_add_i32 s15, s67, s55
	global_load_lds_dwordx4 v[222:223], off
	v_lshl_add_u64 v[224:225], s[6:7], 0, v[164:165]
	s_mov_b32 m0, s15
	v_lshl_add_u64 v[226:227], s[42:43], 0, v[166:167]
	global_load_lds_dwordx4 v[224:225], off
	v_lshl_add_u64 v[224:225], s[6:7], 0, v[168:169]
	s_add_i32 m0, s15, 0x2000
	s_nop 0
	global_load_lds_dwordx4 v[224:225], off
	v_lshl_add_u64 v[224:225], s[42:43], 0, v[162:163]
	s_mov_b32 m0, s56
	s_nop 0
	global_load_lds_dwordx4 v[224:225], off
	s_mov_b32 m0, s57
	s_nop 0
	global_load_lds_dwordx4 v[226:227], off
	s_waitcnt vmcnt(8)
	s_waitcnt lgkmcnt(0)
	s_barrier
	s_setprio 1
	s_waitcnt lgkmcnt(0)
	v_mfma_f32_16x16x32_bf16 v[62:65], v[130:133], v[182:185], 0
	v_mfma_f32_16x16x32_bf16 v[58:61], v[138:141], v[182:185], 0
	v_mfma_f32_16x16x32_bf16 v[46:49], v[130:133], v[192:195], 0
	v_mfma_f32_16x16x32_bf16 v[42:45], v[138:141], v[192:195], 0
	v_mfma_f32_16x16x32_bf16 v[30:33], v[130:133], v[200:203], 0
	v_mfma_f32_16x16x32_bf16 v[26:29], v[138:141], v[200:203], 0
	v_mfma_f32_16x16x32_bf16 v[14:17], v[130:133], v[212:215], 0
	v_mfma_f32_16x16x32_bf16 v[10:13], v[138:141], v[212:215], 0
	v_mfma_f32_16x16x32_bf16 v[62:65], v[134:137], v[186:189], v[62:65]
	v_mfma_f32_16x16x32_bf16 v[58:61], v[142:145], v[186:189], v[58:61]
	v_mfma_f32_16x16x32_bf16 v[46:49], v[134:137], v[196:199], v[46:49]
	v_mfma_f32_16x16x32_bf16 v[42:45], v[142:145], v[196:199], v[42:45]
	v_mfma_f32_16x16x32_bf16 v[30:33], v[134:137], v[208:211], v[30:33]
	v_mfma_f32_16x16x32_bf16 v[26:29], v[142:145], v[208:211], v[26:29]
	v_mfma_f32_16x16x32_bf16 v[14:17], v[134:137], v[216:219], v[14:17]
	v_mfma_f32_16x16x32_bf16 v[10:13], v[142:145], v[216:219], v[10:13]
	s_setprio 0
	s_setprio 1
	v_mfma_f32_16x16x32_bf16 v[54:57], v[146:149], v[182:185], 0
	v_mfma_f32_16x16x32_bf16 v[50:53], v[154:157], v[182:185], 0
	v_mfma_f32_16x16x32_bf16 v[38:41], v[146:149], v[192:195], 0
	v_mfma_f32_16x16x32_bf16 v[34:37], v[154:157], v[192:195], 0
	v_mfma_f32_16x16x32_bf16 v[22:25], v[146:149], v[200:203], 0
	v_mfma_f32_16x16x32_bf16 v[18:21], v[154:157], v[200:203], 0
	v_mfma_f32_16x16x32_bf16 v[6:9], v[146:149], v[212:215], 0
	v_mfma_f32_16x16x32_bf16 v[2:5], v[154:157], v[212:215], 0
	v_mfma_f32_16x16x32_bf16 v[54:57], v[150:153], v[186:189], v[54:57]
	v_mfma_f32_16x16x32_bf16 v[50:53], v[158:161], v[186:189], v[50:53]
	v_mfma_f32_16x16x32_bf16 v[38:41], v[150:153], v[196:199], v[38:41]
	v_mfma_f32_16x16x32_bf16 v[34:37], v[158:161], v[196:199], v[34:37]
	v_mfma_f32_16x16x32_bf16 v[22:25], v[150:153], v[208:211], v[22:25]
	v_mfma_f32_16x16x32_bf16 v[18:21], v[158:161], v[208:211], v[18:21]
	v_mfma_f32_16x16x32_bf16 v[6:9], v[150:153], v[216:219], v[6:9]
	v_mfma_f32_16x16x32_bf16 v[2:5], v[158:161], v[216:219], v[2:5]
	s_setprio 0
	s_barrier
; #define PG8_STAGE(bufoff, gbase, voff) do { _Pragma("unroll") for (int _i = 0; _i < 2; ++_i) \
;         __builtin_amdgcn_global_load_lds((const unsigned*)((const char*)(gbase) + (voff)[_i]), (PG8_LAS unsigned*)(lds + (bufoff) + ldsw + _i * 8192), 16, 0, 0); } while (0)
; #define PG8_LDA(dst, b, h) do { _Pragma("unroll") for (int m = 0; m < 4; ++m) _Pragma("unroll") for (int k = 0; k < 2; ++k) dst[m][k] = *(const PG8_LAS bf16x8*)(lds + PG8_SA(b, h) + aoff + m * 2048 + k * 1024); } while (0)
; #define PG8_LDB(dst, b, h) do { _Pragma("unroll") for (int n = 0; n < 2; ++n) _Pragma("unroll") for (int k = 0; k < 2; ++k) dst[n][k] = *(const PG8_LAS bf16x8*)(lds + PG8_SB(b, h) + boff + n * 2048 + k * 1024); } while (0)
; #define PG8_MMA(ai, bj, At, Bt) do { __builtin_amdgcn_s_setprio(1); _Pragma("unroll") for (int m = 0; m < 4; ++m) _Pragma("unroll") for (int n = 0; n < 2; ++n) _Pragma("unroll") for (int k = 0; k < 2; ++k) \
;         acc[ai][bj][m][n] = __builtin_amdgcn_mfma_f32_16x16x32_bf16(Bt[n][k], At[m][k], acc[ai][bj][m][n], 0, 0, 0); __builtin_amdgcn_s_setprio(0); } while (0)
; #define PG8_WAIT_V(n) asm volatile("s_waitcnt vmcnt(" #n ")" ::: "memory")
; #define PG8_WAIT_L(n) asm volatile("s_waitcnt lgkmcnt(" #n ")" ::: "memory")
; #define PG8_BAR __builtin_amdgcn_s_barrier()
; #define PG8_SCHED __builtin_amdgcn_sched_barrier(0)
; template <class Epi, class Sched, bool ALIGN_EPI = false, bool SP2 = false>
; __device__ __forceinline__ void gemm_phase(PG8_LAS unsigned char* lds, const Gemm g, const Sched& S, const Epi& E, const int tid) {
;     ...
;             PG8_LDB(B0, 1, 0); PG8_LDB(B1, 1, 1); PG8_SCHED; PG8_LDA(At, 1, 0); PG8_STAGE(PG8_SA(0, 1), a2 + hstep, voffA);
;             PG8_WAIT_V(8); PG8_WAIT_L(0); PG8_BAR; PG8_MMA(0, 0, At, B0); PG8_MMA(0, 1, At, B1); PG8_BAR; PG8_SCHED;
	s_add_i32 s15, 0, 0x18000
	s_add_i32 s18, 0, 0x1c000
	v_add_u32_e32 v142, s15, v204
	v_add_u32_e32 v158, s18, v204
	ds_read_b128 v[130:133], v142
	ds_read_b128 v[134:137], v142 offset:1024
	ds_read_b128 v[138:141], v142 offset:2048
	ds_read_b128 v[142:145], v142 offset:3072
	ds_read_b128 v[146:149], v158
	ds_read_b128 v[150:153], v158 offset:1024
	ds_read_b128 v[154:157], v158 offset:2048
	ds_read_b128 v[158:161], v158 offset:3072
	s_add_u32 s6, s42, 0xb0000
	s_addc_u32 s7, s43, 0
	s_mov_b32 m0, s58
	v_lshl_add_u64 v[228:229], s[6:7], 0, v[162:163]
	ds_read_b128 v[182:185], v207 offset:32768
	ds_read_b128 v[186:189], v207 offset:33792
	ds_read_b128 v[192:195], v207 offset:34816
	ds_read_b128 v[196:199], v207 offset:35840
	ds_read_b128 v[200:203], v207 offset:36864
	ds_read_b128 v[208:211], v207 offset:37888
	ds_read_b128 v[212:215], v207 offset:38912
	ds_read_b128 v[216:219], v207 offset:39936
	global_load_lds_dwordx4 v[228:229], off
	v_lshl_add_u64 v[228:229], s[6:7], 0, v[166:167]
	s_mov_b32 m0, s59
	s_nop 0
	global_load_lds_dwordx4 v[228:229], off
	s_waitcnt vmcnt(8)
	s_waitcnt lgkmcnt(0)
	s_barrier
	s_setprio 1
	s_waitcnt lgkmcnt(0)
	v_mfma_f32_16x16x32_bf16 v[126:129], v[130:133], v[182:185], v[126:129]
	v_mfma_f32_16x16x32_bf16 v[122:125], v[138:141], v[182:185], v[122:125]
	v_mfma_f32_16x16x32_bf16 v[110:113], v[130:133], v[192:195], v[110:113]
	v_mfma_f32_16x16x32_bf16 v[106:109], v[138:141], v[192:195], v[106:109]
	v_mfma_f32_16x16x32_bf16 v[94:97], v[130:133], v[200:203], v[94:97]
	v_mfma_f32_16x16x32_bf16 v[90:93], v[138:141], v[200:203], v[90:93]
	v_mfma_f32_16x16x32_bf16 v[78:81], v[130:133], v[212:215], v[78:81]
	v_mfma_f32_16x16x32_bf16 v[74:77], v[138:141], v[212:215], v[74:77]
	v_mfma_f32_16x16x32_bf16 v[126:129], v[134:137], v[186:189], v[126:129]
	v_mfma_f32_16x16x32_bf16 v[122:125], v[142:145], v[186:189], v[122:125]
	v_mfma_f32_16x16x32_bf16 v[110:113], v[134:137], v[196:199], v[110:113]
	v_mfma_f32_16x16x32_bf16 v[106:109], v[142:145], v[196:199], v[106:109]
	v_mfma_f32_16x16x32_bf16 v[94:97], v[134:137], v[208:211], v[94:97]
	v_mfma_f32_16x16x32_bf16 v[90:93], v[142:145], v[208:211], v[90:93]
	v_mfma_f32_16x16x32_bf16 v[78:81], v[134:137], v[216:219], v[78:81]
	v_mfma_f32_16x16x32_bf16 v[74:77], v[142:145], v[216:219], v[74:77]
	s_setprio 0
	s_setprio 1
	v_mfma_f32_16x16x32_bf16 v[118:121], v[146:149], v[182:185], v[118:121]
	v_mfma_f32_16x16x32_bf16 v[114:117], v[154:157], v[182:185], v[114:117]
	v_mfma_f32_16x16x32_bf16 v[102:105], v[146:149], v[192:195], v[102:105]
	v_mfma_f32_16x16x32_bf16 v[98:101], v[154:157], v[192:195], v[98:101]
	v_mfma_f32_16x16x32_bf16 v[86:89], v[146:149], v[200:203], v[86:89]
	v_mfma_f32_16x16x32_bf16 v[82:85], v[154:157], v[200:203], v[82:85]
	v_mfma_f32_16x16x32_bf16 v[70:73], v[146:149], v[212:215], v[70:73]
	v_mfma_f32_16x16x32_bf16 v[66:69], v[154:157], v[212:215], v[66:69]
	v_mfma_f32_16x16x32_bf16 v[118:121], v[150:153], v[186:189], v[118:121]
	v_mfma_f32_16x16x32_bf16 v[114:117], v[158:161], v[186:189], v[114:117]
	v_mfma_f32_16x16x32_bf16 v[102:105], v[150:153], v[196:199], v[102:105]
	v_mfma_f32_16x16x32_bf16 v[98:101], v[158:161], v[196:199], v[98:101]
	v_mfma_f32_16x16x32_bf16 v[86:89], v[150:153], v[208:211], v[86:89]
	v_mfma_f32_16x16x32_bf16 v[82:85], v[158:161], v[208:211], v[82:85]
	v_mfma_f32_16x16x32_bf16 v[70:73], v[150:153], v[216:219], v[70:73]
	v_mfma_f32_16x16x32_bf16 v[66:69], v[158:161], v[216:219], v[66:69]
	s_setprio 0
	s_barrier
; #define PG8_STAGE(bufoff, gbase, voff) do { _Pragma("unroll") for (int _i = 0; _i < 2; ++_i) \
;         __builtin_amdgcn_global_load_lds((const unsigned*)((const char*)(gbase) + (voff)[_i]), (PG8_LAS unsigned*)(lds + (bufoff) + ldsw + _i * 8192), 16, 0, 0); } while (0)
; #define PG8_LDA(dst, b, h) do { _Pragma("unroll") for (int m = 0; m < 4; ++m) _Pragma("unroll") for (int k = 0; k < 2; ++k) dst[m][k] = *(const PG8_LAS bf16x8*)(lds + PG8_SA(b, h) + aoff + m * 2048 + k * 1024); } while (0)
; #define PG8_MMA(ai, bj, At, Bt) do { __builtin_amdgcn_s_setprio(1); _Pragma("unroll") for (int m = 0; m < 4; ++m) _Pragma("unroll") for (int n = 0; n < 2; ++n) _Pragma("unroll") for (int k = 0; k < 2; ++k) \
;         acc[ai][bj][m][n] = __builtin_amdgcn_mfma_f32_16x16x32_bf16(Bt[n][k], At[m][k], acc[ai][bj][m][n], 0, 0, 0); __builtin_amdgcn_s_setprio(0); } while (0)
; #define PG8_WAIT_V(n) asm volatile("s_waitcnt vmcnt(" #n ")" ::: "memory")
; #define PG8_WAIT_L(n) asm volatile("s_waitcnt lgkmcnt(" #n ")" ::: "memory")
; #define PG8_BAR __builtin_amdgcn_s_barrier()
; #define PG8_SCHED __builtin_amdgcn_sched_barrier(0)
; template <class Epi, class Sched, bool ALIGN_EPI = false, bool SP2 = false>
; __device__ __forceinline__ void gemm_phase(PG8_LAS unsigned char* lds, const Gemm g, const Sched& S, const Epi& E, const int tid) {
;     ...
;             PG8_LDA(At, 1, 1); PG8_STAGE(PG8_SB(1, 0), b3, voffB); PG8_STAGE(PG8_SB(1, 1), b3 + hstep, voffB); PG8_STAGE(PG8_SA(1, 0), a3, voffA);
;             PG8_WAIT_V(8); PG8_WAIT_L(0); PG8_BAR; PG8_MMA(1, 0, At, B0); PG8_MMA(1, 1, At, B1); PG8_BAR; PG8_SCHED;
	s_add_i32 s6, s15, s55
	v_lshl_add_u64 v[220:221], v[220:221], 0, s[36:37]
	s_mov_b32 m0, s6
	ds_read_b128 v[182:185], v207 offset:49152
	ds_read_b128 v[186:189], v207 offset:50176
	ds_read_b128 v[192:195], v207 offset:51200
	ds_read_b128 v[196:199], v207 offset:52224
	ds_read_b128 v[200:203], v207 offset:53248
	ds_read_b128 v[208:211], v207 offset:54272
	ds_read_b128 v[212:215], v207 offset:55296
	ds_read_b128 v[216:219], v207 offset:56320
	global_load_lds_dwordx4 v[220:221], off
	s_add_i32 m0, s6, 0x2000
	s_add_u32 s6, s10, 0xb0080
	v_lshl_add_u64 v[220:221], v[222:223], 0, s[36:37]
	s_addc_u32 s7, s11, 0
	s_add_i32 s10, s18, s55
	global_load_lds_dwordx4 v[220:221], off
	v_lshl_add_u64 v[220:221], s[6:7], 0, v[164:165]
	s_mov_b32 m0, s10
	s_nop 0
	global_load_lds_dwordx4 v[220:221], off
	v_lshl_add_u64 v[220:221], s[6:7], 0, v[168:169]
	s_add_i32 m0, s10, 0x2000
	s_nop 0
	global_load_lds_dwordx4 v[220:221], off
	v_lshl_add_u64 v[220:221], v[224:225], 0, s[36:37]
	s_mov_b32 m0, s61
	s_nop 0
	global_load_lds_dwordx4 v[220:221], off
	v_lshl_add_u64 v[220:221], v[226:227], 0, s[36:37]
	s_mov_b32 m0, s62
	s_nop 0
	global_load_lds_dwordx4 v[220:221], off
	s_waitcnt vmcnt(8)
	s_waitcnt lgkmcnt(0)
	s_barrier
	s_setprio 1
	s_waitcnt lgkmcnt(0)
	v_mfma_f32_16x16x32_bf16 v[62:65], v[130:133], v[182:185], v[62:65]
	v_mfma_f32_16x16x32_bf16 v[58:61], v[138:141], v[182:185], v[58:61]
	v_mfma_f32_16x16x32_bf16 v[46:49], v[130:133], v[192:195], v[46:49]
	v_mfma_f32_16x16x32_bf16 v[42:45], v[138:141], v[192:195], v[42:45]
	v_mfma_f32_16x16x32_bf16 v[30:33], v[130:133], v[200:203], v[30:33]
	v_mfma_f32_16x16x32_bf16 v[26:29], v[138:141], v[200:203], v[26:29]
	v_mfma_f32_16x16x32_bf16 v[14:17], v[130:133], v[212:215], v[14:17]
	v_mfma_f32_16x16x32_bf16 v[10:13], v[138:141], v[212:215], v[10:13]
	v_mfma_f32_16x16x32_bf16 v[62:65], v[134:137], v[186:189], v[62:65]
	v_mfma_f32_16x16x32_bf16 v[58:61], v[142:145], v[186:189], v[58:61]
	v_mfma_f32_16x16x32_bf16 v[46:49], v[134:137], v[196:199], v[46:49]
	v_mfma_f32_16x16x32_bf16 v[42:45], v[142:145], v[196:199], v[42:45]
	v_mfma_f32_16x16x32_bf16 v[30:33], v[134:137], v[208:211], v[30:33]
	v_mfma_f32_16x16x32_bf16 v[26:29], v[142:145], v[208:211], v[26:29]
	v_mfma_f32_16x16x32_bf16 v[14:17], v[134:137], v[216:219], v[14:17]
	v_mfma_f32_16x16x32_bf16 v[10:13], v[142:145], v[216:219], v[10:13]
	s_setprio 0
	s_setprio 1
	v_mfma_f32_16x16x32_bf16 v[54:57], v[146:149], v[182:185], v[54:57]
	v_mfma_f32_16x16x32_bf16 v[50:53], v[154:157], v[182:185], v[50:53]
	v_mfma_f32_16x16x32_bf16 v[38:41], v[146:149], v[192:195], v[38:41]
	v_mfma_f32_16x16x32_bf16 v[34:37], v[154:157], v[192:195], v[34:37]
	v_mfma_f32_16x16x32_bf16 v[22:25], v[146:149], v[200:203], v[22:25]
	v_mfma_f32_16x16x32_bf16 v[18:21], v[154:157], v[200:203], v[18:21]
	v_mfma_f32_16x16x32_bf16 v[6:9], v[146:149], v[212:215], v[6:9]
	v_mfma_f32_16x16x32_bf16 v[2:5], v[154:157], v[212:215], v[2:5]
	v_mfma_f32_16x16x32_bf16 v[54:57], v[150:153], v[186:189], v[54:57]
	v_mfma_f32_16x16x32_bf16 v[50:53], v[158:161], v[186:189], v[50:53]
	v_mfma_f32_16x16x32_bf16 v[38:41], v[150:153], v[196:199], v[38:41]
	v_mfma_f32_16x16x32_bf16 v[34:37], v[158:161], v[196:199], v[34:37]
	v_mfma_f32_16x16x32_bf16 v[22:25], v[150:153], v[208:211], v[22:25]
	v_mfma_f32_16x16x32_bf16 v[18:21], v[158:161], v[208:211], v[18:21]
	v_mfma_f32_16x16x32_bf16 v[6:9], v[150:153], v[216:219], v[6:9]
	v_mfma_f32_16x16x32_bf16 v[2:5], v[158:161], v[216:219], v[2:5]
	s_setprio 0
	s_barrier
	s_add_i32 s77, s77, 2
	s_add_u32 s45, s45, 0x100
	s_addc_u32 s47, s47, 0
	s_mov_b64 s[6:7], s[8:9]

; #define PG8_STAGE(bufoff, gbase, voff) do { _Pragma("unroll") for (int _i = 0; _i < 2; ++_i) \
;         __builtin_amdgcn_global_load_lds((const unsigned*)((const char*)(gbase) + (voff)[_i]), (PG8_LAS unsigned*)(lds + (bufoff) + ldsw + _i * 8192), 16, 0, 0); } while (0)
; #define PG8_LDA(dst, b, h) do { _Pragma("unroll") for (int m = 0; m < 4; ++m) _Pragma("unroll") for (int k = 0; k < 2; ++k) dst[m][k] = *(const PG8_LAS bf16x8*)(lds + PG8_SA(b, h) + aoff + m * 2048 + k * 1024); } while (0)
; #define PG8_LDB(dst, b, h) do { _Pragma("unroll") for (int n = 0; n < 2; ++n) _Pragma("unroll") for (int k = 0; k < 2; ++k) dst[n][k] = *(const PG8_LAS bf16x8*)(lds + PG8_SB(b, h) + boff + n * 2048 + k * 1024); } while (0)
; #define PG8_SCHED __builtin_amdgcn_sched_barrier(0)
;     __host__ __device__ bool next(int i, Unit& u) const {
;         const long L = (long)i * G + c; if (L >= nwg) return false;
;         int wgid = (int)L; { const int q = nwg / NXCD, r = nwg % NXCD, xcd = wgid % NXCD, off = wgid / NXCD; wgid = (xcd < r ? xcd * (q + 1) : r * (q + 1) + (xcd - r) * q) + off; }
;         const int nig = WGM * nN, gid = wgid / nig, fm = gid * WGM, gsz = (nM - fm) < WGM ? (nM - fm) : WGM;
;         u.pm = fm + ((wgid % nig) % gsz); u.pn = (wgid % nig) / gsz; u.sub = 0; return true;
; template <class Epi, class Sched, bool ALIGN_EPI = false, bool SP2 = false>
; __device__ __forceinline__ void gemm_phase(PG8_LAS unsigned char* lds, const Gemm g, const Sched& S, const Epi& E, const int tid) {
;     ...
;             PG8_LDB(B0, 0, 0); PG8_LDB(B1, 0, 1); PG8_SCHED; PG8_LDA(At, 0, 0); PG8_STAGE(PG8_SA(1, 1), a1 + hstep, voffA);
.LBB0_726:
	ds_read_b128 v[130:133], v191
	ds_read_b128 v[134:137], v191 offset:1024
	ds_read_b128 v[138:141], v191 offset:2048
	ds_read_b128 v[142:145], v191 offset:3072
	ds_read_b128 v[146:149], v193
	ds_read_b128 v[150:153], v193 offset:1024
	ds_read_b128 v[154:157], v193 offset:2048
	ds_read_b128 v[158:161], v193 offset:3072
	ds_read_b128 v[186:189], v197
	ds_read_b128 v[198:201], v197 offset:1024
	ds_read_b128 v[206:209], v197 offset:2048
	ds_read_b128 v[212:215], v197 offset:3072
	ds_read_b128 v[216:219], v197 offset:4096
	ds_read_b128 v[220:223], v197 offset:5120
	ds_read_b128 v[224:227], v197 offset:6144
	ds_read_b128 v[228:231], v197 offset:7168
	s_add_i32 s78, s78, 1
	s_mul_i32 s2, s78, s64
	s_mul_hi_u32 s3, s78, s45
	s_add_i32 s3, s3, s2
	s_mul_i32 s2, s78, s45
	s_add_u32 s30, s2, s44
	s_addc_u32 s31, s3, s65
	v_cmp_gt_i64_e32 vcc, s[30:31], v[184:185]
	v_cmp_lt_i64_e64 s[2:3], s[30:31], v[182:183]
	s_cbranch_vccnz .LBB0_732
	s_ashr_i32 s15, s30, 31
	s_lshr_b32 s15, s15, 29
	s_add_i32 s15, s30, s15
	s_and_b32 s18, s15, -8
	s_sub_i32 s18, s30, s18
	s_cmp_gt_i32 s18, 3
	s_mov_b64 s[26:27], -1
	s_cbranch_scc0 .LBB0_729
	s_mul_i32 s19, s18, 0x1b4
	s_add_i32 s19, s19, 4
	s_mov_b64 s[26:27], 0

; #define PG8_STAGE(bufoff, gbase, voff) do { _Pragma("unroll") for (int _i = 0; _i < 2; ++_i) \
;         __builtin_amdgcn_global_load_lds((const unsigned*)((const char*)(gbase) + (voff)[_i]), (PG8_LAS unsigned*)(lds + (bufoff) + ldsw + _i * 8192), 16, 0, 0); } while (0)
; #define PG8_LDA(dst, b, h) do { _Pragma("unroll") for (int m = 0; m < 4; ++m) _Pragma("unroll") for (int k = 0; k < 2; ++k) dst[m][k] = *(const PG8_LAS bf16x8*)(lds + PG8_SA(b, h) + aoff + m * 2048 + k * 1024); } while (0)
; #define PG8_LDB(dst, b, h) do { _Pragma("unroll") for (int n = 0; n < 2; ++n) _Pragma("unroll") for (int k = 0; k < 2; ++k) dst[n][k] = *(const PG8_LAS bf16x8*)(lds + PG8_SB(b, h) + boff + n * 2048 + k * 1024); } while (0)
; #define PG8_MMA(ai, bj, At, Bt) do { __builtin_amdgcn_s_setprio(1); _Pragma("unroll") for (int m = 0; m < 4; ++m) _Pragma("unroll") for (int n = 0; n < 2; ++n) _Pragma("unroll") for (int k = 0; k < 2; ++k) \
;         acc[ai][bj][m][n] = __builtin_amdgcn_mfma_f32_16x16x32_bf16(Bt[n][k], At[m][k], acc[ai][bj][m][n], 0, 0, 0); __builtin_amdgcn_s_setprio(0); } while (0)
; template <class Epi, class Sched, bool ALIGN_EPI = false, bool SP2 = false>
; __device__ __forceinline__ void gemm_phase(PG8_LAS unsigned char* lds, const Gemm g, const Sched& S, const Epi& E, const int tid) {
;     ...
;         const char* nA = has_next ? S.aptr(nxt) : cA; const char* nB = has_next ? S.bptr(nxt) : cB;
;         for (int t = 0; t < nt; t += 2) {
;             const bool last = (t == nt - 2);
;             const char* a1 = cA + (size_t)(t + 1) * kstep;
;             const char* a2 = last ? nA : cA + (size_t)(t + 2) * kstep; const char* b2 = last ? nB : cB + (size_t)(t + 2) * kstep;
;             const char* a3 = a2 + kstep; const char* b3 = b2 + kstep;
;             if (last && has_next) S.a_ready(nxt);
;             if constexpr (SP2) {
;             PG8_LDB(B0, 0, 0); PG8_LDB(B1, 0, 1); PG8_SCHED; PG8_LDA(At, 0, 0); PG8_STAGE(PG8_SA(1, 1), a1 + hstep, voffA);
;             PG8_WAIT_V(8); PG8_WAIT_L(0); PG8_BAR; PG8_MMA(0, 0, At, B0); PG8_MMA(0, 1, At, B1); PG8_BAR; PG8_SCHED;
;             PG8_LDA(At, 0, 1); PG8_STAGE(PG8_SB(0, 0), b2, voffB); PG8_STAGE(PG8_SB(0, 1), b2 + hstep, voffB); PG8_STAGE(PG8_SA(0, 0), a2, voffA);
;             PG8_WAIT_V(8); PG8_WAIT_L(0); PG8_BAR; PG8_MMA(1, 0, At, B0); PG8_MMA(1, 1, At, B1); PG8_BAR; PG8_SCHED;
.LBB0_732:
	s_ashr_i32 s29, s28, 31
	s_lshl_b64 s[18:19], s[28:29], 19
	s_add_u32 s30, s50, s18
	s_addc_u32 s31, s51, s19
	s_and_b64 s[18:19], s[2:3], exec
	s_cselect_b32 s29, s31, s41
	s_cselect_b32 s37, s30, s40
	s_ashr_i32 s27, s26, 31
	s_lshl_b64 s[18:19], s[26:27], 19
	s_add_u32 s34, s52, s18
	s_addc_u32 s35, s53, s19
	s_and_b64 s[18:19], s[2:3], exec
	s_cselect_b32 s27, s35, s39
	s_cselect_b32 s79, s34, s38
	s_add_u32 s80, s38, 0x100
	s_addc_u32 s81, s39, 0
	s_add_u32 s38, s40, 0x40080
	s_addc_u32 s39, s41, 0
	s_mov_b32 s82, -2
	s_add_u32 s15, s38, 0xfffc0080
	s_addc_u32 s18, s39, -1
	s_cmp_eq_u32 s82, 12
	s_cselect_b32 s43, s29, s18
	s_cselect_b32 s42, s37, s15
	s_cselect_b32 s41, s27, s81
	s_cselect_b32 s40, s79, s80
	v_lshl_add_u64 v[194:195], s[38:39], 0, v[180:181]
	s_add_i32 m0, s55, 0xc000
	global_load_lds_dwordx4 v[194:195], off
	v_lshl_add_u64 v[194:195], s[38:39], 0, v[178:179]
	s_add_i32 m0, s55, 0xe000
	s_nop 0
	global_load_lds_dwordx4 v[194:195], off
	s_waitcnt vmcnt(8)
	s_waitcnt lgkmcnt(0)
	s_barrier
	s_setprio 1
	s_waitcnt lgkmcnt(0)
	v_mfma_f32_16x16x32_bf16 v[126:129], v[130:133], v[186:189], 0
	v_mfma_f32_16x16x32_bf16 v[122:125], v[138:141], v[186:189], 0
	v_mfma_f32_16x16x32_bf16 v[110:113], v[130:133], v[206:209], 0
	v_mfma_f32_16x16x32_bf16 v[106:109], v[138:141], v[206:209], 0
	v_mfma_f32_16x16x32_bf16 v[94:97], v[130:133], v[216:219], 0
	v_mfma_f32_16x16x32_bf16 v[90:93], v[138:141], v[216:219], 0
	v_mfma_f32_16x16x32_bf16 v[78:81], v[130:133], v[224:227], 0
	v_mfma_f32_16x16x32_bf16 v[74:77], v[138:141], v[224:227], 0
	v_mfma_f32_16x16x32_bf16 v[126:129], v[134:137], v[198:201], v[126:129]
	v_mfma_f32_16x16x32_bf16 v[122:125], v[142:145], v[198:201], v[122:125]
	v_mfma_f32_16x16x32_bf16 v[110:113], v[134:137], v[212:215], v[110:113]
	v_mfma_f32_16x16x32_bf16 v[106:109], v[142:145], v[212:215], v[106:109]
	v_mfma_f32_16x16x32_bf16 v[94:97], v[134:137], v[220:223], v[94:97]
	v_mfma_f32_16x16x32_bf16 v[90:93], v[142:145], v[220:223], v[90:93]
	v_mfma_f32_16x16x32_bf16 v[78:81], v[134:137], v[228:231], v[78:81]
	v_mfma_f32_16x16x32_bf16 v[74:77], v[142:145], v[228:231], v[74:77]
	s_setprio 0
	s_setprio 1
	v_mfma_f32_16x16x32_bf16 v[118:121], v[146:149], v[186:189], 0
	v_mfma_f32_16x16x32_bf16 v[114:117], v[154:157], v[186:189], 0
	v_mfma_f32_16x16x32_bf16 v[102:105], v[146:149], v[206:209], 0
	v_mfma_f32_16x16x32_bf16 v[98:101], v[154:157], v[206:209], 0
	v_mfma_f32_16x16x32_bf16 v[86:89], v[146:149], v[216:219], 0
	v_mfma_f32_16x16x32_bf16 v[82:85], v[154:157], v[216:219], 0
	v_mfma_f32_16x16x32_bf16 v[70:73], v[146:149], v[224:227], 0
	v_mfma_f32_16x16x32_bf16 v[66:69], v[154:157], v[224:227], 0
	v_mfma_f32_16x16x32_bf16 v[118:121], v[150:153], v[198:201], v[118:121]
	v_mfma_f32_16x16x32_bf16 v[114:117], v[158:161], v[198:201], v[114:117]
	v_mfma_f32_16x16x32_bf16 v[102:105], v[150:153], v[212:215], v[102:105]
	v_mfma_f32_16x16x32_bf16 v[98:101], v[158:161], v[212:215], v[98:101]
	v_mfma_f32_16x16x32_bf16 v[86:89], v[150:153], v[220:223], v[86:89]
	v_mfma_f32_16x16x32_bf16 v[82:85], v[158:161], v[220:223], v[82:85]
	v_mfma_f32_16x16x32_bf16 v[70:73], v[150:153], v[228:231], v[70:73]
	v_mfma_f32_16x16x32_bf16 v[66:69], v[158:161], v[228:231], v[66:69]
	s_setprio 0
	s_barrier
	s_add_i32 s15, s66, s54
	v_lshl_add_u64 v[194:195], s[40:41], 0, v[164:165]
	s_mov_b32 m0, s15
	ds_read_b128 v[186:189], v197 offset:16384
	ds_read_b128 v[198:201], v197 offset:17408
	ds_read_b128 v[206:209], v197 offset:18432
	ds_read_b128 v[212:215], v197 offset:19456
	ds_read_b128 v[216:219], v197 offset:20480
	ds_read_b128 v[220:223], v197 offset:21504
	ds_read_b128 v[224:227], v197 offset:22528
	ds_read_b128 v[228:231], v197 offset:23552
	global_load_lds_dwordx4 v[194:195], off
	s_add_i32 m0, s15, 0x2000
	s_add_u32 s18, s40, 0x40000
	v_lshl_add_u64 v[232:233], s[40:41], 0, v[168:169]
	s_addc_u32 s19, s41, 0
	s_add_i32 s15, s67, s54
	global_load_lds_dwordx4 v[232:233], off
	v_lshl_add_u64 v[234:235], s[18:19], 0, v[164:165]
	s_mov_b32 m0, s15
	v_lshl_add_u64 v[236:237], s[42:43], 0, v[166:167]
	global_load_lds_dwordx4 v[234:235], off
	v_lshl_add_u64 v[234:235], s[18:19], 0, v[168:169]
	s_add_i32 m0, s15, 0x2000
	s_nop 0
	global_load_lds_dwordx4 v[234:235], off
	v_lshl_add_u64 v[234:235], s[42:43], 0, v[162:163]
	s_mov_b32 m0, s55
	s_nop 0
	global_load_lds_dwordx4 v[234:235], off
	s_mov_b32 m0, s56
	s_nop 0
	global_load_lds_dwordx4 v[236:237], off
	s_waitcnt vmcnt(8)
	s_waitcnt lgkmcnt(0)
	s_barrier
	s_setprio 1
	s_waitcnt lgkmcnt(0)
	v_mfma_f32_16x16x32_bf16 v[62:65], v[130:133], v[186:189], 0
	v_mfma_f32_16x16x32_bf16 v[58:61], v[138:141], v[186:189], 0
	v_mfma_f32_16x16x32_bf16 v[46:49], v[130:133], v[206:209], 0
	v_mfma_f32_16x16x32_bf16 v[42:45], v[138:141], v[206:209], 0
	v_mfma_f32_16x16x32_bf16 v[30:33], v[130:133], v[216:219], 0
	v_mfma_f32_16x16x32_bf16 v[26:29], v[138:141], v[216:219], 0
	v_mfma_f32_16x16x32_bf16 v[14:17], v[130:133], v[224:227], 0
	v_mfma_f32_16x16x32_bf16 v[10:13], v[138:141], v[224:227], 0
	v_mfma_f32_16x16x32_bf16 v[62:65], v[134:137], v[198:201], v[62:65]
	v_mfma_f32_16x16x32_bf16 v[58:61], v[142:145], v[198:201], v[58:61]
	v_mfma_f32_16x16x32_bf16 v[46:49], v[134:137], v[212:215], v[46:49]
	v_mfma_f32_16x16x32_bf16 v[42:45], v[142:145], v[212:215], v[42:45]
	v_mfma_f32_16x16x32_bf16 v[30:33], v[134:137], v[220:223], v[30:33]
	v_mfma_f32_16x16x32_bf16 v[26:29], v[142:145], v[220:223], v[26:29]
	v_mfma_f32_16x16x32_bf16 v[14:17], v[134:137], v[228:231], v[14:17]
	v_mfma_f32_16x16x32_bf16 v[10:13], v[142:145], v[228:231], v[10:13]
	s_setprio 0
	s_setprio 1
	v_mfma_f32_16x16x32_bf16 v[54:57], v[146:149], v[186:189], 0
	v_mfma_f32_16x16x32_bf16 v[50:53], v[154:157], v[186:189], 0
	v_mfma_f32_16x16x32_bf16 v[38:41], v[146:149], v[206:209], 0
	v_mfma_f32_16x16x32_bf16 v[34:37], v[154:157], v[206:209], 0
	v_mfma_f32_16x16x32_bf16 v[22:25], v[146:149], v[216:219], 0
	v_mfma_f32_16x16x32_bf16 v[18:21], v[154:157], v[216:219], 0
	v_mfma_f32_16x16x32_bf16 v[6:9], v[146:149], v[224:227], 0
	v_mfma_f32_16x16x32_bf16 v[2:5], v[154:157], v[224:227], 0
	v_mfma_f32_16x16x32_bf16 v[54:57], v[150:153], v[198:201], v[54:57]
	v_mfma_f32_16x16x32_bf16 v[50:53], v[158:161], v[198:201], v[50:53]
	v_mfma_f32_16x16x32_bf16 v[38:41], v[150:153], v[212:215], v[38:41]
	v_mfma_f32_16x16x32_bf16 v[34:37], v[158:161], v[212:215], v[34:37]
	v_mfma_f32_16x16x32_bf16 v[22:25], v[150:153], v[220:223], v[22:25]
	v_mfma_f32_16x16x32_bf16 v[18:21], v[158:161], v[220:223], v[18:21]
	v_mfma_f32_16x16x32_bf16 v[6:9], v[150:153], v[228:231], v[6:9]
	v_mfma_f32_16x16x32_bf16 v[2:5], v[158:161], v[228:231], v[2:5]
	s_setprio 0
	s_barrier
; #define PG8_STAGE(bufoff, gbase, voff) do { _Pragma("unroll") for (int _i = 0; _i < 2; ++_i) \
;         __builtin_amdgcn_global_load_lds((const unsigned*)((const char*)(gbase) + (voff)[_i]), (PG8_LAS unsigned*)(lds + (bufoff) + ldsw + _i * 8192), 16, 0, 0); } while (0)
; #define PG8_LDA(dst, b, h) do { _Pragma("unroll") for (int m = 0; m < 4; ++m) _Pragma("unroll") for (int k = 0; k < 2; ++k) dst[m][k] = *(const PG8_LAS bf16x8*)(lds + PG8_SA(b, h) + aoff + m * 2048 + k * 1024); } while (0)
; #define PG8_LDB(dst, b, h) do { _Pragma("unroll") for (int n = 0; n < 2; ++n) _Pragma("unroll") for (int k = 0; k < 2; ++k) dst[n][k] = *(const PG8_LAS bf16x8*)(lds + PG8_SB(b, h) + boff + n * 2048 + k * 1024); } while (0)
; #define PG8_MMA(ai, bj, At, Bt) do { __builtin_amdgcn_s_setprio(1); _Pragma("unroll") for (int m = 0; m < 4; ++m) _Pragma("unroll") for (int n = 0; n < 2; ++n) _Pragma("unroll") for (int k = 0; k < 2; ++k) \
;         acc[ai][bj][m][n] = __builtin_amdgcn_mfma_f32_16x16x32_bf16(Bt[n][k], At[m][k], acc[ai][bj][m][n], 0, 0, 0); __builtin_amdgcn_s_setprio(0); } while (0)
; #define PG8_WAIT_V(n) asm volatile("s_waitcnt vmcnt(" #n ")" ::: "memory")
; #define PG8_WAIT_L(n) asm volatile("s_waitcnt lgkmcnt(" #n ")" ::: "memory")
; #define PG8_BAR __builtin_amdgcn_s_barrier()
; #define PG8_SCHED __builtin_amdgcn_sched_barrier(0)
; template <class Epi, class Sched, bool ALIGN_EPI = false, bool SP2 = false>
; __device__ __forceinline__ void gemm_phase(PG8_LAS unsigned char* lds, const Gemm g, const Sched& S, const Epi& E, const int tid) {
;     ...
;             PG8_LDB(B0, 1, 0); PG8_LDB(B1, 1, 1); PG8_SCHED; PG8_LDA(At, 1, 0); PG8_STAGE(PG8_SA(0, 1), a2 + hstep, voffA);
;             PG8_WAIT_V(8); PG8_WAIT_L(0); PG8_BAR; PG8_MMA(0, 0, At, B0); PG8_MMA(0, 1, At, B1); PG8_BAR; PG8_SCHED;
	s_add_i32 s15, 0, 0x18000
	s_add_i32 s83, 0, 0x1c000
	v_add_u32_e32 v142, s15, v173
	v_add_u32_e32 v158, s83, v173
	ds_read_b128 v[130:133], v142
	ds_read_b128 v[134:137], v142 offset:1024
	ds_read_b128 v[138:141], v142 offset:2048
	ds_read_b128 v[142:145], v142 offset:3072
	ds_read_b128 v[146:149], v158
	ds_read_b128 v[150:153], v158 offset:1024
	ds_read_b128 v[154:157], v158 offset:2048
	ds_read_b128 v[158:161], v158 offset:3072
	s_add_u32 s18, s42, 0x40000
	s_addc_u32 s19, s43, 0
	s_mov_b32 m0, s57
	v_lshl_add_u64 v[238:239], s[18:19], 0, v[162:163]
	ds_read_b128 v[186:189], v197 offset:32768
	ds_read_b128 v[198:201], v197 offset:33792
	ds_read_b128 v[206:209], v197 offset:34816
	ds_read_b128 v[212:215], v197 offset:35840
	ds_read_b128 v[216:219], v197 offset:36864
	ds_read_b128 v[220:223], v197 offset:37888
	ds_read_b128 v[224:227], v197 offset:38912
	ds_read_b128 v[228:231], v197 offset:39936
	global_load_lds_dwordx4 v[238:239], off
	v_lshl_add_u64 v[238:239], s[18:19], 0, v[166:167]
	s_mov_b32 m0, s58
	s_nop 0
	global_load_lds_dwordx4 v[238:239], off
	s_waitcnt vmcnt(8)
	s_waitcnt lgkmcnt(0)
	s_barrier
	s_setprio 1
	s_waitcnt lgkmcnt(0)
	v_mfma_f32_16x16x32_bf16 v[126:129], v[130:133], v[186:189], v[126:129]
	v_mfma_f32_16x16x32_bf16 v[122:125], v[138:141], v[186:189], v[122:125]
	v_mfma_f32_16x16x32_bf16 v[110:113], v[130:133], v[206:209], v[110:113]
	v_mfma_f32_16x16x32_bf16 v[106:109], v[138:141], v[206:209], v[106:109]
	v_mfma_f32_16x16x32_bf16 v[94:97], v[130:133], v[216:219], v[94:97]
	v_mfma_f32_16x16x32_bf16 v[90:93], v[138:141], v[216:219], v[90:93]
	v_mfma_f32_16x16x32_bf16 v[78:81], v[130:133], v[224:227], v[78:81]
	v_mfma_f32_16x16x32_bf16 v[74:77], v[138:141], v[224:227], v[74:77]
	v_mfma_f32_16x16x32_bf16 v[126:129], v[134:137], v[198:201], v[126:129]
	v_mfma_f32_16x16x32_bf16 v[122:125], v[142:145], v[198:201], v[122:125]
	v_mfma_f32_16x16x32_bf16 v[110:113], v[134:137], v[212:215], v[110:113]
	v_mfma_f32_16x16x32_bf16 v[106:109], v[142:145], v[212:215], v[106:109]
	v_mfma_f32_16x16x32_bf16 v[94:97], v[134:137], v[220:223], v[94:97]
	v_mfma_f32_16x16x32_bf16 v[90:93], v[142:145], v[220:223], v[90:93]
	v_mfma_f32_16x16x32_bf16 v[78:81], v[134:137], v[228:231], v[78:81]
	v_mfma_f32_16x16x32_bf16 v[74:77], v[142:145], v[228:231], v[74:77]
	s_setprio 0
	s_setprio 1
	v_mfma_f32_16x16x32_bf16 v[118:121], v[146:149], v[186:189], v[118:121]
	v_mfma_f32_16x16x32_bf16 v[114:117], v[154:157], v[186:189], v[114:117]
	v_mfma_f32_16x16x32_bf16 v[102:105], v[146:149], v[206:209], v[102:105]
	v_mfma_f32_16x16x32_bf16 v[98:101], v[154:157], v[206:209], v[98:101]
	v_mfma_f32_16x16x32_bf16 v[86:89], v[146:149], v[216:219], v[86:89]
	v_mfma_f32_16x16x32_bf16 v[82:85], v[154:157], v[216:219], v[82:85]
	v_mfma_f32_16x16x32_bf16 v[70:73], v[146:149], v[224:227], v[70:73]
	v_mfma_f32_16x16x32_bf16 v[66:69], v[154:157], v[224:227], v[66:69]
	v_mfma_f32_16x16x32_bf16 v[118:121], v[150:153], v[198:201], v[118:121]
	v_mfma_f32_16x16x32_bf16 v[114:117], v[158:161], v[198:201], v[114:117]
	v_mfma_f32_16x16x32_bf16 v[102:105], v[150:153], v[212:215], v[102:105]
	v_mfma_f32_16x16x32_bf16 v[98:101], v[158:161], v[212:215], v[98:101]
	v_mfma_f32_16x16x32_bf16 v[86:89], v[150:153], v[220:223], v[86:89]
	v_mfma_f32_16x16x32_bf16 v[82:85], v[158:161], v[220:223], v[82:85]
	v_mfma_f32_16x16x32_bf16 v[70:73], v[150:153], v[228:231], v[70:73]
	v_mfma_f32_16x16x32_bf16 v[66:69], v[158:161], v[228:231], v[66:69]
	s_setprio 0
	s_barrier
; #define PG8_STAGE(bufoff, gbase, voff) do { _Pragma("unroll") for (int _i = 0; _i < 2; ++_i) \
;         __builtin_amdgcn_global_load_lds((const unsigned*)((const char*)(gbase) + (voff)[_i]), (PG8_LAS unsigned*)(lds + (bufoff) + ldsw + _i * 8192), 16, 0, 0); } while (0)
; #define PG8_LDA(dst, b, h) do { _Pragma("unroll") for (int m = 0; m < 4; ++m) _Pragma("unroll") for (int k = 0; k < 2; ++k) dst[m][k] = *(const PG8_LAS bf16x8*)(lds + PG8_SA(b, h) + aoff + m * 2048 + k * 1024); } while (0)
; #define PG8_MMA(ai, bj, At, Bt) do { __builtin_amdgcn_s_setprio(1); _Pragma("unroll") for (int m = 0; m < 4; ++m) _Pragma("unroll") for (int n = 0; n < 2; ++n) _Pragma("unroll") for (int k = 0; k < 2; ++k) \
;         acc[ai][bj][m][n] = __builtin_amdgcn_mfma_f32_16x16x32_bf16(Bt[n][k], At[m][k], acc[ai][bj][m][n], 0, 0, 0); __builtin_amdgcn_s_setprio(0); } while (0)
; #define PG8_WAIT_V(n) asm volatile("s_waitcnt vmcnt(" #n ")" ::: "memory")
; #define PG8_WAIT_L(n) asm volatile("s_waitcnt lgkmcnt(" #n ")" ::: "memory")
; #define PG8_BAR __builtin_amdgcn_s_barrier()
; #define PG8_SCHED __builtin_amdgcn_sched_barrier(0)
; template <class Epi, class Sched, bool ALIGN_EPI = false, bool SP2 = false>
; __device__ __forceinline__ void gemm_phase(PG8_LAS unsigned char* lds, const Gemm g, const Sched& S, const Epi& E, const int tid) {
;     ...
;             PG8_LDA(At, 1, 1); PG8_STAGE(PG8_SB(1, 0), b3, voffB); PG8_STAGE(PG8_SB(1, 1), b3 + hstep, voffB); PG8_STAGE(PG8_SA(1, 0), a3, voffA);
;             PG8_WAIT_V(8); PG8_WAIT_L(0); PG8_BAR; PG8_MMA(1, 0, At, B0); PG8_MMA(1, 1, At, B1); PG8_BAR; PG8_SCHED;
	s_add_i32 s15, s15, s54
	v_lshl_add_u64 v[194:195], v[194:195], 0, s[10:11]
	s_mov_b32 m0, s15
	ds_read_b128 v[186:189], v197 offset:49152
	ds_read_b128 v[198:201], v197 offset:50176
	ds_read_b128 v[206:209], v197 offset:51200
	ds_read_b128 v[212:215], v197 offset:52224
	ds_read_b128 v[216:219], v197 offset:53248
	ds_read_b128 v[220:223], v197 offset:54272
	ds_read_b128 v[224:227], v197 offset:55296
	ds_read_b128 v[228:231], v197 offset:56320
	global_load_lds_dwordx4 v[194:195], off
	s_add_i32 m0, s15, 0x2000
	s_add_u32 s18, s40, 0x40080
	v_lshl_add_u64 v[194:195], v[232:233], 0, s[10:11]
	s_addc_u32 s19, s41, 0
	s_add_i32 s15, s83, s54
	global_load_lds_dwordx4 v[194:195], off
	v_lshl_add_u64 v[194:195], s[18:19], 0, v[164:165]
	s_mov_b32 m0, s15
	s_nop 0
	global_load_lds_dwordx4 v[194:195], off
	v_lshl_add_u64 v[194:195], s[18:19], 0, v[168:169]
	s_add_i32 m0, s15, 0x2000
	s_nop 0
	global_load_lds_dwordx4 v[194:195], off
	v_lshl_add_u64 v[194:195], v[234:235], 0, s[10:11]
	s_mov_b32 m0, s61
	s_nop 0
	global_load_lds_dwordx4 v[194:195], off
	v_lshl_add_u64 v[194:195], v[236:237], 0, s[10:11]
	s_mov_b32 m0, s62
	s_nop 0
	global_load_lds_dwordx4 v[194:195], off
	s_waitcnt vmcnt(8)
	s_waitcnt lgkmcnt(0)
	s_barrier
	s_setprio 1
	s_waitcnt lgkmcnt(0)
	v_mfma_f32_16x16x32_bf16 v[62:65], v[130:133], v[186:189], v[62:65]
	v_mfma_f32_16x16x32_bf16 v[58:61], v[138:141], v[186:189], v[58:61]
	v_mfma_f32_16x16x32_bf16 v[46:49], v[130:133], v[206:209], v[46:49]
	v_mfma_f32_16x16x32_bf16 v[42:45], v[138:141], v[206:209], v[42:45]
	v_mfma_f32_16x16x32_bf16 v[30:33], v[130:133], v[216:219], v[30:33]
	v_mfma_f32_16x16x32_bf16 v[26:29], v[138:141], v[216:219], v[26:29]
	v_mfma_f32_16x16x32_bf16 v[14:17], v[130:133], v[224:227], v[14:17]
	v_mfma_f32_16x16x32_bf16 v[10:13], v[138:141], v[224:227], v[10:13]
	v_mfma_f32_16x16x32_bf16 v[62:65], v[134:137], v[198:201], v[62:65]
	v_mfma_f32_16x16x32_bf16 v[58:61], v[142:145], v[198:201], v[58:61]
	v_mfma_f32_16x16x32_bf16 v[46:49], v[134:137], v[212:215], v[46:49]
	v_mfma_f32_16x16x32_bf16 v[42:45], v[142:145], v[212:215], v[42:45]
	v_mfma_f32_16x16x32_bf16 v[30:33], v[134:137], v[220:223], v[30:33]
	v_mfma_f32_16x16x32_bf16 v[26:29], v[142:145], v[220:223], v[26:29]
	v_mfma_f32_16x16x32_bf16 v[14:17], v[134:137], v[228:231], v[14:17]
	v_mfma_f32_16x16x32_bf16 v[10:13], v[142:145], v[228:231], v[10:13]
	s_setprio 0
	s_setprio 1
	v_mfma_f32_16x16x32_bf16 v[54:57], v[146:149], v[186:189], v[54:57]
	v_mfma_f32_16x16x32_bf16 v[50:53], v[154:157], v[186:189], v[50:53]
	v_mfma_f32_16x16x32_bf16 v[38:41], v[146:149], v[206:209], v[38:41]
	v_mfma_f32_16x16x32_bf16 v[34:37], v[154:157], v[206:209], v[34:37]
	v_mfma_f32_16x16x32_bf16 v[22:25], v[146:149], v[216:219], v[22:25]
	v_mfma_f32_16x16x32_bf16 v[18:21], v[154:157], v[216:219], v[18:21]
	v_mfma_f32_16x16x32_bf16 v[6:9], v[146:149], v[224:227], v[6:9]
	v_mfma_f32_16x16x32_bf16 v[2:5], v[154:157], v[224:227], v[2:5]
	v_mfma_f32_16x16x32_bf16 v[54:57], v[150:153], v[198:201], v[54:57]
	v_mfma_f32_16x16x32_bf16 v[50:53], v[158:161], v[198:201], v[50:53]
	v_mfma_f32_16x16x32_bf16 v[38:41], v[150:153], v[212:215], v[38:41]
	v_mfma_f32_16x16x32_bf16 v[34:37], v[158:161], v[212:215], v[34:37]
	v_mfma_f32_16x16x32_bf16 v[22:25], v[150:153], v[220:223], v[22:25]
	v_mfma_f32_16x16x32_bf16 v[18:21], v[158:161], v[220:223], v[18:21]
	v_mfma_f32_16x16x32_bf16 v[6:9], v[150:153], v[228:231], v[6:9]
	v_mfma_f32_16x16x32_bf16 v[2:5], v[158:161], v[228:231], v[2:5]
	s_setprio 0
	s_barrier
	s_add_i32 s82, s82, 2
	s_add_u32 s80, s80, 0x100
	s_addc_u32 s81, s81, 0
	s_add_u32 s38, s38, 0x100
	s_addc_u32 s39, s39, 0

; #define PG8_STAGE(bufoff, gbase, voff) do { _Pragma("unroll") for (int _i = 0; _i < 2; ++_i) \
;         __builtin_amdgcn_global_load_lds((const unsigned*)((const char*)(gbase) + (voff)[_i]), (PG8_LAS unsigned*)(lds + (bufoff) + ldsw + _i * 8192), 16, 0, 0); } while (0)
; #define PG8_LDA(dst, b, h) do { _Pragma("unroll") for (int m = 0; m < 4; ++m) _Pragma("unroll") for (int k = 0; k < 2; ++k) dst[m][k] = *(const PG8_LAS bf16x8*)(lds + PG8_SA(b, h) + aoff + m * 2048 + k * 1024); } while (0)
; #define PG8_LDB(dst, b, h) do { _Pragma("unroll") for (int n = 0; n < 2; ++n) _Pragma("unroll") for (int k = 0; k < 2; ++k) dst[n][k] = *(const PG8_LAS bf16x8*)(lds + PG8_SB(b, h) + boff + n * 2048 + k * 1024); } while (0)
; #define PG8_SCHED __builtin_amdgcn_sched_barrier(0)
;     __host__ __device__ bool next(int i, Unit& u) const {
;         const long L = (long)i * G + c; if (L >= nwg) return false;
;         int wgid = (int)L; { const int q = nwg / NXCD, r = nwg % NXCD, xcd = wgid % NXCD, off = wgid / NXCD; wgid = (xcd < r ? xcd * (q + 1) : r * (q + 1) + (xcd - r) * q) + off; }
;         const int nig = WGM * nN, gid = wgid / nig, fm = gid * WGM, gsz = (nM - fm) < WGM ? (nM - fm) : WGM;
;         u.pm = fm + ((wgid % nig) % gsz); u.pn = (wgid % nig) / gsz; u.sub = 0; return true;
; template <class Epi, class Sched, bool ALIGN_EPI = false, bool SP2 = false>
; __device__ __forceinline__ void gemm_phase(PG8_LAS unsigned char* lds, const Gemm g, const Sched& S, const Epi& E, const int tid) {
;     ...
;             PG8_LDB(B0, 0, 0); PG8_LDB(B1, 0, 1); PG8_SCHED; PG8_LDA(At, 0, 0); PG8_STAGE(PG8_SA(1, 1), a1 + hstep, voffA);
.LBB0_1093:
	ds_read_b128 v[130:133], v139
	ds_read_b128 v[134:137], v139 offset:1024
	ds_read_b128 v[162:165], v139 offset:2048
	ds_read_b128 v[166:169], v139 offset:3072
	ds_read_b128 v[176:179], v173
	ds_read_b128 v[180:183], v173 offset:1024
	ds_read_b128 v[184:187], v173 offset:2048
	ds_read_b128 v[192:195], v173 offset:3072
	ds_read_b128 v[196:199], v174
	ds_read_b128 v[200:203], v174 offset:1024
	ds_read_b128 v[204:207], v174 offset:2048
	ds_read_b128 v[208:211], v174 offset:3072
	ds_read_b128 v[212:215], v174 offset:4096
	ds_read_b128 v[216:219], v174 offset:5120
	ds_read_b128 v[220:223], v174 offset:6144
	ds_read_b128 v[224:227], v174 offset:7168
	s_add_i32 s94, s94, 1
	s_lshr_b32 s0, s94, 2
	s_mul_hi_i32 s1, s0, s64
	s_mul_i32 s0, s0, s64
	s_add_u32 s2, s0, s8
	s_addc_u32 s3, s1, s9
	v_cmp_gt_i64_e32 vcc, s[2:3], v[160:161]
	v_cmp_lt_i64_e64 s[0:1], s[2:3], v[158:159]
	s_cbranch_vccnz .LBB0_1095
	s_ashr_i32 s3, s2, 31
	s_lshr_b32 s3, s3, 29
	s_add_i32 s3, s2, s3
	s_ashr_i32 s5, s3, 3
	s_and_b32 s3, s3, -8
	s_sub_i32 s2, s2, s3
	s_cmp_lt_i32 s2, 0
	s_cselect_b32 s3, s85, 0x61
	s_mul_i32 s2, s3, s2
	s_add_i32 s2, s2, s5
	s_ashr_i32 s3, s2, 31
	s_lshr_b32 s3, s3, 27
	s_add_i32 s3, s2, s3
	s_ashr_i32 s5, s3, 5
	s_lshl_b32 s5, s5, 3
	s_sub_i32 s15, 0xc2, s5
	s_min_i32 s15, s15, 8
	s_abs_i32 s18, s15
	v_cvt_f32_u32_e32 v2, s18
	s_sub_i32 s48, 0, s18
	s_andn2_b32 s3, s3, 31
	s_sub_i32 s2, s2, s3
	v_rcp_iflag_f32_e32 v2, v2
	s_abs_i32 s3, s2
	s_xor_b32 s19, s2, s15
	s_ashr_i32 s19, s19, 31
	v_mul_f32_e32 v2, 0x4f7ffffe, v2
	v_cvt_u32_f32_e32 v2, v2
	s_nop 0
	v_readfirstlane_b32 s49, v2
	s_mul_i32 s48, s48, s49
	s_mul_hi_u32 s48, s49, s48
	s_add_i32 s49, s49, s48
	s_mul_hi_u32 s48, s3, s49
	s_mul_i32 s49, s48, s18
	s_sub_i32 s3, s3, s49
	s_add_i32 s50, s48, 1
	s_sub_i32 s49, s3, s18
	s_cmp_ge_u32 s3, s18
	s_cselect_b32 s48, s50, s48
	s_cselect_b32 s3, s49, s3
	s_add_i32 s49, s48, 1
	s_cmp_ge_u32 s3, s18
	s_cselect_b32 s3, s49, s48
	s_xor_b32 s3, s3, s19
	s_sub_i32 s48, s3, s19
	s_mul_i32 s3, s48, s15
	s_sub_i32 s2, s2, s3
	s_add_i32 s50, s2, s5
	s_and_b32 s95, s94, 3

; #define PG8_STAGE(bufoff, gbase, voff) do { _Pragma("unroll") for (int _i = 0; _i < 2; ++_i) \
;         __builtin_amdgcn_global_load_lds((const unsigned*)((const char*)(gbase) + (voff)[_i]), (PG8_LAS unsigned*)(lds + (bufoff) + ldsw + _i * 8192), 16, 0, 0); } while (0)
; #define PG8_LDA(dst, b, h) do { _Pragma("unroll") for (int m = 0; m < 4; ++m) _Pragma("unroll") for (int k = 0; k < 2; ++k) dst[m][k] = *(const PG8_LAS bf16x8*)(lds + PG8_SA(b, h) + aoff + m * 2048 + k * 1024); } while (0)
; #define PG8_LDB(dst, b, h) do { _Pragma("unroll") for (int n = 0; n < 2; ++n) _Pragma("unroll") for (int k = 0; k < 2; ++k) dst[n][k] = *(const PG8_LAS bf16x8*)(lds + PG8_SB(b, h) + boff + n * 2048 + k * 1024); } while (0)
; #define PG8_MMA(ai, bj, At, Bt) do { __builtin_amdgcn_s_setprio(1); _Pragma("unroll") for (int m = 0; m < 4; ++m) _Pragma("unroll") for (int n = 0; n < 2; ++n) _Pragma("unroll") for (int k = 0; k < 2; ++k) \
;         acc[ai][bj][m][n] = __builtin_amdgcn_mfma_f32_16x16x32_bf16(Bt[n][k], At[m][k], acc[ai][bj][m][n], 0, 0, 0); __builtin_amdgcn_s_setprio(0); } while (0)
; #define PG8_WAIT_V(n) asm volatile("s_waitcnt vmcnt(" #n ")" ::: "memory")
; #define PG8_BAR __builtin_amdgcn_s_barrier()
; template <class Epi, class Sched, bool ALIGN_EPI = false, bool SP2 = false>
; __device__ __forceinline__ void gemm_phase(PG8_LAS unsigned char* lds, const Gemm g, const Sched& S, const Epi& E, const int tid) {
;     ...
;         for (int t = 0; t < nt; t += 2) {
;             const bool last = (t == nt - 2);
;             const char* a1 = cA + (size_t)(t + 1) * kstep;
;             const char* a2 = last ? nA : cA + (size_t)(t + 2) * kstep; const char* b2 = last ? nB : cB + (size_t)(t + 2) * kstep;
;             const char* a3 = a2 + kstep; const char* b3 = b2 + kstep;
;             if (last && has_next) S.a_ready(nxt);
;             if constexpr (SP2) {
;             PG8_LDB(B0, 0, 0); PG8_LDB(B1, 0, 1); PG8_SCHED; PG8_LDA(At, 0, 0); PG8_STAGE(PG8_SA(1, 1), a1 + hstep, voffA);
;             PG8_WAIT_V(8); PG8_WAIT_L(0); PG8_BAR; PG8_MMA(0, 0, At, B0); PG8_MMA(0, 1, At, B1); PG8_BAR; PG8_SCHED;
;             PG8_LDA(At, 0, 1); PG8_STAGE(PG8_SB(0, 0), b2, voffB); PG8_STAGE(PG8_SB(0, 1), b2 + hstep, voffB); PG8_STAGE(PG8_SA(0, 0), a2, voffA);
;             PG8_WAIT_V(8); PG8_WAIT_L(0); PG8_BAR; PG8_MMA(1, 0, At, B0); PG8_MMA(1, 1, At, B1); PG8_BAR; PG8_SCHED;
.LBB0_1121:
	s_add_u32 s5, s56, 0x100
	s_addc_u32 s49, s57, 0
	s_add_u32 s56, s58, 0x40080
	s_addc_u32 s57, s59, 0
	s_mov_b32 s51, -2
	s_add_u32 s15, s56, 0xfffc0080
	s_addc_u32 s18, s57, -1
	s_cmp_eq_u32 s51, 12
	s_cselect_b32 s61, s1, s18
	s_cselect_b32 s60, s0, s15
	s_cselect_b32 s59, s53, s49
	s_cselect_b32 s58, s52, s5
	v_lshl_add_u64 v[170:171], s[56:57], 0, v[156:157]
	s_add_i32 m0, s67, 0xc000
	global_load_lds_dwordx4 v[170:171], off
	v_lshl_add_u64 v[170:171], s[56:57], 0, v[154:155]
	s_add_i32 m0, s67, 0xe000
	s_nop 0
	global_load_lds_dwordx4 v[170:171], off
	s_waitcnt vmcnt(8)
	s_waitcnt lgkmcnt(0)
	s_barrier
	s_setprio 1
	s_waitcnt lgkmcnt(0)
	v_mfma_f32_16x16x32_bf16 v[126:129], v[130:133], v[196:199], 0
	v_mfma_f32_16x16x32_bf16 v[122:125], v[162:165], v[196:199], 0
	v_mfma_f32_16x16x32_bf16 v[110:113], v[130:133], v[204:207], 0
	v_mfma_f32_16x16x32_bf16 v[106:109], v[162:165], v[204:207], 0
	v_mfma_f32_16x16x32_bf16 v[94:97], v[130:133], v[212:215], 0
	v_mfma_f32_16x16x32_bf16 v[90:93], v[162:165], v[212:215], 0
	v_mfma_f32_16x16x32_bf16 v[78:81], v[130:133], v[220:223], 0
	v_mfma_f32_16x16x32_bf16 v[74:77], v[162:165], v[220:223], 0
	v_mfma_f32_16x16x32_bf16 v[126:129], v[134:137], v[200:203], v[126:129]
	v_mfma_f32_16x16x32_bf16 v[122:125], v[166:169], v[200:203], v[122:125]
	v_mfma_f32_16x16x32_bf16 v[110:113], v[134:137], v[208:211], v[110:113]
	v_mfma_f32_16x16x32_bf16 v[106:109], v[166:169], v[208:211], v[106:109]
	v_mfma_f32_16x16x32_bf16 v[94:97], v[134:137], v[216:219], v[94:97]
	v_mfma_f32_16x16x32_bf16 v[90:93], v[166:169], v[216:219], v[90:93]
	v_mfma_f32_16x16x32_bf16 v[78:81], v[134:137], v[224:227], v[78:81]
	v_mfma_f32_16x16x32_bf16 v[74:77], v[166:169], v[224:227], v[74:77]
	s_setprio 0
	s_setprio 1
	v_mfma_f32_16x16x32_bf16 v[118:121], v[176:179], v[196:199], 0
	v_mfma_f32_16x16x32_bf16 v[114:117], v[184:187], v[196:199], 0
	v_mfma_f32_16x16x32_bf16 v[102:105], v[176:179], v[204:207], 0
	v_mfma_f32_16x16x32_bf16 v[98:101], v[184:187], v[204:207], 0
	v_mfma_f32_16x16x32_bf16 v[86:89], v[176:179], v[212:215], 0
	v_mfma_f32_16x16x32_bf16 v[82:85], v[184:187], v[212:215], 0
	v_mfma_f32_16x16x32_bf16 v[70:73], v[176:179], v[220:223], 0
	v_mfma_f32_16x16x32_bf16 v[66:69], v[184:187], v[220:223], 0
	v_mfma_f32_16x16x32_bf16 v[118:121], v[180:183], v[200:203], v[118:121]
	v_mfma_f32_16x16x32_bf16 v[114:117], v[192:195], v[200:203], v[114:117]
	v_mfma_f32_16x16x32_bf16 v[102:105], v[180:183], v[208:211], v[102:105]
	v_mfma_f32_16x16x32_bf16 v[98:101], v[192:195], v[208:211], v[98:101]
	v_mfma_f32_16x16x32_bf16 v[86:89], v[180:183], v[216:219], v[86:89]
	v_mfma_f32_16x16x32_bf16 v[82:85], v[192:195], v[216:219], v[82:85]
	v_mfma_f32_16x16x32_bf16 v[70:73], v[180:183], v[224:227], v[70:73]
	v_mfma_f32_16x16x32_bf16 v[66:69], v[192:195], v[224:227], v[66:69]
	s_setprio 0
	s_barrier
	s_add_i32 s15, s86, s66
	v_lshl_add_u64 v[170:171], s[58:59], 0, v[142:143]
	s_mov_b32 m0, s15
	ds_read_b128 v[196:199], v174 offset:16384
	ds_read_b128 v[200:203], v174 offset:17408
	ds_read_b128 v[204:207], v174 offset:18432
	ds_read_b128 v[208:211], v174 offset:19456
	ds_read_b128 v[212:215], v174 offset:20480
	ds_read_b128 v[216:219], v174 offset:21504
	ds_read_b128 v[220:223], v174 offset:22528
	ds_read_b128 v[224:227], v174 offset:23552
	global_load_lds_dwordx4 v[170:171], off
	s_add_i32 m0, s15, 0x2000
	s_add_u32 s18, s58, 0x40000
	v_lshl_add_u64 v[188:189], s[58:59], 0, v[146:147]
	s_addc_u32 s19, s59, 0
	s_add_i32 s15, s87, s66
	global_load_lds_dwordx4 v[188:189], off
	v_lshl_add_u64 v[228:229], s[18:19], 0, v[142:143]
	s_mov_b32 m0, s15
	v_lshl_add_u64 v[230:231], s[60:61], 0, v[144:145]
	global_load_lds_dwordx4 v[228:229], off
	v_lshl_add_u64 v[228:229], s[18:19], 0, v[146:147]
	s_add_i32 m0, s15, 0x2000
	s_nop 0
	global_load_lds_dwordx4 v[228:229], off
	v_lshl_add_u64 v[228:229], s[60:61], 0, v[140:141]
	s_mov_b32 m0, s67
	s_nop 0
	global_load_lds_dwordx4 v[228:229], off
	s_mov_b32 m0, s68
	s_nop 0
	global_load_lds_dwordx4 v[230:231], off
	s_waitcnt vmcnt(8)
	s_waitcnt lgkmcnt(0)
	s_barrier
	s_setprio 1
	s_waitcnt lgkmcnt(0)
	v_mfma_f32_16x16x32_bf16 v[62:65], v[130:133], v[196:199], 0
	v_mfma_f32_16x16x32_bf16 v[58:61], v[162:165], v[196:199], 0
	v_mfma_f32_16x16x32_bf16 v[46:49], v[130:133], v[204:207], 0
	v_mfma_f32_16x16x32_bf16 v[42:45], v[162:165], v[204:207], 0
	v_mfma_f32_16x16x32_bf16 v[30:33], v[130:133], v[212:215], 0
	v_mfma_f32_16x16x32_bf16 v[26:29], v[162:165], v[212:215], 0
	v_mfma_f32_16x16x32_bf16 v[14:17], v[130:133], v[220:223], 0
	v_mfma_f32_16x16x32_bf16 v[10:13], v[162:165], v[220:223], 0
	v_mfma_f32_16x16x32_bf16 v[62:65], v[134:137], v[200:203], v[62:65]
	v_mfma_f32_16x16x32_bf16 v[58:61], v[166:169], v[200:203], v[58:61]
	v_mfma_f32_16x16x32_bf16 v[46:49], v[134:137], v[208:211], v[46:49]
	v_mfma_f32_16x16x32_bf16 v[42:45], v[166:169], v[208:211], v[42:45]
	v_mfma_f32_16x16x32_bf16 v[30:33], v[134:137], v[216:219], v[30:33]
	v_mfma_f32_16x16x32_bf16 v[26:29], v[166:169], v[216:219], v[26:29]
	v_mfma_f32_16x16x32_bf16 v[14:17], v[134:137], v[224:227], v[14:17]
	v_mfma_f32_16x16x32_bf16 v[10:13], v[166:169], v[224:227], v[10:13]
	s_setprio 0
	s_setprio 1
	v_mfma_f32_16x16x32_bf16 v[54:57], v[176:179], v[196:199], 0
	v_mfma_f32_16x16x32_bf16 v[50:53], v[184:187], v[196:199], 0
	v_mfma_f32_16x16x32_bf16 v[38:41], v[176:179], v[204:207], 0
	v_mfma_f32_16x16x32_bf16 v[34:37], v[184:187], v[204:207], 0
	v_mfma_f32_16x16x32_bf16 v[22:25], v[176:179], v[212:215], 0
	v_mfma_f32_16x16x32_bf16 v[18:21], v[184:187], v[212:215], 0
	v_mfma_f32_16x16x32_bf16 v[6:9], v[176:179], v[220:223], 0
	v_mfma_f32_16x16x32_bf16 v[2:5], v[184:187], v[220:223], 0
	v_mfma_f32_16x16x32_bf16 v[54:57], v[180:183], v[200:203], v[54:57]
	v_mfma_f32_16x16x32_bf16 v[50:53], v[192:195], v[200:203], v[50:53]
	v_mfma_f32_16x16x32_bf16 v[38:41], v[180:183], v[208:211], v[38:41]
	v_mfma_f32_16x16x32_bf16 v[34:37], v[192:195], v[208:211], v[34:37]
	v_mfma_f32_16x16x32_bf16 v[22:25], v[180:183], v[216:219], v[22:25]
	v_mfma_f32_16x16x32_bf16 v[18:21], v[192:195], v[216:219], v[18:21]
	v_mfma_f32_16x16x32_bf16 v[6:9], v[180:183], v[224:227], v[6:9]
	v_mfma_f32_16x16x32_bf16 v[2:5], v[192:195], v[224:227], v[2:5]
	s_setprio 0
	s_barrier
; #define PG8_STAGE(bufoff, gbase, voff) do { _Pragma("unroll") for (int _i = 0; _i < 2; ++_i) \
;         __builtin_amdgcn_global_load_lds((const unsigned*)((const char*)(gbase) + (voff)[_i]), (PG8_LAS unsigned*)(lds + (bufoff) + ldsw + _i * 8192), 16, 0, 0); } while (0)
; #define PG8_LDA(dst, b, h) do { _Pragma("unroll") for (int m = 0; m < 4; ++m) _Pragma("unroll") for (int k = 0; k < 2; ++k) dst[m][k] = *(const PG8_LAS bf16x8*)(lds + PG8_SA(b, h) + aoff + m * 2048 + k * 1024); } while (0)
; #define PG8_LDB(dst, b, h) do { _Pragma("unroll") for (int n = 0; n < 2; ++n) _Pragma("unroll") for (int k = 0; k < 2; ++k) dst[n][k] = *(const PG8_LAS bf16x8*)(lds + PG8_SB(b, h) + boff + n * 2048 + k * 1024); } while (0)
; #define PG8_MMA(ai, bj, At, Bt) do { __builtin_amdgcn_s_setprio(1); _Pragma("unroll") for (int m = 0; m < 4; ++m) _Pragma("unroll") for (int n = 0; n < 2; ++n) _Pragma("unroll") for (int k = 0; k < 2; ++k) \
;         acc[ai][bj][m][n] = __builtin_amdgcn_mfma_f32_16x16x32_bf16(Bt[n][k], At[m][k], acc[ai][bj][m][n], 0, 0, 0); __builtin_amdgcn_s_setprio(0); } while (0)
; #define PG8_WAIT_V(n) asm volatile("s_waitcnt vmcnt(" #n ")" ::: "memory")
; #define PG8_WAIT_L(n) asm volatile("s_waitcnt lgkmcnt(" #n ")" ::: "memory")
; #define PG8_BAR __builtin_amdgcn_s_barrier()
; #define PG8_SCHED __builtin_amdgcn_sched_barrier(0)
; template <class Epi, class Sched, bool ALIGN_EPI = false, bool SP2 = false>
; __device__ __forceinline__ void gemm_phase(PG8_LAS unsigned char* lds, const Gemm g, const Sched& S, const Epi& E, const int tid) {
;     ...
;             PG8_LDB(B0, 1, 0); PG8_LDB(B1, 1, 1); PG8_SCHED; PG8_LDA(At, 1, 0); PG8_STAGE(PG8_SA(0, 1), a2 + hstep, voffA);
;             PG8_WAIT_V(8); PG8_WAIT_L(0); PG8_BAR; PG8_MMA(0, 0, At, B0); PG8_MMA(0, 1, At, B1); PG8_BAR; PG8_SCHED;
	s_add_i32 s15, 0, 0x18000
	s_add_i32 s62, 0, 0x1c000
	v_add_u32_e32 v166, s15, v172
	v_add_u32_e32 v191, s62, v172
	ds_read_b128 v[130:133], v166
	ds_read_b128 v[134:137], v166 offset:1024
	ds_read_b128 v[162:165], v166 offset:2048
	ds_read_b128 v[166:169], v166 offset:3072
	ds_read_b128 v[176:179], v191
	ds_read_b128 v[180:183], v191 offset:1024
	ds_read_b128 v[184:187], v191 offset:2048
	ds_read_b128 v[192:195], v191 offset:3072
	s_add_u32 s18, s60, 0x40000
	s_addc_u32 s19, s61, 0
	s_mov_b32 m0, s69
	v_lshl_add_u64 v[232:233], s[18:19], 0, v[140:141]
	ds_read_b128 v[196:199], v174 offset:32768
	ds_read_b128 v[200:203], v174 offset:33792
	ds_read_b128 v[204:207], v174 offset:34816
	ds_read_b128 v[208:211], v174 offset:35840
	ds_read_b128 v[212:215], v174 offset:36864
	ds_read_b128 v[216:219], v174 offset:37888
	ds_read_b128 v[220:223], v174 offset:38912
	ds_read_b128 v[224:227], v174 offset:39936
	global_load_lds_dwordx4 v[232:233], off
	v_lshl_add_u64 v[232:233], s[18:19], 0, v[144:145]
	s_mov_b32 m0, s71
	s_nop 0
	global_load_lds_dwordx4 v[232:233], off
	s_waitcnt vmcnt(8)
	s_waitcnt lgkmcnt(0)
	s_barrier
	s_setprio 1
	s_waitcnt lgkmcnt(0)
	v_mfma_f32_16x16x32_bf16 v[126:129], v[130:133], v[196:199], v[126:129]
	v_mfma_f32_16x16x32_bf16 v[122:125], v[162:165], v[196:199], v[122:125]
	v_mfma_f32_16x16x32_bf16 v[110:113], v[130:133], v[204:207], v[110:113]
	v_mfma_f32_16x16x32_bf16 v[106:109], v[162:165], v[204:207], v[106:109]
	v_mfma_f32_16x16x32_bf16 v[94:97], v[130:133], v[212:215], v[94:97]
	v_mfma_f32_16x16x32_bf16 v[90:93], v[162:165], v[212:215], v[90:93]
	v_mfma_f32_16x16x32_bf16 v[78:81], v[130:133], v[220:223], v[78:81]
	v_mfma_f32_16x16x32_bf16 v[74:77], v[162:165], v[220:223], v[74:77]
	v_mfma_f32_16x16x32_bf16 v[126:129], v[134:137], v[200:203], v[126:129]
	v_mfma_f32_16x16x32_bf16 v[122:125], v[166:169], v[200:203], v[122:125]
	v_mfma_f32_16x16x32_bf16 v[110:113], v[134:137], v[208:211], v[110:113]
	v_mfma_f32_16x16x32_bf16 v[106:109], v[166:169], v[208:211], v[106:109]
	v_mfma_f32_16x16x32_bf16 v[94:97], v[134:137], v[216:219], v[94:97]
	v_mfma_f32_16x16x32_bf16 v[90:93], v[166:169], v[216:219], v[90:93]
	v_mfma_f32_16x16x32_bf16 v[78:81], v[134:137], v[224:227], v[78:81]
	v_mfma_f32_16x16x32_bf16 v[74:77], v[166:169], v[224:227], v[74:77]
	s_setprio 0
	s_setprio 1
	v_mfma_f32_16x16x32_bf16 v[118:121], v[176:179], v[196:199], v[118:121]
	v_mfma_f32_16x16x32_bf16 v[114:117], v[184:187], v[196:199], v[114:117]
	v_mfma_f32_16x16x32_bf16 v[102:105], v[176:179], v[204:207], v[102:105]
	v_mfma_f32_16x16x32_bf16 v[98:101], v[184:187], v[204:207], v[98:101]
	v_mfma_f32_16x16x32_bf16 v[86:89], v[176:179], v[212:215], v[86:89]
	v_mfma_f32_16x16x32_bf16 v[82:85], v[184:187], v[212:215], v[82:85]
	v_mfma_f32_16x16x32_bf16 v[70:73], v[176:179], v[220:223], v[70:73]
	v_mfma_f32_16x16x32_bf16 v[66:69], v[184:187], v[220:223], v[66:69]
	v_mfma_f32_16x16x32_bf16 v[118:121], v[180:183], v[200:203], v[118:121]
	v_mfma_f32_16x16x32_bf16 v[114:117], v[192:195], v[200:203], v[114:117]
	v_mfma_f32_16x16x32_bf16 v[102:105], v[180:183], v[208:211], v[102:105]
	v_mfma_f32_16x16x32_bf16 v[98:101], v[192:195], v[208:211], v[98:101]
	v_mfma_f32_16x16x32_bf16 v[86:89], v[180:183], v[216:219], v[86:89]
	v_mfma_f32_16x16x32_bf16 v[82:85], v[192:195], v[216:219], v[82:85]
	v_mfma_f32_16x16x32_bf16 v[70:73], v[180:183], v[224:227], v[70:73]
	v_mfma_f32_16x16x32_bf16 v[66:69], v[192:195], v[224:227], v[66:69]
	s_setprio 0
	s_barrier
; #define PG8_STAGE(bufoff, gbase, voff) do { _Pragma("unroll") for (int _i = 0; _i < 2; ++_i) \
;         __builtin_amdgcn_global_load_lds((const unsigned*)((const char*)(gbase) + (voff)[_i]), (PG8_LAS unsigned*)(lds + (bufoff) + ldsw + _i * 8192), 16, 0, 0); } while (0)
; #define PG8_LDA(dst, b, h) do { _Pragma("unroll") for (int m = 0; m < 4; ++m) _Pragma("unroll") for (int k = 0; k < 2; ++k) dst[m][k] = *(const PG8_LAS bf16x8*)(lds + PG8_SA(b, h) + aoff + m * 2048 + k * 1024); } while (0)
; #define PG8_MMA(ai, bj, At, Bt) do { __builtin_amdgcn_s_setprio(1); _Pragma("unroll") for (int m = 0; m < 4; ++m) _Pragma("unroll") for (int n = 0; n < 2; ++n) _Pragma("unroll") for (int k = 0; k < 2; ++k) \
;         acc[ai][bj][m][n] = __builtin_amdgcn_mfma_f32_16x16x32_bf16(Bt[n][k], At[m][k], acc[ai][bj][m][n], 0, 0, 0); __builtin_amdgcn_s_setprio(0); } while (0)
; #define PG8_WAIT_V(n) asm volatile("s_waitcnt vmcnt(" #n ")" ::: "memory")
; #define PG8_WAIT_L(n) asm volatile("s_waitcnt lgkmcnt(" #n ")" ::: "memory")
; #define PG8_BAR __builtin_amdgcn_s_barrier()
; #define PG8_SCHED __builtin_amdgcn_sched_barrier(0)
; template <class Epi, class Sched, bool ALIGN_EPI = false, bool SP2 = false>
; __device__ __forceinline__ void gemm_phase(PG8_LAS unsigned char* lds, const Gemm g, const Sched& S, const Epi& E, const int tid) {
;     ...
;             PG8_LDA(At, 1, 1); PG8_STAGE(PG8_SB(1, 0), b3, voffB); PG8_STAGE(PG8_SB(1, 1), b3 + hstep, voffB); PG8_STAGE(PG8_SA(1, 0), a3, voffA);
;             PG8_WAIT_V(8); PG8_WAIT_L(0); PG8_BAR; PG8_MMA(1, 0, At, B0); PG8_MMA(1, 1, At, B1); PG8_BAR; PG8_SCHED;
	s_add_i32 s15, s15, s66
	v_lshl_add_u64 v[170:171], v[170:171], 0, s[44:45]
	s_mov_b32 m0, s15
	ds_read_b128 v[196:199], v174 offset:49152
	ds_read_b128 v[200:203], v174 offset:50176
	ds_read_b128 v[204:207], v174 offset:51200
	ds_read_b128 v[208:211], v174 offset:52224
	ds_read_b128 v[212:215], v174 offset:53248
	ds_read_b128 v[216:219], v174 offset:54272
	ds_read_b128 v[220:223], v174 offset:55296
	ds_read_b128 v[224:227], v174 offset:56320
	global_load_lds_dwordx4 v[170:171], off
	s_add_i32 m0, s15, 0x2000
	s_add_u32 s18, s58, 0x40080
	v_lshl_add_u64 v[170:171], v[188:189], 0, s[44:45]
	s_addc_u32 s19, s59, 0
	s_add_i32 s15, s62, s66
	global_load_lds_dwordx4 v[170:171], off
	v_lshl_add_u64 v[170:171], s[18:19], 0, v[142:143]
	s_mov_b32 m0, s15
	s_nop 0
	global_load_lds_dwordx4 v[170:171], off
	v_lshl_add_u64 v[170:171], s[18:19], 0, v[146:147]
	s_add_i32 m0, s15, 0x2000
	s_nop 0
	global_load_lds_dwordx4 v[170:171], off
	v_lshl_add_u64 v[170:171], v[228:229], 0, s[44:45]
	s_mov_b32 m0, s77
	s_nop 0
	global_load_lds_dwordx4 v[170:171], off
	v_lshl_add_u64 v[170:171], v[230:231], 0, s[44:45]
	s_mov_b32 m0, s78
	s_nop 0
	global_load_lds_dwordx4 v[170:171], off
	s_waitcnt vmcnt(8)
	s_waitcnt lgkmcnt(0)
	s_barrier
	s_setprio 1
	s_waitcnt lgkmcnt(0)
	v_mfma_f32_16x16x32_bf16 v[62:65], v[130:133], v[196:199], v[62:65]
	v_mfma_f32_16x16x32_bf16 v[58:61], v[162:165], v[196:199], v[58:61]
	v_mfma_f32_16x16x32_bf16 v[46:49], v[130:133], v[204:207], v[46:49]
	v_mfma_f32_16x16x32_bf16 v[42:45], v[162:165], v[204:207], v[42:45]
	v_mfma_f32_16x16x32_bf16 v[30:33], v[130:133], v[212:215], v[30:33]
	v_mfma_f32_16x16x32_bf16 v[26:29], v[162:165], v[212:215], v[26:29]
	v_mfma_f32_16x16x32_bf16 v[14:17], v[130:133], v[220:223], v[14:17]
	v_mfma_f32_16x16x32_bf16 v[10:13], v[162:165], v[220:223], v[10:13]
	v_mfma_f32_16x16x32_bf16 v[62:65], v[134:137], v[200:203], v[62:65]
	v_mfma_f32_16x16x32_bf16 v[58:61], v[166:169], v[200:203], v[58:61]
	v_mfma_f32_16x16x32_bf16 v[46:49], v[134:137], v[208:211], v[46:49]
	v_mfma_f32_16x16x32_bf16 v[42:45], v[166:169], v[208:211], v[42:45]
	v_mfma_f32_16x16x32_bf16 v[30:33], v[134:137], v[216:219], v[30:33]
	v_mfma_f32_16x16x32_bf16 v[26:29], v[166:169], v[216:219], v[26:29]
	v_mfma_f32_16x16x32_bf16 v[14:17], v[134:137], v[224:227], v[14:17]
	v_mfma_f32_16x16x32_bf16 v[10:13], v[166:169], v[224:227], v[10:13]
	s_setprio 0
	s_setprio 1
	v_mfma_f32_16x16x32_bf16 v[54:57], v[176:179], v[196:199], v[54:57]
	v_mfma_f32_16x16x32_bf16 v[50:53], v[184:187], v[196:199], v[50:53]
	v_mfma_f32_16x16x32_bf16 v[38:41], v[176:179], v[204:207], v[38:41]
	v_mfma_f32_16x16x32_bf16 v[34:37], v[184:187], v[204:207], v[34:37]
	v_mfma_f32_16x16x32_bf16 v[22:25], v[176:179], v[212:215], v[22:25]
	v_mfma_f32_16x16x32_bf16 v[18:21], v[184:187], v[212:215], v[18:21]
	v_mfma_f32_16x16x32_bf16 v[6:9], v[176:179], v[220:223], v[6:9]
	v_mfma_f32_16x16x32_bf16 v[2:5], v[184:187], v[220:223], v[2:5]
	v_mfma_f32_16x16x32_bf16 v[54:57], v[180:183], v[200:203], v[54:57]
	v_mfma_f32_16x16x32_bf16 v[50:53], v[192:195], v[200:203], v[50:53]
	v_mfma_f32_16x16x32_bf16 v[38:41], v[180:183], v[208:211], v[38:41]
	v_mfma_f32_16x16x32_bf16 v[34:37], v[192:195], v[208:211], v[34:37]
	v_mfma_f32_16x16x32_bf16 v[22:25], v[180:183], v[216:219], v[22:25]
	v_mfma_f32_16x16x32_bf16 v[18:21], v[192:195], v[216:219], v[18:21]
	v_mfma_f32_16x16x32_bf16 v[6:9], v[180:183], v[224:227], v[6:9]
	v_mfma_f32_16x16x32_bf16 v[2:5], v[192:195], v[224:227], v[2:5]
	s_setprio 0
	s_barrier
	s_add_i32 s51, s51, 2
	s_add_u32 s5, s5, 0x100
	s_addc_u32 s49, s49, 0
	s_add_u32 s56, s56, 0x100
	s_addc_u32 s57, s57, 0

; #define PG8_STAGE(bufoff, gbase, voff) do { _Pragma("unroll") for (int _i = 0; _i < 2; ++_i) \
;         __builtin_amdgcn_global_load_lds((const unsigned*)((const char*)(gbase) + (voff)[_i]), (PG8_LAS unsigned*)(lds + (bufoff) + ldsw + _i * 8192), 16, 0, 0); } while (0)
; #define PG8_LDA(dst, b, h) do { _Pragma("unroll") for (int m = 0; m < 4; ++m) _Pragma("unroll") for (int k = 0; k < 2; ++k) dst[m][k] = *(const PG8_LAS bf16x8*)(lds + PG8_SA(b, h) + aoff + m * 2048 + k * 1024); } while (0)
; #define PG8_LDB(dst, b, h) do { _Pragma("unroll") for (int n = 0; n < 2; ++n) _Pragma("unroll") for (int k = 0; k < 2; ++k) dst[n][k] = *(const PG8_LAS bf16x8*)(lds + PG8_SB(b, h) + boff + n * 2048 + k * 1024); } while (0)
; #define PG8_WAIT_V(n) asm volatile("s_waitcnt vmcnt(" #n ")" ::: "memory")
; #define PG8_WAIT_L(n) asm volatile("s_waitcnt lgkmcnt(" #n ")" ::: "memory")
;     __host__ __device__ bool next(int i, Unit& u) const {
;         const long L = (long)i * G + c; if (L >= nwg) return false;
;         int wgid = (int)L; { const int q = nwg / NXCD, r = nwg % NXCD, xcd = wgid % NXCD, off = wgid / NXCD; wgid = (xcd < r ? xcd * (q + 1) : r * (q + 1) + (xcd - r) * q) + off; }
;         const int nig = WGM * nN, gid = wgid / nig, fm = gid * WGM, gsz = (nM - fm) < WGM ? (nM - fm) : WGM;
;         u.pm = fm + ((wgid % nig) % gsz); u.pn = (wgid % nig) / gsz; u.sub = 0; return true;
; template <class Epi, class Sched, bool ALIGN_EPI = false, bool SP2 = false>
; __device__ __forceinline__ void gemm_phase(PG8_LAS unsigned char* lds, const Gemm g, const Sched& S, const Epi& E, const int tid) {
;     ...
;         const char* nA = has_next ? S.aptr(nxt) : cA; const char* nB = has_next ? S.bptr(nxt) : cB;
;         for (int t = 0; t < nt; t += 2) {
;             const bool last = (t == nt - 2);
;             const char* a1 = cA + (size_t)(t + 1) * kstep;
;             const char* a2 = last ? nA : cA + (size_t)(t + 2) * kstep; const char* b2 = last ? nB : cB + (size_t)(t + 2) * kstep;
;             const char* a3 = a2 + kstep; const char* b3 = b2 + kstep;
;             if (last && has_next) S.a_ready(nxt);
;             if constexpr (SP2) {
;             PG8_LDB(B0, 0, 0); PG8_LDB(B1, 0, 1); PG8_SCHED; PG8_LDA(At, 0, 0); PG8_STAGE(PG8_SA(1, 1), a1 + hstep, voffA);
;             PG8_WAIT_V(8); PG8_WAIT_L(0); PG8_BAR; PG8_MMA(0, 0, At, B0); PG8_MMA(0, 1, At, B1); PG8_BAR; PG8_SCHED;
.LBB0_1371:
	ds_read_b128 v[130:133], v204
	ds_read_b128 v[134:137], v204 offset:1024
	ds_read_b128 v[138:141], v204 offset:2048
	ds_read_b128 v[142:145], v204 offset:3072
	ds_read_b128 v[146:149], v205
	ds_read_b128 v[150:153], v205 offset:1024
	ds_read_b128 v[154:157], v205 offset:2048
	ds_read_b128 v[158:161], v205 offset:3072
	ds_read_b128 v[182:185], v206
	ds_read_b128 v[186:189], v206 offset:1024
	ds_read_b128 v[192:195], v206 offset:2048
	ds_read_b128 v[196:199], v206 offset:3072
	ds_read_b128 v[200:203], v206 offset:4096
	ds_read_b128 v[208:211], v206 offset:5120
	ds_read_b128 v[212:215], v206 offset:6144
	ds_read_b128 v[216:219], v206 offset:7168
	s_add_i32 s75, s75, 1
	s_mul_i32 s4, s75, s64
	s_mul_hi_u32 s5, s75, s51
	s_add_i32 s5, s5, s4
	s_mul_i32 s4, s75, s51
	s_add_u32 s40, s4, s50
	s_addc_u32 s41, s5, s65
	v_cmp_gt_i64_e32 vcc, s[40:41], v[180:181]
	v_cmp_lt_i64_e64 s[4:5], s[40:41], v[178:179]
	s_cbranch_vccnz .LBB0_1373
	s_ashr_i32 s7, s40, 31
	s_lshr_b32 s7, s7, 29
	s_add_i32 s7, s40, s7
	s_ashr_i32 s15, s7, 3
	s_and_b32 s7, s7, -8
	s_sub_i32 s7, s40, s7
	s_cmp_lt_i32 s7, 0
	s_cselect_b32 s18, s66, 0x61
	s_mul_i32 s7, s18, s7
	s_add_i32 s7, s7, s15
	s_ashr_i32 s15, s7, 31
	s_lshr_b32 s15, s15, 27
	s_add_i32 s15, s7, s15
	s_ashr_i32 s18, s15, 5
	s_lshl_b32 s18, s18, 3
	s_sub_i32 s19, 0xc2, s18
	s_min_i32 s19, s19, 8
	s_abs_i32 s36, s19
	v_cvt_f32_u32_e32 v2, s36
	s_sub_i32 s38, 0, s36
	s_andn2_b32 s15, s15, 31
	s_sub_i32 s7, s7, s15
	v_rcp_iflag_f32_e32 v2, v2
	s_abs_i32 s15, s7
	s_xor_b32 s37, s7, s19
	s_ashr_i32 s37, s37, 31
	v_mul_f32_e32 v2, 0x4f7ffffe, v2
	v_cvt_u32_f32_e32 v2, v2
	s_nop 0
	v_readfirstlane_b32 s39, v2
	s_mul_i32 s38, s38, s39
	s_mul_hi_u32 s38, s39, s38
	s_add_i32 s39, s39, s38
	s_mul_hi_u32 s38, s15, s39
	s_mul_i32 s39, s38, s36
	s_sub_i32 s15, s15, s39
	s_add_i32 s40, s38, 1
	s_sub_i32 s39, s15, s36
	s_cmp_ge_u32 s15, s36
	s_cselect_b32 s38, s40, s38
	s_cselect_b32 s15, s39, s15
	s_add_i32 s39, s38, 1
	s_cmp_ge_u32 s15, s36
	s_cselect_b32 s15, s39, s38
	s_xor_b32 s15, s15, s37
	s_sub_i32 s36, s15, s37
	s_mul_i32 s15, s36, s19
	s_sub_i32 s7, s7, s15
	s_add_i32 s38, s7, s18
.LBB0_1373:
	s_ashr_i32 s39, s38, 31
	s_lshl_b64 s[18:19], s[38:39], 19
	s_add_u32 s40, s52, s18
	s_addc_u32 s41, s53, s19
	s_and_b64 s[18:19], s[4:5], exec
	s_cselect_b32 s7, s41, s11
	s_cselect_b32 s39, s40, s10
	s_ashr_i32 s37, s36, 31
	s_lshl_b64 s[18:19], s[36:37], 19
	s_add_u32 s42, s54, s18
	s_addc_u32 s43, s55, s19
	s_and_b64 s[18:19], s[4:5], exec
	s_cselect_b32 s37, s43, s9
	s_cselect_b32 s45, s42, s8
	s_add_u32 s48, s8, 0x100
	s_addc_u32 s49, s9, 0
	s_add_u32 s8, s10, 0x40080
	s_addc_u32 s9, s11, 0
	s_mov_b32 s76, -2
	s_add_u32 s10, s8, 0xfffc0080
	s_addc_u32 s11, s9, -1
	s_cmp_eq_u32 s76, 12
	s_cselect_b32 s47, s7, s11
	s_cselect_b32 s46, s39, s10
	s_cselect_b32 s11, s37, s49
	s_cselect_b32 s10, s45, s48
	v_lshl_add_u64 v[220:221], s[8:9], 0, v[176:177]
	s_add_i32 m0, s57, 0xc000
	global_load_lds_dwordx4 v[220:221], off
	v_lshl_add_u64 v[220:221], s[8:9], 0, v[174:175]
	s_add_i32 m0, s57, 0xe000
	s_nop 0
	global_load_lds_dwordx4 v[220:221], off
	s_waitcnt vmcnt(8)
	s_waitcnt lgkmcnt(0)
	s_barrier
	s_setprio 1
	s_waitcnt lgkmcnt(0)
	v_mfma_f32_16x16x32_bf16 v[126:129], v[130:133], v[182:185], 0
	v_mfma_f32_16x16x32_bf16 v[122:125], v[138:141], v[182:185], 0
	v_mfma_f32_16x16x32_bf16 v[110:113], v[130:133], v[192:195], 0
	v_mfma_f32_16x16x32_bf16 v[106:109], v[138:141], v[192:195], 0
	v_mfma_f32_16x16x32_bf16 v[94:97], v[130:133], v[200:203], 0
	v_mfma_f32_16x16x32_bf16 v[90:93], v[138:141], v[200:203], 0
	v_mfma_f32_16x16x32_bf16 v[78:81], v[130:133], v[212:215], 0
	v_mfma_f32_16x16x32_bf16 v[74:77], v[138:141], v[212:215], 0
	v_mfma_f32_16x16x32_bf16 v[126:129], v[134:137], v[186:189], v[126:129]
	v_mfma_f32_16x16x32_bf16 v[122:125], v[142:145], v[186:189], v[122:125]
	v_mfma_f32_16x16x32_bf16 v[110:113], v[134:137], v[196:199], v[110:113]
	v_mfma_f32_16x16x32_bf16 v[106:109], v[142:145], v[196:199], v[106:109]
	v_mfma_f32_16x16x32_bf16 v[94:97], v[134:137], v[208:211], v[94:97]
	v_mfma_f32_16x16x32_bf16 v[90:93], v[142:145], v[208:211], v[90:93]
	v_mfma_f32_16x16x32_bf16 v[78:81], v[134:137], v[216:219], v[78:81]
	v_mfma_f32_16x16x32_bf16 v[74:77], v[142:145], v[216:219], v[74:77]
	s_setprio 0
	s_setprio 1
	v_mfma_f32_16x16x32_bf16 v[118:121], v[146:149], v[182:185], 0
	v_mfma_f32_16x16x32_bf16 v[114:117], v[154:157], v[182:185], 0
	v_mfma_f32_16x16x32_bf16 v[102:105], v[146:149], v[192:195], 0
	v_mfma_f32_16x16x32_bf16 v[98:101], v[154:157], v[192:195], 0
	v_mfma_f32_16x16x32_bf16 v[86:89], v[146:149], v[200:203], 0
	v_mfma_f32_16x16x32_bf16 v[82:85], v[154:157], v[200:203], 0
	v_mfma_f32_16x16x32_bf16 v[70:73], v[146:149], v[212:215], 0
	v_mfma_f32_16x16x32_bf16 v[66:69], v[154:157], v[212:215], 0
	v_mfma_f32_16x16x32_bf16 v[118:121], v[150:153], v[186:189], v[118:121]
	v_mfma_f32_16x16x32_bf16 v[114:117], v[158:161], v[186:189], v[114:117]
	v_mfma_f32_16x16x32_bf16 v[102:105], v[150:153], v[196:199], v[102:105]
	v_mfma_f32_16x16x32_bf16 v[98:101], v[158:161], v[196:199], v[98:101]
	v_mfma_f32_16x16x32_bf16 v[86:89], v[150:153], v[208:211], v[86:89]
	v_mfma_f32_16x16x32_bf16 v[82:85], v[158:161], v[208:211], v[82:85]
	v_mfma_f32_16x16x32_bf16 v[70:73], v[150:153], v[216:219], v[70:73]
	v_mfma_f32_16x16x32_bf16 v[66:69], v[158:161], v[216:219], v[66:69]
	s_setprio 0
	s_barrier
; #define PG8_STAGE(bufoff, gbase, voff) do { _Pragma("unroll") for (int _i = 0; _i < 2; ++_i) \
;         __builtin_amdgcn_global_load_lds((const unsigned*)((const char*)(gbase) + (voff)[_i]), (PG8_LAS unsigned*)(lds + (bufoff) + ldsw + _i * 8192), 16, 0, 0); } while (0)
; #define PG8_LDA(dst, b, h) do { _Pragma("unroll") for (int m = 0; m < 4; ++m) _Pragma("unroll") for (int k = 0; k < 2; ++k) dst[m][k] = *(const PG8_LAS bf16x8*)(lds + PG8_SA(b, h) + aoff + m * 2048 + k * 1024); } while (0)
; #define PG8_LDB(dst, b, h) do { _Pragma("unroll") for (int n = 0; n < 2; ++n) _Pragma("unroll") for (int k = 0; k < 2; ++k) dst[n][k] = *(const PG8_LAS bf16x8*)(lds + PG8_SB(b, h) + boff + n * 2048 + k * 1024); } while (0)
; #define PG8_MMA(ai, bj, At, Bt) do { __builtin_amdgcn_s_setprio(1); _Pragma("unroll") for (int m = 0; m < 4; ++m) _Pragma("unroll") for (int n = 0; n < 2; ++n) _Pragma("unroll") for (int k = 0; k < 2; ++k) \
;         acc[ai][bj][m][n] = __builtin_amdgcn_mfma_f32_16x16x32_bf16(Bt[n][k], At[m][k], acc[ai][bj][m][n], 0, 0, 0); __builtin_amdgcn_s_setprio(0); } while (0)
; #define PG8_WAIT_V(n) asm volatile("s_waitcnt vmcnt(" #n ")" ::: "memory")
; #define PG8_WAIT_L(n) asm volatile("s_waitcnt lgkmcnt(" #n ")" ::: "memory")
; #define PG8_BAR __builtin_amdgcn_s_barrier()
; #define PG8_SCHED __builtin_amdgcn_sched_barrier(0)
; template <class Epi, class Sched, bool ALIGN_EPI = false, bool SP2 = false>
; __device__ __forceinline__ void gemm_phase(PG8_LAS unsigned char* lds, const Gemm g, const Sched& S, const Epi& E, const int tid) {
;     ...
;             PG8_LDA(At, 0, 1); PG8_STAGE(PG8_SB(0, 0), b2, voffB); PG8_STAGE(PG8_SB(0, 1), b2 + hstep, voffB); PG8_STAGE(PG8_SA(0, 0), a2, voffA);
;             PG8_WAIT_V(8); PG8_WAIT_L(0); PG8_BAR; PG8_MMA(1, 0, At, B0); PG8_MMA(1, 1, At, B1); PG8_BAR; PG8_SCHED;
;             PG8_LDB(B0, 1, 0); PG8_LDB(B1, 1, 1); PG8_SCHED; PG8_LDA(At, 1, 0); PG8_STAGE(PG8_SA(0, 1), a2 + hstep, voffA);
;             PG8_WAIT_V(8); PG8_WAIT_L(0); PG8_BAR; PG8_MMA(0, 0, At, B0); PG8_MMA(0, 1, At, B1); PG8_BAR; PG8_SCHED;
	s_add_i32 s15, s67, s56
	v_lshl_add_u64 v[220:221], s[10:11], 0, v[164:165]
	s_mov_b32 m0, s15
	ds_read_b128 v[182:185], v206 offset:16384
	ds_read_b128 v[186:189], v206 offset:17408
	ds_read_b128 v[192:195], v206 offset:18432
	ds_read_b128 v[196:199], v206 offset:19456
	ds_read_b128 v[200:203], v206 offset:20480
	ds_read_b128 v[208:211], v206 offset:21504
	ds_read_b128 v[212:215], v206 offset:22528
	ds_read_b128 v[216:219], v206 offset:23552
	global_load_lds_dwordx4 v[220:221], off
	s_add_i32 m0, s15, 0x2000
	s_add_u32 s18, s10, 0x40000
	v_lshl_add_u64 v[222:223], s[10:11], 0, v[168:169]
	s_addc_u32 s19, s11, 0
	s_add_i32 s15, s68, s56
	global_load_lds_dwordx4 v[222:223], off
	v_lshl_add_u64 v[224:225], s[18:19], 0, v[164:165]
	s_mov_b32 m0, s15
	v_lshl_add_u64 v[226:227], s[46:47], 0, v[166:167]
	global_load_lds_dwordx4 v[224:225], off
	v_lshl_add_u64 v[224:225], s[18:19], 0, v[168:169]
	s_add_i32 m0, s15, 0x2000
	s_nop 0
	global_load_lds_dwordx4 v[224:225], off
	v_lshl_add_u64 v[224:225], s[46:47], 0, v[162:163]
	s_mov_b32 m0, s57
	s_nop 0
	global_load_lds_dwordx4 v[224:225], off
	s_mov_b32 m0, s58
	s_nop 0
	global_load_lds_dwordx4 v[226:227], off
	s_waitcnt vmcnt(8)
	s_waitcnt lgkmcnt(0)
	s_barrier
	s_setprio 1
	s_waitcnt lgkmcnt(0)
	v_mfma_f32_16x16x32_bf16 v[62:65], v[130:133], v[182:185], 0
	v_mfma_f32_16x16x32_bf16 v[58:61], v[138:141], v[182:185], 0
	v_mfma_f32_16x16x32_bf16 v[46:49], v[130:133], v[192:195], 0
	v_mfma_f32_16x16x32_bf16 v[42:45], v[138:141], v[192:195], 0
	v_mfma_f32_16x16x32_bf16 v[30:33], v[130:133], v[200:203], 0
	v_mfma_f32_16x16x32_bf16 v[26:29], v[138:141], v[200:203], 0
	v_mfma_f32_16x16x32_bf16 v[14:17], v[130:133], v[212:215], 0
	v_mfma_f32_16x16x32_bf16 v[10:13], v[138:141], v[212:215], 0
	v_mfma_f32_16x16x32_bf16 v[62:65], v[134:137], v[186:189], v[62:65]
	v_mfma_f32_16x16x32_bf16 v[58:61], v[142:145], v[186:189], v[58:61]
	v_mfma_f32_16x16x32_bf16 v[46:49], v[134:137], v[196:199], v[46:49]
	v_mfma_f32_16x16x32_bf16 v[42:45], v[142:145], v[196:199], v[42:45]
	v_mfma_f32_16x16x32_bf16 v[30:33], v[134:137], v[208:211], v[30:33]
	v_mfma_f32_16x16x32_bf16 v[26:29], v[142:145], v[208:211], v[26:29]
	v_mfma_f32_16x16x32_bf16 v[14:17], v[134:137], v[216:219], v[14:17]
	v_mfma_f32_16x16x32_bf16 v[10:13], v[142:145], v[216:219], v[10:13]
	s_setprio 0
	s_setprio 1
	v_mfma_f32_16x16x32_bf16 v[54:57], v[146:149], v[182:185], 0
	v_mfma_f32_16x16x32_bf16 v[50:53], v[154:157], v[182:185], 0
	v_mfma_f32_16x16x32_bf16 v[38:41], v[146:149], v[192:195], 0
	v_mfma_f32_16x16x32_bf16 v[34:37], v[154:157], v[192:195], 0
	v_mfma_f32_16x16x32_bf16 v[22:25], v[146:149], v[200:203], 0
	v_mfma_f32_16x16x32_bf16 v[18:21], v[154:157], v[200:203], 0
	v_mfma_f32_16x16x32_bf16 v[6:9], v[146:149], v[212:215], 0
	v_mfma_f32_16x16x32_bf16 v[2:5], v[154:157], v[212:215], 0
	v_mfma_f32_16x16x32_bf16 v[54:57], v[150:153], v[186:189], v[54:57]
	v_mfma_f32_16x16x32_bf16 v[50:53], v[158:161], v[186:189], v[50:53]
	v_mfma_f32_16x16x32_bf16 v[38:41], v[150:153], v[196:199], v[38:41]
	v_mfma_f32_16x16x32_bf16 v[34:37], v[158:161], v[196:199], v[34:37]
	v_mfma_f32_16x16x32_bf16 v[22:25], v[150:153], v[208:211], v[22:25]
	v_mfma_f32_16x16x32_bf16 v[18:21], v[158:161], v[208:211], v[18:21]
	v_mfma_f32_16x16x32_bf16 v[6:9], v[150:153], v[216:219], v[6:9]
	v_mfma_f32_16x16x32_bf16 v[2:5], v[158:161], v[216:219], v[2:5]
	s_setprio 0
	s_barrier
	s_add_i32 s15, 0, 0x18000
	s_add_i32 s77, 0, 0x1c000
	v_add_u32_e32 v142, s15, v191
	v_add_u32_e32 v158, s77, v191
	ds_read_b128 v[130:133], v142
	ds_read_b128 v[134:137], v142 offset:1024
	ds_read_b128 v[138:141], v142 offset:2048
	ds_read_b128 v[142:145], v142 offset:3072
	ds_read_b128 v[146:149], v158
	ds_read_b128 v[150:153], v158 offset:1024
	ds_read_b128 v[154:157], v158 offset:2048
	ds_read_b128 v[158:161], v158 offset:3072
	s_add_u32 s18, s46, 0x40000
	s_addc_u32 s19, s47, 0
	s_mov_b32 m0, s59
	v_lshl_add_u64 v[228:229], s[18:19], 0, v[162:163]
	ds_read_b128 v[182:185], v206 offset:32768
	ds_read_b128 v[186:189], v206 offset:33792
	ds_read_b128 v[192:195], v206 offset:34816
	ds_read_b128 v[196:199], v206 offset:35840
	ds_read_b128 v[200:203], v206 offset:36864
	ds_read_b128 v[208:211], v206 offset:37888
	ds_read_b128 v[212:215], v206 offset:38912
	ds_read_b128 v[216:219], v206 offset:39936
	global_load_lds_dwordx4 v[228:229], off
	v_lshl_add_u64 v[228:229], s[18:19], 0, v[166:167]
	s_mov_b32 m0, s60
	s_nop 0
	global_load_lds_dwordx4 v[228:229], off
	s_waitcnt vmcnt(8)
	s_waitcnt lgkmcnt(0)
	s_barrier
; #define PG8_STAGE(bufoff, gbase, voff) do { _Pragma("unroll") for (int _i = 0; _i < 2; ++_i) \
;         __builtin_amdgcn_global_load_lds((const unsigned*)((const char*)(gbase) + (voff)[_i]), (PG8_LAS unsigned*)(lds + (bufoff) + ldsw + _i * 8192), 16, 0, 0); } while (0)
; #define PG8_LDA(dst, b, h) do { _Pragma("unroll") for (int m = 0; m < 4; ++m) _Pragma("unroll") for (int k = 0; k < 2; ++k) dst[m][k] = *(const PG8_LAS bf16x8*)(lds + PG8_SA(b, h) + aoff + m * 2048 + k * 1024); } while (0)
; #define PG8_MMA(ai, bj, At, Bt) do { __builtin_amdgcn_s_setprio(1); _Pragma("unroll") for (int m = 0; m < 4; ++m) _Pragma("unroll") for (int n = 0; n < 2; ++n) _Pragma("unroll") for (int k = 0; k < 2; ++k) \
;         acc[ai][bj][m][n] = __builtin_amdgcn_mfma_f32_16x16x32_bf16(Bt[n][k], At[m][k], acc[ai][bj][m][n], 0, 0, 0); __builtin_amdgcn_s_setprio(0); } while (0)
; #define PG8_WAIT_V(n) asm volatile("s_waitcnt vmcnt(" #n ")" ::: "memory")
; #define PG8_WAIT_L(n) asm volatile("s_waitcnt lgkmcnt(" #n ")" ::: "memory")
; #define PG8_BAR __builtin_amdgcn_s_barrier()
; #define PG8_SCHED __builtin_amdgcn_sched_barrier(0)
; template <class Epi, class Sched, bool ALIGN_EPI = false, bool SP2 = false>
; __device__ __forceinline__ void gemm_phase(PG8_LAS unsigned char* lds, const Gemm g, const Sched& S, const Epi& E, const int tid) {
;     ...
;             PG8_WAIT_V(8); PG8_WAIT_L(0); PG8_BAR; PG8_MMA(0, 0, At, B0); PG8_MMA(0, 1, At, B1); PG8_BAR; PG8_SCHED;
;             PG8_LDA(At, 1, 1); PG8_STAGE(PG8_SB(1, 0), b3, voffB); PG8_STAGE(PG8_SB(1, 1), b3 + hstep, voffB); PG8_STAGE(PG8_SA(1, 0), a3, voffA);
;             PG8_WAIT_V(8); PG8_WAIT_L(0); PG8_BAR; PG8_MMA(1, 0, At, B0); PG8_MMA(1, 1, At, B1); PG8_BAR; PG8_SCHED;
	s_setprio 1
	s_waitcnt lgkmcnt(0)
	v_mfma_f32_16x16x32_bf16 v[126:129], v[130:133], v[182:185], v[126:129]
	v_mfma_f32_16x16x32_bf16 v[122:125], v[138:141], v[182:185], v[122:125]
	v_mfma_f32_16x16x32_bf16 v[110:113], v[130:133], v[192:195], v[110:113]
	v_mfma_f32_16x16x32_bf16 v[106:109], v[138:141], v[192:195], v[106:109]
	v_mfma_f32_16x16x32_bf16 v[94:97], v[130:133], v[200:203], v[94:97]
	v_mfma_f32_16x16x32_bf16 v[90:93], v[138:141], v[200:203], v[90:93]
	v_mfma_f32_16x16x32_bf16 v[78:81], v[130:133], v[212:215], v[78:81]
	v_mfma_f32_16x16x32_bf16 v[74:77], v[138:141], v[212:215], v[74:77]
	v_mfma_f32_16x16x32_bf16 v[126:129], v[134:137], v[186:189], v[126:129]
	v_mfma_f32_16x16x32_bf16 v[122:125], v[142:145], v[186:189], v[122:125]
	v_mfma_f32_16x16x32_bf16 v[110:113], v[134:137], v[196:199], v[110:113]
	v_mfma_f32_16x16x32_bf16 v[106:109], v[142:145], v[196:199], v[106:109]
	v_mfma_f32_16x16x32_bf16 v[94:97], v[134:137], v[208:211], v[94:97]
	v_mfma_f32_16x16x32_bf16 v[90:93], v[142:145], v[208:211], v[90:93]
	v_mfma_f32_16x16x32_bf16 v[78:81], v[134:137], v[216:219], v[78:81]
	v_mfma_f32_16x16x32_bf16 v[74:77], v[142:145], v[216:219], v[74:77]
	s_setprio 0
	s_setprio 1
	v_mfma_f32_16x16x32_bf16 v[118:121], v[146:149], v[182:185], v[118:121]
	v_mfma_f32_16x16x32_bf16 v[114:117], v[154:157], v[182:185], v[114:117]
	v_mfma_f32_16x16x32_bf16 v[102:105], v[146:149], v[192:195], v[102:105]
	v_mfma_f32_16x16x32_bf16 v[98:101], v[154:157], v[192:195], v[98:101]
	v_mfma_f32_16x16x32_bf16 v[86:89], v[146:149], v[200:203], v[86:89]
	v_mfma_f32_16x16x32_bf16 v[82:85], v[154:157], v[200:203], v[82:85]
	v_mfma_f32_16x16x32_bf16 v[70:73], v[146:149], v[212:215], v[70:73]
	v_mfma_f32_16x16x32_bf16 v[66:69], v[154:157], v[212:215], v[66:69]
	v_mfma_f32_16x16x32_bf16 v[118:121], v[150:153], v[186:189], v[118:121]
	v_mfma_f32_16x16x32_bf16 v[114:117], v[158:161], v[186:189], v[114:117]
	v_mfma_f32_16x16x32_bf16 v[102:105], v[150:153], v[196:199], v[102:105]
	v_mfma_f32_16x16x32_bf16 v[98:101], v[158:161], v[196:199], v[98:101]
	v_mfma_f32_16x16x32_bf16 v[86:89], v[150:153], v[208:211], v[86:89]
	v_mfma_f32_16x16x32_bf16 v[82:85], v[158:161], v[208:211], v[82:85]
	v_mfma_f32_16x16x32_bf16 v[70:73], v[150:153], v[216:219], v[70:73]
	v_mfma_f32_16x16x32_bf16 v[66:69], v[158:161], v[216:219], v[66:69]
	s_setprio 0
	s_barrier
	s_add_i32 s15, s15, s56
	v_lshl_add_u64 v[220:221], v[220:221], 0, s[30:31]
	s_mov_b32 m0, s15
	ds_read_b128 v[182:185], v206 offset:49152
	ds_read_b128 v[186:189], v206 offset:50176
	ds_read_b128 v[192:195], v206 offset:51200
	ds_read_b128 v[196:199], v206 offset:52224
	ds_read_b128 v[200:203], v206 offset:53248
	ds_read_b128 v[208:211], v206 offset:54272
	ds_read_b128 v[212:215], v206 offset:55296
	ds_read_b128 v[216:219], v206 offset:56320
	global_load_lds_dwordx4 v[220:221], off
	s_add_i32 m0, s15, 0x2000
	s_add_u32 s10, s10, 0x40080
	v_lshl_add_u64 v[220:221], v[222:223], 0, s[30:31]
	s_addc_u32 s11, s11, 0
	s_add_i32 s15, s77, s56
	global_load_lds_dwordx4 v[220:221], off
	v_lshl_add_u64 v[220:221], s[10:11], 0, v[164:165]
	s_mov_b32 m0, s15
	s_nop 0
	global_load_lds_dwordx4 v[220:221], off
	v_lshl_add_u64 v[220:221], s[10:11], 0, v[168:169]
	s_add_i32 m0, s15, 0x2000
	s_nop 0
	global_load_lds_dwordx4 v[220:221], off
	v_lshl_add_u64 v[220:221], v[224:225], 0, s[30:31]
	s_mov_b32 m0, s62
	s_nop 0
	global_load_lds_dwordx4 v[220:221], off
	v_lshl_add_u64 v[220:221], v[226:227], 0, s[30:31]
	s_mov_b32 m0, s63
	s_nop 0
	global_load_lds_dwordx4 v[220:221], off
	s_waitcnt vmcnt(8)
	s_waitcnt lgkmcnt(0)
	s_barrier
	s_setprio 1
	s_waitcnt lgkmcnt(0)
	v_mfma_f32_16x16x32_bf16 v[62:65], v[130:133], v[182:185], v[62:65]
	v_mfma_f32_16x16x32_bf16 v[58:61], v[138:141], v[182:185], v[58:61]
	v_mfma_f32_16x16x32_bf16 v[46:49], v[130:133], v[192:195], v[46:49]
	v_mfma_f32_16x16x32_bf16 v[42:45], v[138:141], v[192:195], v[42:45]
	v_mfma_f32_16x16x32_bf16 v[30:33], v[130:133], v[200:203], v[30:33]
	v_mfma_f32_16x16x32_bf16 v[26:29], v[138:141], v[200:203], v[26:29]
	v_mfma_f32_16x16x32_bf16 v[14:17], v[130:133], v[212:215], v[14:17]
	v_mfma_f32_16x16x32_bf16 v[10:13], v[138:141], v[212:215], v[10:13]
	v_mfma_f32_16x16x32_bf16 v[62:65], v[134:137], v[186:189], v[62:65]
	v_mfma_f32_16x16x32_bf16 v[58:61], v[142:145], v[186:189], v[58:61]
	v_mfma_f32_16x16x32_bf16 v[46:49], v[134:137], v[196:199], v[46:49]
	v_mfma_f32_16x16x32_bf16 v[42:45], v[142:145], v[196:199], v[42:45]
	v_mfma_f32_16x16x32_bf16 v[30:33], v[134:137], v[208:211], v[30:33]
	v_mfma_f32_16x16x32_bf16 v[26:29], v[142:145], v[208:211], v[26:29]
	v_mfma_f32_16x16x32_bf16 v[14:17], v[134:137], v[216:219], v[14:17]
	v_mfma_f32_16x16x32_bf16 v[10:13], v[142:145], v[216:219], v[10:13]
	s_setprio 0
	s_setprio 1
	v_mfma_f32_16x16x32_bf16 v[54:57], v[146:149], v[182:185], v[54:57]
	v_mfma_f32_16x16x32_bf16 v[50:53], v[154:157], v[182:185], v[50:53]
	v_mfma_f32_16x16x32_bf16 v[38:41], v[146:149], v[192:195], v[38:41]
	v_mfma_f32_16x16x32_bf16 v[34:37], v[154:157], v[192:195], v[34:37]
	v_mfma_f32_16x16x32_bf16 v[22:25], v[146:149], v[200:203], v[22:25]
	v_mfma_f32_16x16x32_bf16 v[18:21], v[154:157], v[200:203], v[18:21]
	v_mfma_f32_16x16x32_bf16 v[6:9], v[146:149], v[212:215], v[6:9]
	v_mfma_f32_16x16x32_bf16 v[2:5], v[154:157], v[212:215], v[2:5]
	v_mfma_f32_16x16x32_bf16 v[54:57], v[150:153], v[186:189], v[54:57]
	v_mfma_f32_16x16x32_bf16 v[50:53], v[158:161], v[186:189], v[50:53]
	v_mfma_f32_16x16x32_bf16 v[38:41], v[150:153], v[196:199], v[38:41]
	v_mfma_f32_16x16x32_bf16 v[34:37], v[158:161], v[196:199], v[34:37]
	v_mfma_f32_16x16x32_bf16 v[22:25], v[150:153], v[208:211], v[22:25]
	v_mfma_f32_16x16x32_bf16 v[18:21], v[158:161], v[208:211], v[18:21]
	v_mfma_f32_16x16x32_bf16 v[6:9], v[150:153], v[216:219], v[6:9]
	v_mfma_f32_16x16x32_bf16 v[2:5], v[158:161], v[216:219], v[2:5]
	s_setprio 0
	s_barrier
	s_add_i32 s76, s76, 2
	s_add_u32 s48, s48, 0x100
	s_addc_u32 s49, s49, 0
	s_add_u32 s8, s8, 0x100
	s_addc_u32 s9, s9, 0

; #define PG8_STAGE(bufoff, gbase, voff) do { _Pragma("unroll") for (int _i = 0; _i < 2; ++_i) \
;         __builtin_amdgcn_global_load_lds((const unsigned*)((const char*)(gbase) + (voff)[_i]), (PG8_LAS unsigned*)(lds + (bufoff) + ldsw + _i * 8192), 16, 0, 0); } while (0)
; #define PG8_LDA(dst, b, h) do { _Pragma("unroll") for (int m = 0; m < 4; ++m) _Pragma("unroll") for (int k = 0; k < 2; ++k) dst[m][k] = *(const PG8_LAS bf16x8*)(lds + PG8_SA(b, h) + aoff + m * 2048 + k * 1024); } while (0)
; #define PG8_LDB(dst, b, h) do { _Pragma("unroll") for (int n = 0; n < 2; ++n) _Pragma("unroll") for (int k = 0; k < 2; ++k) dst[n][k] = *(const PG8_LAS bf16x8*)(lds + PG8_SB(b, h) + boff + n * 2048 + k * 1024); } while (0)
; #define PG8_SCHED __builtin_amdgcn_sched_barrier(0)
;     __host__ __device__ bool next(int i, Unit& u) const {
;         const long L = (long)i * G + c; if (L >= nwg) return false;
;         int wgid = (int)L; { const int q = nwg / NXCD, r = nwg % NXCD, xcd = wgid % NXCD, off = wgid / NXCD; wgid = (xcd < r ? xcd * (q + 1) : r * (q + 1) + (xcd - r) * q) + off; }
;         const int nig = WGM * nN, gid = wgid / nig, fm = gid * WGM, gsz = (nM - fm) < WGM ? (nM - fm) : WGM;
;         u.pm = fm + ((wgid % nig) % gsz); u.pn = (wgid % nig) / gsz; u.sub = 0; return true;
; template <class Epi, class Sched, bool ALIGN_EPI = false, bool SP2 = false>
; __device__ __forceinline__ void gemm_phase(PG8_LAS unsigned char* lds, const Gemm g, const Sched& S, const Epi& E, const int tid) {
;     ...
;             PG8_LDB(B0, 0, 0); PG8_LDB(B1, 0, 1); PG8_SCHED; PG8_LDA(At, 0, 0); PG8_STAGE(PG8_SA(1, 1), a1 + hstep, voffA);
.LBB0_5213:
	ds_read_b128 v[130:133], v204
	ds_read_b128 v[134:137], v204 offset:1024
	ds_read_b128 v[138:141], v204 offset:2048
	ds_read_b128 v[142:145], v204 offset:3072
	ds_read_b128 v[146:149], v205
	ds_read_b128 v[150:153], v205 offset:1024
	ds_read_b128 v[154:157], v205 offset:2048
	ds_read_b128 v[158:161], v205 offset:3072
	ds_read_b128 v[182:185], v206
	ds_read_b128 v[186:189], v206 offset:1024
	ds_read_b128 v[192:195], v206 offset:2048
	ds_read_b128 v[196:199], v206 offset:3072
	ds_read_b128 v[200:203], v206 offset:4096
	ds_read_b128 v[208:211], v206 offset:5120
	ds_read_b128 v[212:215], v206 offset:6144
	ds_read_b128 v[216:219], v206 offset:7168
	s_add_i32 s71, s71, 1
	s_mul_i32 s0, s71, s60
	s_mul_hi_u32 s1, s71, s47
	s_add_i32 s1, s1, s0
	s_mul_i32 s0, s71, s47
	s_add_u32 s4, s0, s46
	s_addc_u32 s5, s1, s61
	v_cmp_gt_i64_e32 vcc, s[4:5], v[180:181]
	v_cmp_lt_i64_e64 s[0:1], s[4:5], v[178:179]
	s_cbranch_vccnz .LBB0_5215
	s_ashr_i32 s5, s4, 31
	s_lshr_b32 s5, s5, 29
	s_add_i32 s5, s4, s5
	s_ashr_i32 s10, s5, 3
	s_and_b32 s5, s5, -8
	s_sub_i32 s4, s4, s5
	s_cmp_lt_i32 s4, 0
	s_cselect_b32 s5, s62, 0x61
	s_mul_i32 s4, s5, s4
	s_add_i32 s4, s4, s10
	s_ashr_i32 s5, s4, 31
	s_lshr_b32 s5, s5, 27
	s_add_i32 s5, s4, s5
	s_ashr_i32 s10, s5, 5
	s_lshl_b32 s10, s10, 3
	s_sub_i32 s11, 0xc2, s10
	s_min_i32 s11, s11, 8
	s_abs_i32 s15, s11
	v_cvt_f32_u32_e32 v2, s15
	s_sub_i32 s19, 0, s15
	s_andn2_b32 s5, s5, 31
	s_sub_i32 s4, s4, s5
	v_rcp_iflag_f32_e32 v2, v2
	s_abs_i32 s5, s4
	s_xor_b32 s18, s4, s11
	s_ashr_i32 s18, s18, 31
	v_mul_f32_e32 v2, 0x4f7ffffe, v2
	v_cvt_u32_f32_e32 v2, v2
	s_nop 0
	v_readfirstlane_b32 s38, v2
	s_mul_i32 s19, s19, s38
	s_mul_hi_u32 s19, s38, s19
	s_add_i32 s38, s38, s19
	s_mul_hi_u32 s19, s5, s38
	s_mul_i32 s38, s19, s15
	s_sub_i32 s5, s5, s38
	s_add_i32 s39, s19, 1
	s_sub_i32 s38, s5, s15
	s_cmp_ge_u32 s5, s15
	s_cselect_b32 s19, s39, s19
	s_cselect_b32 s5, s38, s5
	s_add_i32 s38, s19, 1
	s_cmp_ge_u32 s5, s15
	s_cselect_b32 s5, s38, s19
	s_xor_b32 s5, s5, s18
	s_sub_i32 s72, s5, s18
	s_mul_i32 s5, s72, s11
	s_sub_i32 s4, s4, s5
	s_add_i32 s73, s4, s10

; #define PG8_STAGE(bufoff, gbase, voff) do { _Pragma("unroll") for (int _i = 0; _i < 2; ++_i) \
;         __builtin_amdgcn_global_load_lds((const unsigned*)((const char*)(gbase) + (voff)[_i]), (PG8_LAS unsigned*)(lds + (bufoff) + ldsw + _i * 8192), 16, 0, 0); } while (0)
; #define PG8_LDA(dst, b, h) do { _Pragma("unroll") for (int m = 0; m < 4; ++m) _Pragma("unroll") for (int k = 0; k < 2; ++k) dst[m][k] = *(const PG8_LAS bf16x8*)(lds + PG8_SA(b, h) + aoff + m * 2048 + k * 1024); } while (0)
; #define PG8_LDB(dst, b, h) do { _Pragma("unroll") for (int n = 0; n < 2; ++n) _Pragma("unroll") for (int k = 0; k < 2; ++k) dst[n][k] = *(const PG8_LAS bf16x8*)(lds + PG8_SB(b, h) + boff + n * 2048 + k * 1024); } while (0)
; #define PG8_MMA(ai, bj, At, Bt) do { __builtin_amdgcn_s_setprio(1); _Pragma("unroll") for (int m = 0; m < 4; ++m) _Pragma("unroll") for (int n = 0; n < 2; ++n) _Pragma("unroll") for (int k = 0; k < 2; ++k) \
;         acc[ai][bj][m][n] = __builtin_amdgcn_mfma_f32_16x16x32_bf16(Bt[n][k], At[m][k], acc[ai][bj][m][n], 0, 0, 0); __builtin_amdgcn_s_setprio(0); } while (0)
; #define PG8_WAIT_V(n) asm volatile("s_waitcnt vmcnt(" #n ")" ::: "memory")
; #define PG8_BAR __builtin_amdgcn_s_barrier()
; template <class Epi, class Sched, bool ALIGN_EPI = false, bool SP2 = false>
; __device__ __forceinline__ void gemm_phase(PG8_LAS unsigned char* lds, const Gemm g, const Sched& S, const Epi& E, const int tid) {
;     ...
;         for (int t = 0; t < nt; t += 2) {
;             const bool last = (t == nt - 2);
;             const char* a1 = cA + (size_t)(t + 1) * kstep;
;             const char* a2 = last ? nA : cA + (size_t)(t + 2) * kstep; const char* b2 = last ? nB : cB + (size_t)(t + 2) * kstep;
;             const char* a3 = a2 + kstep; const char* b3 = b2 + kstep;
;             if (last && has_next) S.a_ready(nxt);
;             if constexpr (SP2) {
;             PG8_LDB(B0, 0, 0); PG8_LDB(B1, 0, 1); PG8_SCHED; PG8_LDA(At, 0, 0); PG8_STAGE(PG8_SA(1, 1), a1 + hstep, voffA);
;             PG8_WAIT_V(8); PG8_WAIT_L(0); PG8_BAR; PG8_MMA(0, 0, At, B0); PG8_MMA(0, 1, At, B1); PG8_BAR; PG8_SCHED;
;             PG8_LDA(At, 0, 1); PG8_STAGE(PG8_SB(0, 0), b2, voffB); PG8_STAGE(PG8_SB(0, 1), b2 + hstep, voffB); PG8_STAGE(PG8_SA(0, 0), a2, voffA);
;             PG8_WAIT_V(8); PG8_WAIT_L(0); PG8_BAR; PG8_MMA(1, 0, At, B0); PG8_MMA(1, 1, At, B1); PG8_BAR; PG8_SCHED;
.LBB0_5219:
	s_add_u32 s43, s8, 0x100
	s_addc_u32 s45, s9, 0
	s_mov_b32 s74, -2
	s_add_u32 s8, s6, 0x100
	s_addc_u32 s9, s7, 0
	s_cmp_eq_u32 s74, 40
	s_cselect_b32 s41, s1, s9
	s_cselect_b32 s40, s0, s8
	s_cselect_b32 s11, s39, s45
	s_cselect_b32 s10, s38, s43
	v_lshl_add_u64 v[220:221], s[6:7], 0, v[176:177]
	s_add_i32 m0, s53, 0xc000
	global_load_lds_dwordx4 v[220:221], off
	v_lshl_add_u64 v[220:221], s[6:7], 0, v[174:175]
	s_add_i32 m0, s53, 0xe000
	s_nop 0
	global_load_lds_dwordx4 v[220:221], off
	s_waitcnt vmcnt(8)
	s_waitcnt lgkmcnt(0)
	s_barrier
	s_setprio 1
	s_waitcnt lgkmcnt(0)
	v_mfma_f32_16x16x32_bf16 v[126:129], v[130:133], v[182:185], 0
	v_mfma_f32_16x16x32_bf16 v[122:125], v[138:141], v[182:185], 0
	v_mfma_f32_16x16x32_bf16 v[110:113], v[130:133], v[192:195], 0
	v_mfma_f32_16x16x32_bf16 v[106:109], v[138:141], v[192:195], 0
	v_mfma_f32_16x16x32_bf16 v[94:97], v[130:133], v[200:203], 0
	v_mfma_f32_16x16x32_bf16 v[90:93], v[138:141], v[200:203], 0
	v_mfma_f32_16x16x32_bf16 v[78:81], v[130:133], v[212:215], 0
	v_mfma_f32_16x16x32_bf16 v[74:77], v[138:141], v[212:215], 0
	v_mfma_f32_16x16x32_bf16 v[126:129], v[134:137], v[186:189], v[126:129]
	v_mfma_f32_16x16x32_bf16 v[122:125], v[142:145], v[186:189], v[122:125]
	v_mfma_f32_16x16x32_bf16 v[110:113], v[134:137], v[196:199], v[110:113]
	v_mfma_f32_16x16x32_bf16 v[106:109], v[142:145], v[196:199], v[106:109]
	v_mfma_f32_16x16x32_bf16 v[94:97], v[134:137], v[208:211], v[94:97]
	v_mfma_f32_16x16x32_bf16 v[90:93], v[142:145], v[208:211], v[90:93]
	v_mfma_f32_16x16x32_bf16 v[78:81], v[134:137], v[216:219], v[78:81]
	v_mfma_f32_16x16x32_bf16 v[74:77], v[142:145], v[216:219], v[74:77]
	s_setprio 0
	s_setprio 1
	v_mfma_f32_16x16x32_bf16 v[118:121], v[146:149], v[182:185], 0
	v_mfma_f32_16x16x32_bf16 v[114:117], v[154:157], v[182:185], 0
	v_mfma_f32_16x16x32_bf16 v[102:105], v[146:149], v[192:195], 0
	v_mfma_f32_16x16x32_bf16 v[98:101], v[154:157], v[192:195], 0
	v_mfma_f32_16x16x32_bf16 v[86:89], v[146:149], v[200:203], 0
	v_mfma_f32_16x16x32_bf16 v[82:85], v[154:157], v[200:203], 0
	v_mfma_f32_16x16x32_bf16 v[70:73], v[146:149], v[212:215], 0
	v_mfma_f32_16x16x32_bf16 v[66:69], v[154:157], v[212:215], 0
	v_mfma_f32_16x16x32_bf16 v[118:121], v[150:153], v[186:189], v[118:121]
	v_mfma_f32_16x16x32_bf16 v[114:117], v[158:161], v[186:189], v[114:117]
	v_mfma_f32_16x16x32_bf16 v[102:105], v[150:153], v[196:199], v[102:105]
	v_mfma_f32_16x16x32_bf16 v[98:101], v[158:161], v[196:199], v[98:101]
	v_mfma_f32_16x16x32_bf16 v[86:89], v[150:153], v[208:211], v[86:89]
	v_mfma_f32_16x16x32_bf16 v[82:85], v[158:161], v[208:211], v[82:85]
	v_mfma_f32_16x16x32_bf16 v[70:73], v[150:153], v[216:219], v[70:73]
	v_mfma_f32_16x16x32_bf16 v[66:69], v[158:161], v[216:219], v[66:69]
	s_setprio 0
	s_barrier
	s_add_i32 s6, s63, s52
	v_lshl_add_u64 v[220:221], s[10:11], 0, v[164:165]
	s_mov_b32 m0, s6
	ds_read_b128 v[182:185], v206 offset:16384
	ds_read_b128 v[186:189], v206 offset:17408
	ds_read_b128 v[192:195], v206 offset:18432
	ds_read_b128 v[196:199], v206 offset:19456
	ds_read_b128 v[200:203], v206 offset:20480
	ds_read_b128 v[208:211], v206 offset:21504
	ds_read_b128 v[212:215], v206 offset:22528
	ds_read_b128 v[216:219], v206 offset:23552
	global_load_lds_dwordx4 v[220:221], off
	s_add_i32 m0, s6, 0x2000
	s_add_u32 s6, s10, 0xb0000
	v_lshl_add_u64 v[222:223], s[10:11], 0, v[168:169]
	s_addc_u32 s7, s11, 0
	s_add_i32 s15, s64, s52
	global_load_lds_dwordx4 v[222:223], off
	v_lshl_add_u64 v[224:225], s[6:7], 0, v[164:165]
	s_mov_b32 m0, s15
	v_lshl_add_u64 v[226:227], s[40:41], 0, v[166:167]
	global_load_lds_dwordx4 v[224:225], off
	v_lshl_add_u64 v[224:225], s[6:7], 0, v[168:169]
	s_add_i32 m0, s15, 0x2000
	s_nop 0
	global_load_lds_dwordx4 v[224:225], off
	v_lshl_add_u64 v[224:225], s[40:41], 0, v[162:163]
	s_mov_b32 m0, s53
	s_nop 0
	global_load_lds_dwordx4 v[224:225], off
	s_mov_b32 m0, s54
	s_nop 0
	global_load_lds_dwordx4 v[226:227], off
	s_waitcnt vmcnt(8)
	s_waitcnt lgkmcnt(0)
	s_barrier
	s_setprio 1
	s_waitcnt lgkmcnt(0)
	v_mfma_f32_16x16x32_bf16 v[62:65], v[130:133], v[182:185], 0
	v_mfma_f32_16x16x32_bf16 v[58:61], v[138:141], v[182:185], 0
	v_mfma_f32_16x16x32_bf16 v[46:49], v[130:133], v[192:195], 0
	v_mfma_f32_16x16x32_bf16 v[42:45], v[138:141], v[192:195], 0
	v_mfma_f32_16x16x32_bf16 v[30:33], v[130:133], v[200:203], 0
	v_mfma_f32_16x16x32_bf16 v[26:29], v[138:141], v[200:203], 0
	v_mfma_f32_16x16x32_bf16 v[14:17], v[130:133], v[212:215], 0
	v_mfma_f32_16x16x32_bf16 v[10:13], v[138:141], v[212:215], 0
	v_mfma_f32_16x16x32_bf16 v[62:65], v[134:137], v[186:189], v[62:65]
	v_mfma_f32_16x16x32_bf16 v[58:61], v[142:145], v[186:189], v[58:61]
	v_mfma_f32_16x16x32_bf16 v[46:49], v[134:137], v[196:199], v[46:49]
	v_mfma_f32_16x16x32_bf16 v[42:45], v[142:145], v[196:199], v[42:45]
	v_mfma_f32_16x16x32_bf16 v[30:33], v[134:137], v[208:211], v[30:33]
	v_mfma_f32_16x16x32_bf16 v[26:29], v[142:145], v[208:211], v[26:29]
	v_mfma_f32_16x16x32_bf16 v[14:17], v[134:137], v[216:219], v[14:17]
	v_mfma_f32_16x16x32_bf16 v[10:13], v[142:145], v[216:219], v[10:13]
	s_setprio 0
	s_setprio 1
	v_mfma_f32_16x16x32_bf16 v[54:57], v[146:149], v[182:185], 0
	v_mfma_f32_16x16x32_bf16 v[50:53], v[154:157], v[182:185], 0
	v_mfma_f32_16x16x32_bf16 v[38:41], v[146:149], v[192:195], 0
	v_mfma_f32_16x16x32_bf16 v[34:37], v[154:157], v[192:195], 0
	v_mfma_f32_16x16x32_bf16 v[22:25], v[146:149], v[200:203], 0
	v_mfma_f32_16x16x32_bf16 v[18:21], v[154:157], v[200:203], 0
	v_mfma_f32_16x16x32_bf16 v[6:9], v[146:149], v[212:215], 0
	v_mfma_f32_16x16x32_bf16 v[2:5], v[154:157], v[212:215], 0
	v_mfma_f32_16x16x32_bf16 v[54:57], v[150:153], v[186:189], v[54:57]
	v_mfma_f32_16x16x32_bf16 v[50:53], v[158:161], v[186:189], v[50:53]
	v_mfma_f32_16x16x32_bf16 v[38:41], v[150:153], v[196:199], v[38:41]
	v_mfma_f32_16x16x32_bf16 v[34:37], v[158:161], v[196:199], v[34:37]
	v_mfma_f32_16x16x32_bf16 v[22:25], v[150:153], v[208:211], v[22:25]
	v_mfma_f32_16x16x32_bf16 v[18:21], v[158:161], v[208:211], v[18:21]
	v_mfma_f32_16x16x32_bf16 v[6:9], v[150:153], v[216:219], v[6:9]
	v_mfma_f32_16x16x32_bf16 v[2:5], v[158:161], v[216:219], v[2:5]
	s_setprio 0
	s_barrier
; #define PG8_STAGE(bufoff, gbase, voff) do { _Pragma("unroll") for (int _i = 0; _i < 2; ++_i) \
;         __builtin_amdgcn_global_load_lds((const unsigned*)((const char*)(gbase) + (voff)[_i]), (PG8_LAS unsigned*)(lds + (bufoff) + ldsw + _i * 8192), 16, 0, 0); } while (0)
; #define PG8_LDA(dst, b, h) do { _Pragma("unroll") for (int m = 0; m < 4; ++m) _Pragma("unroll") for (int k = 0; k < 2; ++k) dst[m][k] = *(const PG8_LAS bf16x8*)(lds + PG8_SA(b, h) + aoff + m * 2048 + k * 1024); } while (0)
; #define PG8_LDB(dst, b, h) do { _Pragma("unroll") for (int n = 0; n < 2; ++n) _Pragma("unroll") for (int k = 0; k < 2; ++k) dst[n][k] = *(const PG8_LAS bf16x8*)(lds + PG8_SB(b, h) + boff + n * 2048 + k * 1024); } while (0)
; #define PG8_MMA(ai, bj, At, Bt) do { __builtin_amdgcn_s_setprio(1); _Pragma("unroll") for (int m = 0; m < 4; ++m) _Pragma("unroll") for (int n = 0; n < 2; ++n) _Pragma("unroll") for (int k = 0; k < 2; ++k) \
;         acc[ai][bj][m][n] = __builtin_amdgcn_mfma_f32_16x16x32_bf16(Bt[n][k], At[m][k], acc[ai][bj][m][n], 0, 0, 0); __builtin_amdgcn_s_setprio(0); } while (0)
; #define PG8_WAIT_V(n) asm volatile("s_waitcnt vmcnt(" #n ")" ::: "memory")
; #define PG8_WAIT_L(n) asm volatile("s_waitcnt lgkmcnt(" #n ")" ::: "memory")
; #define PG8_BAR __builtin_amdgcn_s_barrier()
; #define PG8_SCHED __builtin_amdgcn_sched_barrier(0)
; template <class Epi, class Sched, bool ALIGN_EPI = false, bool SP2 = false>
; __device__ __forceinline__ void gemm_phase(PG8_LAS unsigned char* lds, const Gemm g, const Sched& S, const Epi& E, const int tid) {
;     ...
;             PG8_LDB(B0, 1, 0); PG8_LDB(B1, 1, 1); PG8_SCHED; PG8_LDA(At, 1, 0); PG8_STAGE(PG8_SA(0, 1), a2 + hstep, voffA);
;             PG8_WAIT_V(8); PG8_WAIT_L(0); PG8_BAR; PG8_MMA(0, 0, At, B0); PG8_MMA(0, 1, At, B1); PG8_BAR; PG8_SCHED;
	s_add_i32 s15, 0, 0x18000
	s_add_i32 s18, 0, 0x1c000
	v_add_u32_e32 v142, s15, v191
	v_add_u32_e32 v158, s18, v191
	ds_read_b128 v[130:133], v142
	ds_read_b128 v[134:137], v142 offset:1024
	ds_read_b128 v[138:141], v142 offset:2048
	ds_read_b128 v[142:145], v142 offset:3072
	ds_read_b128 v[146:149], v158
	ds_read_b128 v[150:153], v158 offset:1024
	ds_read_b128 v[154:157], v158 offset:2048
	ds_read_b128 v[158:161], v158 offset:3072
	s_add_u32 s6, s40, 0xb0000
	s_addc_u32 s7, s41, 0
	s_mov_b32 m0, s55
	v_lshl_add_u64 v[228:229], s[6:7], 0, v[162:163]
	ds_read_b128 v[182:185], v206 offset:32768
	ds_read_b128 v[186:189], v206 offset:33792
	ds_read_b128 v[192:195], v206 offset:34816
	ds_read_b128 v[196:199], v206 offset:35840
	ds_read_b128 v[200:203], v206 offset:36864
	ds_read_b128 v[208:211], v206 offset:37888
	ds_read_b128 v[212:215], v206 offset:38912
	ds_read_b128 v[216:219], v206 offset:39936
	global_load_lds_dwordx4 v[228:229], off
	v_lshl_add_u64 v[228:229], s[6:7], 0, v[166:167]
	s_mov_b32 m0, s56
	s_nop 0
	global_load_lds_dwordx4 v[228:229], off
	s_waitcnt vmcnt(8)
	s_waitcnt lgkmcnt(0)
	s_barrier
	s_setprio 1
	s_waitcnt lgkmcnt(0)
	v_mfma_f32_16x16x32_bf16 v[126:129], v[130:133], v[182:185], v[126:129]
	v_mfma_f32_16x16x32_bf16 v[122:125], v[138:141], v[182:185], v[122:125]
	v_mfma_f32_16x16x32_bf16 v[110:113], v[130:133], v[192:195], v[110:113]
	v_mfma_f32_16x16x32_bf16 v[106:109], v[138:141], v[192:195], v[106:109]
	v_mfma_f32_16x16x32_bf16 v[94:97], v[130:133], v[200:203], v[94:97]
	v_mfma_f32_16x16x32_bf16 v[90:93], v[138:141], v[200:203], v[90:93]
	v_mfma_f32_16x16x32_bf16 v[78:81], v[130:133], v[212:215], v[78:81]
	v_mfma_f32_16x16x32_bf16 v[74:77], v[138:141], v[212:215], v[74:77]
	v_mfma_f32_16x16x32_bf16 v[126:129], v[134:137], v[186:189], v[126:129]
	v_mfma_f32_16x16x32_bf16 v[122:125], v[142:145], v[186:189], v[122:125]
	v_mfma_f32_16x16x32_bf16 v[110:113], v[134:137], v[196:199], v[110:113]
	v_mfma_f32_16x16x32_bf16 v[106:109], v[142:145], v[196:199], v[106:109]
	v_mfma_f32_16x16x32_bf16 v[94:97], v[134:137], v[208:211], v[94:97]
	v_mfma_f32_16x16x32_bf16 v[90:93], v[142:145], v[208:211], v[90:93]
	v_mfma_f32_16x16x32_bf16 v[78:81], v[134:137], v[216:219], v[78:81]
	v_mfma_f32_16x16x32_bf16 v[74:77], v[142:145], v[216:219], v[74:77]
	s_setprio 0
	s_setprio 1
	v_mfma_f32_16x16x32_bf16 v[118:121], v[146:149], v[182:185], v[118:121]
	v_mfma_f32_16x16x32_bf16 v[114:117], v[154:157], v[182:185], v[114:117]
	v_mfma_f32_16x16x32_bf16 v[102:105], v[146:149], v[192:195], v[102:105]
	v_mfma_f32_16x16x32_bf16 v[98:101], v[154:157], v[192:195], v[98:101]
	v_mfma_f32_16x16x32_bf16 v[86:89], v[146:149], v[200:203], v[86:89]
	v_mfma_f32_16x16x32_bf16 v[82:85], v[154:157], v[200:203], v[82:85]
	v_mfma_f32_16x16x32_bf16 v[70:73], v[146:149], v[212:215], v[70:73]
	v_mfma_f32_16x16x32_bf16 v[66:69], v[154:157], v[212:215], v[66:69]
	v_mfma_f32_16x16x32_bf16 v[118:121], v[150:153], v[186:189], v[118:121]
	v_mfma_f32_16x16x32_bf16 v[114:117], v[158:161], v[186:189], v[114:117]
	v_mfma_f32_16x16x32_bf16 v[102:105], v[150:153], v[196:199], v[102:105]
	v_mfma_f32_16x16x32_bf16 v[98:101], v[158:161], v[196:199], v[98:101]
	v_mfma_f32_16x16x32_bf16 v[86:89], v[150:153], v[208:211], v[86:89]
	v_mfma_f32_16x16x32_bf16 v[82:85], v[158:161], v[208:211], v[82:85]
	v_mfma_f32_16x16x32_bf16 v[70:73], v[150:153], v[216:219], v[70:73]
	v_mfma_f32_16x16x32_bf16 v[66:69], v[158:161], v[216:219], v[66:69]
	s_setprio 0
	s_barrier
; #define PG8_STAGE(bufoff, gbase, voff) do { _Pragma("unroll") for (int _i = 0; _i < 2; ++_i) \
;         __builtin_amdgcn_global_load_lds((const unsigned*)((const char*)(gbase) + (voff)[_i]), (PG8_LAS unsigned*)(lds + (bufoff) + ldsw + _i * 8192), 16, 0, 0); } while (0)
; #define PG8_LDA(dst, b, h) do { _Pragma("unroll") for (int m = 0; m < 4; ++m) _Pragma("unroll") for (int k = 0; k < 2; ++k) dst[m][k] = *(const PG8_LAS bf16x8*)(lds + PG8_SA(b, h) + aoff + m * 2048 + k * 1024); } while (0)
; #define PG8_MMA(ai, bj, At, Bt) do { __builtin_amdgcn_s_setprio(1); _Pragma("unroll") for (int m = 0; m < 4; ++m) _Pragma("unroll") for (int n = 0; n < 2; ++n) _Pragma("unroll") for (int k = 0; k < 2; ++k) \
;         acc[ai][bj][m][n] = __builtin_amdgcn_mfma_f32_16x16x32_bf16(Bt[n][k], At[m][k], acc[ai][bj][m][n], 0, 0, 0); __builtin_amdgcn_s_setprio(0); } while (0)
; #define PG8_WAIT_V(n) asm volatile("s_waitcnt vmcnt(" #n ")" ::: "memory")
; #define PG8_WAIT_L(n) asm volatile("s_waitcnt lgkmcnt(" #n ")" ::: "memory")
; #define PG8_BAR __builtin_amdgcn_s_barrier()
; #define PG8_SCHED __builtin_amdgcn_sched_barrier(0)
; template <class Epi, class Sched, bool ALIGN_EPI = false, bool SP2 = false>
; __device__ __forceinline__ void gemm_phase(PG8_LAS unsigned char* lds, const Gemm g, const Sched& S, const Epi& E, const int tid) {
;     ...
;             PG8_LDA(At, 1, 1); PG8_STAGE(PG8_SB(1, 0), b3, voffB); PG8_STAGE(PG8_SB(1, 1), b3 + hstep, voffB); PG8_STAGE(PG8_SA(1, 0), a3, voffA);
;             PG8_WAIT_V(8); PG8_WAIT_L(0); PG8_BAR; PG8_MMA(1, 0, At, B0); PG8_MMA(1, 1, At, B1); PG8_BAR; PG8_SCHED;
	s_add_i32 s6, s15, s52
	v_lshl_add_u64 v[220:221], v[220:221], 0, s[34:35]
	s_mov_b32 m0, s6
	ds_read_b128 v[182:185], v206 offset:49152
	ds_read_b128 v[186:189], v206 offset:50176
	ds_read_b128 v[192:195], v206 offset:51200
	ds_read_b128 v[196:199], v206 offset:52224
	ds_read_b128 v[200:203], v206 offset:53248
	ds_read_b128 v[208:211], v206 offset:54272
	ds_read_b128 v[212:215], v206 offset:55296
	ds_read_b128 v[216:219], v206 offset:56320
	global_load_lds_dwordx4 v[220:221], off
	s_add_i32 m0, s6, 0x2000
	s_add_u32 s6, s10, 0xb0080
	v_lshl_add_u64 v[220:221], v[222:223], 0, s[34:35]
	s_addc_u32 s7, s11, 0
	s_add_i32 s10, s18, s52
	global_load_lds_dwordx4 v[220:221], off
	v_lshl_add_u64 v[220:221], s[6:7], 0, v[164:165]
	s_mov_b32 m0, s10
	s_nop 0
	global_load_lds_dwordx4 v[220:221], off
	v_lshl_add_u64 v[220:221], s[6:7], 0, v[168:169]
	s_add_i32 m0, s10, 0x2000
	s_nop 0
	global_load_lds_dwordx4 v[220:221], off
	v_lshl_add_u64 v[220:221], v[224:225], 0, s[34:35]
	s_mov_b32 m0, s58
	s_nop 0
	global_load_lds_dwordx4 v[220:221], off
	v_lshl_add_u64 v[220:221], v[226:227], 0, s[34:35]
	s_mov_b32 m0, s59
	s_nop 0
	global_load_lds_dwordx4 v[220:221], off
	s_waitcnt vmcnt(8)
	s_waitcnt lgkmcnt(0)
	s_barrier
	s_setprio 1
	s_waitcnt lgkmcnt(0)
	v_mfma_f32_16x16x32_bf16 v[62:65], v[130:133], v[182:185], v[62:65]
	v_mfma_f32_16x16x32_bf16 v[58:61], v[138:141], v[182:185], v[58:61]
	v_mfma_f32_16x16x32_bf16 v[46:49], v[130:133], v[192:195], v[46:49]
	v_mfma_f32_16x16x32_bf16 v[42:45], v[138:141], v[192:195], v[42:45]
	v_mfma_f32_16x16x32_bf16 v[30:33], v[130:133], v[200:203], v[30:33]
	v_mfma_f32_16x16x32_bf16 v[26:29], v[138:141], v[200:203], v[26:29]
	v_mfma_f32_16x16x32_bf16 v[14:17], v[130:133], v[212:215], v[14:17]
	v_mfma_f32_16x16x32_bf16 v[10:13], v[138:141], v[212:215], v[10:13]
	v_mfma_f32_16x16x32_bf16 v[62:65], v[134:137], v[186:189], v[62:65]
	v_mfma_f32_16x16x32_bf16 v[58:61], v[142:145], v[186:189], v[58:61]
	v_mfma_f32_16x16x32_bf16 v[46:49], v[134:137], v[196:199], v[46:49]
	v_mfma_f32_16x16x32_bf16 v[42:45], v[142:145], v[196:199], v[42:45]
	v_mfma_f32_16x16x32_bf16 v[30:33], v[134:137], v[208:211], v[30:33]
	v_mfma_f32_16x16x32_bf16 v[26:29], v[142:145], v[208:211], v[26:29]
	v_mfma_f32_16x16x32_bf16 v[14:17], v[134:137], v[216:219], v[14:17]
	v_mfma_f32_16x16x32_bf16 v[10:13], v[142:145], v[216:219], v[10:13]
	s_setprio 0
	s_setprio 1
	v_mfma_f32_16x16x32_bf16 v[54:57], v[146:149], v[182:185], v[54:57]
	v_mfma_f32_16x16x32_bf16 v[50:53], v[154:157], v[182:185], v[50:53]
	v_mfma_f32_16x16x32_bf16 v[38:41], v[146:149], v[192:195], v[38:41]
	v_mfma_f32_16x16x32_bf16 v[34:37], v[154:157], v[192:195], v[34:37]
	v_mfma_f32_16x16x32_bf16 v[22:25], v[146:149], v[200:203], v[22:25]
	v_mfma_f32_16x16x32_bf16 v[18:21], v[154:157], v[200:203], v[18:21]
	v_mfma_f32_16x16x32_bf16 v[6:9], v[146:149], v[212:215], v[6:9]
	v_mfma_f32_16x16x32_bf16 v[2:5], v[154:157], v[212:215], v[2:5]
	v_mfma_f32_16x16x32_bf16 v[54:57], v[150:153], v[186:189], v[54:57]
	v_mfma_f32_16x16x32_bf16 v[50:53], v[158:161], v[186:189], v[50:53]
	v_mfma_f32_16x16x32_bf16 v[38:41], v[150:153], v[196:199], v[38:41]
	v_mfma_f32_16x16x32_bf16 v[34:37], v[158:161], v[196:199], v[34:37]
	v_mfma_f32_16x16x32_bf16 v[22:25], v[150:153], v[208:211], v[22:25]
	v_mfma_f32_16x16x32_bf16 v[18:21], v[158:161], v[208:211], v[18:21]
	v_mfma_f32_16x16x32_bf16 v[6:9], v[150:153], v[216:219], v[6:9]
	v_mfma_f32_16x16x32_bf16 v[2:5], v[158:161], v[216:219], v[2:5]
	s_setprio 0
	s_barrier
	s_add_i32 s74, s74, 2
	s_add_u32 s43, s43, 0x100
	s_addc_u32 s45, s45, 0
	s_mov_b64 s[6:7], s[8:9]

; #define PG8_STAGE(bufoff, gbase, voff) do { _Pragma("unroll") for (int _i = 0; _i < 2; ++_i) \
;         __builtin_amdgcn_global_load_lds((const unsigned*)((const char*)(gbase) + (voff)[_i]), (PG8_LAS unsigned*)(lds + (bufoff) + ldsw + _i * 8192), 16, 0, 0); } while (0)
; #define PG8_LDA(dst, b, h) do { _Pragma("unroll") for (int m = 0; m < 4; ++m) _Pragma("unroll") for (int k = 0; k < 2; ++k) dst[m][k] = *(const PG8_LAS bf16x8*)(lds + PG8_SA(b, h) + aoff + m * 2048 + k * 1024); } while (0)
; #define PG8_LDB(dst, b, h) do { _Pragma("unroll") for (int n = 0; n < 2; ++n) _Pragma("unroll") for (int k = 0; k < 2; ++k) dst[n][k] = *(const PG8_LAS bf16x8*)(lds + PG8_SB(b, h) + boff + n * 2048 + k * 1024); } while (0)
; #define PG8_SCHED __builtin_amdgcn_sched_barrier(0)
;     __host__ __device__ bool next(int i, Unit& u) const {
;         const long L = (long)i * G + c; if (L >= nwg) return false;
;         int wgid = (int)L; { const int q = nwg / NXCD, r = nwg % NXCD, xcd = wgid % NXCD, off = wgid / NXCD; wgid = (xcd < r ? xcd * (q + 1) : r * (q + 1) + (xcd - r) * q) + off; }
;         const int nig = WGM * nN, gid = wgid / nig, fm = gid * WGM, gsz = (nM - fm) < WGM ? (nM - fm) : WGM;
;         u.pm = fm + ((wgid % nig) % gsz); u.pn = (wgid % nig) / gsz; u.sub = 0; return true;
; template <class Epi, class Sched, bool ALIGN_EPI = false, bool SP2 = false>
; __device__ __forceinline__ void gemm_phase(PG8_LAS unsigned char* lds, const Gemm g, const Sched& S, const Epi& E, const int tid) {
;     ...
;             PG8_LDB(B0, 0, 0); PG8_LDB(B1, 0, 1); PG8_SCHED; PG8_LDA(At, 0, 0); PG8_STAGE(PG8_SA(1, 1), a1 + hstep, voffA);
.LBB0_5748:
	ds_read_b128 v[130:133], v171
	ds_read_b128 v[134:137], v171 offset:1024
	ds_read_b128 v[160:163], v171 offset:2048
	ds_read_b128 v[164:167], v171 offset:3072
	ds_read_b128 v[176:179], v172
	ds_read_b128 v[180:183], v172 offset:1024
	ds_read_b128 v[184:187], v172 offset:2048
	ds_read_b128 v[192:195], v172 offset:3072
	ds_read_b128 v[196:199], v173
	ds_read_b128 v[200:203], v173 offset:1024
	ds_read_b128 v[204:207], v173 offset:2048
	ds_read_b128 v[208:211], v173 offset:3072
	ds_read_b128 v[212:215], v173 offset:4096
	ds_read_b128 v[216:219], v173 offset:5120
	ds_read_b128 v[220:223], v173 offset:6144
	ds_read_b128 v[224:227], v173 offset:7168
	s_add_i32 s91, s91, 1
	s_lshr_b32 s0, s91, 2
	s_mul_hi_i32 s1, s0, s62
	s_mul_i32 s0, s0, s62
	s_add_u32 s2, s0, s6
	s_addc_u32 s3, s1, s7
	v_cmp_gt_i64_e32 vcc, s[2:3], v[158:159]
	v_cmp_lt_i64_e64 s[0:1], s[2:3], v[156:157]
	s_cbranch_vccnz .LBB0_5750
	s_ashr_i32 s3, s2, 31
	s_lshr_b32 s3, s3, 29
	s_add_i32 s3, s2, s3
	s_ashr_i32 s5, s3, 3
	s_and_b32 s3, s3, -8
	s_sub_i32 s2, s2, s3
	s_cmp_lt_i32 s2, 0
	s_cselect_b32 s3, s82, 0x61
	s_mul_i32 s2, s3, s2
	s_add_i32 s2, s2, s5
	s_ashr_i32 s3, s2, 31
	s_lshr_b32 s3, s3, 27
	s_add_i32 s3, s2, s3
	s_ashr_i32 s5, s3, 5
	s_lshl_b32 s5, s5, 3
	s_sub_i32 s15, 0xc2, s5
	s_min_i32 s15, s15, 8
	s_abs_i32 s18, s15
	v_cvt_f32_u32_e32 v2, s18
	s_sub_i32 s46, 0, s18
	s_andn2_b32 s3, s3, 31
	s_sub_i32 s2, s2, s3
	v_rcp_iflag_f32_e32 v2, v2
	s_abs_i32 s3, s2
	s_xor_b32 s19, s2, s15
	s_ashr_i32 s19, s19, 31
	v_mul_f32_e32 v2, 0x4f7ffffe, v2
	v_cvt_u32_f32_e32 v2, v2
	s_nop 0
	v_readfirstlane_b32 s47, v2
	s_mul_i32 s46, s46, s47
	s_mul_hi_u32 s46, s47, s46
	s_add_i32 s47, s47, s46
	s_mul_hi_u32 s46, s3, s47
	s_mul_i32 s47, s46, s18
	s_sub_i32 s3, s3, s47
	s_add_i32 s48, s46, 1
	s_sub_i32 s47, s3, s18
	s_cmp_ge_u32 s3, s18
	s_cselect_b32 s46, s48, s46
	s_cselect_b32 s3, s47, s3
	s_add_i32 s47, s46, 1
	s_cmp_ge_u32 s3, s18
	s_cselect_b32 s3, s47, s46
	s_xor_b32 s3, s3, s19
	s_sub_i32 s46, s3, s19
	s_mul_i32 s3, s46, s15
	s_sub_i32 s2, s2, s3
	s_add_i32 s48, s2, s5
	s_and_b32 s92, s91, 3

; #define PG8_STAGE(bufoff, gbase, voff) do { _Pragma("unroll") for (int _i = 0; _i < 2; ++_i) \
;         __builtin_amdgcn_global_load_lds((const unsigned*)((const char*)(gbase) + (voff)[_i]), (PG8_LAS unsigned*)(lds + (bufoff) + ldsw + _i * 8192), 16, 0, 0); } while (0)
; #define PG8_LDA(dst, b, h) do { _Pragma("unroll") for (int m = 0; m < 4; ++m) _Pragma("unroll") for (int k = 0; k < 2; ++k) dst[m][k] = *(const PG8_LAS bf16x8*)(lds + PG8_SA(b, h) + aoff + m * 2048 + k * 1024); } while (0)
; #define PG8_LDB(dst, b, h) do { _Pragma("unroll") for (int n = 0; n < 2; ++n) _Pragma("unroll") for (int k = 0; k < 2; ++k) dst[n][k] = *(const PG8_LAS bf16x8*)(lds + PG8_SB(b, h) + boff + n * 2048 + k * 1024); } while (0)
; #define PG8_MMA(ai, bj, At, Bt) do { __builtin_amdgcn_s_setprio(1); _Pragma("unroll") for (int m = 0; m < 4; ++m) _Pragma("unroll") for (int n = 0; n < 2; ++n) _Pragma("unroll") for (int k = 0; k < 2; ++k) \
;         acc[ai][bj][m][n] = __builtin_amdgcn_mfma_f32_16x16x32_bf16(Bt[n][k], At[m][k], acc[ai][bj][m][n], 0, 0, 0); __builtin_amdgcn_s_setprio(0); } while (0)
; #define PG8_WAIT_V(n) asm volatile("s_waitcnt vmcnt(" #n ")" ::: "memory")
; #define PG8_BAR __builtin_amdgcn_s_barrier()
; template <class Epi, class Sched, bool ALIGN_EPI = false, bool SP2 = false>
; __device__ __forceinline__ void gemm_phase(PG8_LAS unsigned char* lds, const Gemm g, const Sched& S, const Epi& E, const int tid) {
;     ...
;         for (int t = 0; t < nt; t += 2) {
;             const bool last = (t == nt - 2);
;             const char* a1 = cA + (size_t)(t + 1) * kstep;
;             const char* a2 = last ? nA : cA + (size_t)(t + 2) * kstep; const char* b2 = last ? nB : cB + (size_t)(t + 2) * kstep;
;             const char* a3 = a2 + kstep; const char* b3 = b2 + kstep;
;             if (last && has_next) S.a_ready(nxt);
;             if constexpr (SP2) {
;             PG8_LDB(B0, 0, 0); PG8_LDB(B1, 0, 1); PG8_SCHED; PG8_LDA(At, 0, 0); PG8_STAGE(PG8_SA(1, 1), a1 + hstep, voffA);
;             PG8_WAIT_V(8); PG8_WAIT_L(0); PG8_BAR; PG8_MMA(0, 0, At, B0); PG8_MMA(0, 1, At, B1); PG8_BAR; PG8_SCHED;
;             PG8_LDA(At, 0, 1); PG8_STAGE(PG8_SB(0, 0), b2, voffB); PG8_STAGE(PG8_SB(0, 1), b2 + hstep, voffB); PG8_STAGE(PG8_SA(0, 0), a2, voffA);
;             PG8_WAIT_V(8); PG8_WAIT_L(0); PG8_BAR; PG8_MMA(1, 0, At, B0); PG8_MMA(1, 1, At, B1); PG8_BAR; PG8_SCHED;
.LBB0_5776:
	s_add_u32 s5, s54, 0x100
	s_addc_u32 s47, s55, 0
	s_add_u32 s54, s56, 0x40080
	s_addc_u32 s55, s57, 0
	s_mov_b32 s49, -2
	s_add_u32 s15, s54, 0xfffc0080
	s_addc_u32 s18, s55, -1
	s_cmp_eq_u32 s49, 12
	s_cselect_b32 s59, s1, s18
	s_cselect_b32 s58, s0, s15
	s_cselect_b32 s57, s51, s47
	s_cselect_b32 s56, s50, s5
	v_lshl_add_u64 v[168:169], s[54:55], 0, v[154:155]
	s_add_i32 m0, s64, 0xc000
	global_load_lds_dwordx4 v[168:169], off
	v_lshl_add_u64 v[168:169], s[54:55], 0, v[152:153]
	s_add_i32 m0, s64, 0xe000
	s_nop 0
	global_load_lds_dwordx4 v[168:169], off
	s_waitcnt vmcnt(8)
	s_waitcnt lgkmcnt(0)
	s_barrier
	s_setprio 1
	s_waitcnt lgkmcnt(0)
	v_mfma_f32_16x16x32_bf16 v[126:129], v[130:133], v[196:199], 0
	v_mfma_f32_16x16x32_bf16 v[122:125], v[160:163], v[196:199], 0
	v_mfma_f32_16x16x32_bf16 v[110:113], v[130:133], v[204:207], 0
	v_mfma_f32_16x16x32_bf16 v[106:109], v[160:163], v[204:207], 0
	v_mfma_f32_16x16x32_bf16 v[94:97], v[130:133], v[212:215], 0
	v_mfma_f32_16x16x32_bf16 v[90:93], v[160:163], v[212:215], 0
	v_mfma_f32_16x16x32_bf16 v[78:81], v[130:133], v[220:223], 0
	v_mfma_f32_16x16x32_bf16 v[74:77], v[160:163], v[220:223], 0
	v_mfma_f32_16x16x32_bf16 v[126:129], v[134:137], v[200:203], v[126:129]
	v_mfma_f32_16x16x32_bf16 v[122:125], v[164:167], v[200:203], v[122:125]
	v_mfma_f32_16x16x32_bf16 v[110:113], v[134:137], v[208:211], v[110:113]
	v_mfma_f32_16x16x32_bf16 v[106:109], v[164:167], v[208:211], v[106:109]
	v_mfma_f32_16x16x32_bf16 v[94:97], v[134:137], v[216:219], v[94:97]
	v_mfma_f32_16x16x32_bf16 v[90:93], v[164:167], v[216:219], v[90:93]
	v_mfma_f32_16x16x32_bf16 v[78:81], v[134:137], v[224:227], v[78:81]
	v_mfma_f32_16x16x32_bf16 v[74:77], v[164:167], v[224:227], v[74:77]
	s_setprio 0
	s_setprio 1
	v_mfma_f32_16x16x32_bf16 v[118:121], v[176:179], v[196:199], 0
	v_mfma_f32_16x16x32_bf16 v[114:117], v[184:187], v[196:199], 0
	v_mfma_f32_16x16x32_bf16 v[102:105], v[176:179], v[204:207], 0
	v_mfma_f32_16x16x32_bf16 v[98:101], v[184:187], v[204:207], 0
	v_mfma_f32_16x16x32_bf16 v[86:89], v[176:179], v[212:215], 0
	v_mfma_f32_16x16x32_bf16 v[82:85], v[184:187], v[212:215], 0
	v_mfma_f32_16x16x32_bf16 v[70:73], v[176:179], v[220:223], 0
	v_mfma_f32_16x16x32_bf16 v[66:69], v[184:187], v[220:223], 0
	v_mfma_f32_16x16x32_bf16 v[118:121], v[180:183], v[200:203], v[118:121]
	v_mfma_f32_16x16x32_bf16 v[114:117], v[192:195], v[200:203], v[114:117]
	v_mfma_f32_16x16x32_bf16 v[102:105], v[180:183], v[208:211], v[102:105]
	v_mfma_f32_16x16x32_bf16 v[98:101], v[192:195], v[208:211], v[98:101]
	v_mfma_f32_16x16x32_bf16 v[86:89], v[180:183], v[216:219], v[86:89]
	v_mfma_f32_16x16x32_bf16 v[82:85], v[192:195], v[216:219], v[82:85]
	v_mfma_f32_16x16x32_bf16 v[70:73], v[180:183], v[224:227], v[70:73]
	v_mfma_f32_16x16x32_bf16 v[66:69], v[192:195], v[224:227], v[66:69]
	s_setprio 0
	s_barrier
	s_add_i32 s15, s83, s63
	v_lshl_add_u64 v[168:169], s[56:57], 0, v[140:141]
	s_mov_b32 m0, s15
	ds_read_b128 v[196:199], v173 offset:16384
	ds_read_b128 v[200:203], v173 offset:17408
	ds_read_b128 v[204:207], v173 offset:18432
	ds_read_b128 v[208:211], v173 offset:19456
	ds_read_b128 v[212:215], v173 offset:20480
	ds_read_b128 v[216:219], v173 offset:21504
	ds_read_b128 v[220:223], v173 offset:22528
	ds_read_b128 v[224:227], v173 offset:23552
	global_load_lds_dwordx4 v[168:169], off
	s_add_i32 m0, s15, 0x2000
	s_add_u32 s18, s56, 0x40000
	v_lshl_add_u64 v[188:189], s[56:57], 0, v[144:145]
	s_addc_u32 s19, s57, 0
	s_add_i32 s15, s84, s63
	global_load_lds_dwordx4 v[188:189], off
	v_lshl_add_u64 v[228:229], s[18:19], 0, v[140:141]
	s_mov_b32 m0, s15
	v_lshl_add_u64 v[230:231], s[58:59], 0, v[142:143]
	global_load_lds_dwordx4 v[228:229], off
	v_lshl_add_u64 v[228:229], s[18:19], 0, v[144:145]
	s_add_i32 m0, s15, 0x2000
	s_nop 0
	global_load_lds_dwordx4 v[228:229], off
	v_lshl_add_u64 v[228:229], s[58:59], 0, v[138:139]
	s_mov_b32 m0, s64
	s_nop 0
	global_load_lds_dwordx4 v[228:229], off
	s_mov_b32 m0, s65
	s_nop 0
	global_load_lds_dwordx4 v[230:231], off
	s_waitcnt vmcnt(8)
	s_waitcnt lgkmcnt(0)
	s_barrier
	s_setprio 1
	s_waitcnt lgkmcnt(0)
	v_mfma_f32_16x16x32_bf16 v[62:65], v[130:133], v[196:199], 0
	v_mfma_f32_16x16x32_bf16 v[58:61], v[160:163], v[196:199], 0
	v_mfma_f32_16x16x32_bf16 v[46:49], v[130:133], v[204:207], 0
	v_mfma_f32_16x16x32_bf16 v[42:45], v[160:163], v[204:207], 0
	v_mfma_f32_16x16x32_bf16 v[30:33], v[130:133], v[212:215], 0
	v_mfma_f32_16x16x32_bf16 v[26:29], v[160:163], v[212:215], 0
	v_mfma_f32_16x16x32_bf16 v[14:17], v[130:133], v[220:223], 0
	v_mfma_f32_16x16x32_bf16 v[10:13], v[160:163], v[220:223], 0
	v_mfma_f32_16x16x32_bf16 v[62:65], v[134:137], v[200:203], v[62:65]
	v_mfma_f32_16x16x32_bf16 v[58:61], v[164:167], v[200:203], v[58:61]
	v_mfma_f32_16x16x32_bf16 v[46:49], v[134:137], v[208:211], v[46:49]
	v_mfma_f32_16x16x32_bf16 v[42:45], v[164:167], v[208:211], v[42:45]
	v_mfma_f32_16x16x32_bf16 v[30:33], v[134:137], v[216:219], v[30:33]
	v_mfma_f32_16x16x32_bf16 v[26:29], v[164:167], v[216:219], v[26:29]
	v_mfma_f32_16x16x32_bf16 v[14:17], v[134:137], v[224:227], v[14:17]
	v_mfma_f32_16x16x32_bf16 v[10:13], v[164:167], v[224:227], v[10:13]
	s_setprio 0
	s_setprio 1
	v_mfma_f32_16x16x32_bf16 v[54:57], v[176:179], v[196:199], 0
	v_mfma_f32_16x16x32_bf16 v[50:53], v[184:187], v[196:199], 0
	v_mfma_f32_16x16x32_bf16 v[38:41], v[176:179], v[204:207], 0
	v_mfma_f32_16x16x32_bf16 v[34:37], v[184:187], v[204:207], 0
	v_mfma_f32_16x16x32_bf16 v[22:25], v[176:179], v[212:215], 0
	v_mfma_f32_16x16x32_bf16 v[18:21], v[184:187], v[212:215], 0
	v_mfma_f32_16x16x32_bf16 v[6:9], v[176:179], v[220:223], 0
	v_mfma_f32_16x16x32_bf16 v[2:5], v[184:187], v[220:223], 0
	v_mfma_f32_16x16x32_bf16 v[54:57], v[180:183], v[200:203], v[54:57]
	v_mfma_f32_16x16x32_bf16 v[50:53], v[192:195], v[200:203], v[50:53]
	v_mfma_f32_16x16x32_bf16 v[38:41], v[180:183], v[208:211], v[38:41]
	v_mfma_f32_16x16x32_bf16 v[34:37], v[192:195], v[208:211], v[34:37]
	v_mfma_f32_16x16x32_bf16 v[22:25], v[180:183], v[216:219], v[22:25]
	v_mfma_f32_16x16x32_bf16 v[18:21], v[192:195], v[216:219], v[18:21]
	v_mfma_f32_16x16x32_bf16 v[6:9], v[180:183], v[224:227], v[6:9]
	v_mfma_f32_16x16x32_bf16 v[2:5], v[192:195], v[224:227], v[2:5]
	s_setprio 0
	s_barrier
; #define PG8_STAGE(bufoff, gbase, voff) do { _Pragma("unroll") for (int _i = 0; _i < 2; ++_i) \
;         __builtin_amdgcn_global_load_lds((const unsigned*)((const char*)(gbase) + (voff)[_i]), (PG8_LAS unsigned*)(lds + (bufoff) + ldsw + _i * 8192), 16, 0, 0); } while (0)
; #define PG8_LDA(dst, b, h) do { _Pragma("unroll") for (int m = 0; m < 4; ++m) _Pragma("unroll") for (int k = 0; k < 2; ++k) dst[m][k] = *(const PG8_LAS bf16x8*)(lds + PG8_SA(b, h) + aoff + m * 2048 + k * 1024); } while (0)
; #define PG8_LDB(dst, b, h) do { _Pragma("unroll") for (int n = 0; n < 2; ++n) _Pragma("unroll") for (int k = 0; k < 2; ++k) dst[n][k] = *(const PG8_LAS bf16x8*)(lds + PG8_SB(b, h) + boff + n * 2048 + k * 1024); } while (0)
; #define PG8_MMA(ai, bj, At, Bt) do { __builtin_amdgcn_s_setprio(1); _Pragma("unroll") for (int m = 0; m < 4; ++m) _Pragma("unroll") for (int n = 0; n < 2; ++n) _Pragma("unroll") for (int k = 0; k < 2; ++k) \
;         acc[ai][bj][m][n] = __builtin_amdgcn_mfma_f32_16x16x32_bf16(Bt[n][k], At[m][k], acc[ai][bj][m][n], 0, 0, 0); __builtin_amdgcn_s_setprio(0); } while (0)
; #define PG8_WAIT_V(n) asm volatile("s_waitcnt vmcnt(" #n ")" ::: "memory")
; #define PG8_WAIT_L(n) asm volatile("s_waitcnt lgkmcnt(" #n ")" ::: "memory")
; #define PG8_BAR __builtin_amdgcn_s_barrier()
; #define PG8_SCHED __builtin_amdgcn_sched_barrier(0)
; template <class Epi, class Sched, bool ALIGN_EPI = false, bool SP2 = false>
; __device__ __forceinline__ void gemm_phase(PG8_LAS unsigned char* lds, const Gemm g, const Sched& S, const Epi& E, const int tid) {
;     ...
;             PG8_LDB(B0, 1, 0); PG8_LDB(B1, 1, 1); PG8_SCHED; PG8_LDA(At, 1, 0); PG8_STAGE(PG8_SA(0, 1), a2 + hstep, voffA);
;             PG8_WAIT_V(8); PG8_WAIT_L(0); PG8_BAR; PG8_MMA(0, 0, At, B0); PG8_MMA(0, 1, At, B1); PG8_BAR; PG8_SCHED;
	s_add_i32 s15, 0, 0x18000
	s_add_i32 s60, 0, 0x1c000
	v_add_u32_e32 v164, s15, v170
	v_add_u32_e32 v175, s60, v170
	ds_read_b128 v[130:133], v164
	ds_read_b128 v[134:137], v164 offset:1024
	ds_read_b128 v[160:163], v164 offset:2048
	ds_read_b128 v[164:167], v164 offset:3072
	ds_read_b128 v[176:179], v175
	ds_read_b128 v[180:183], v175 offset:1024
	ds_read_b128 v[184:187], v175 offset:2048
	ds_read_b128 v[192:195], v175 offset:3072
	s_add_u32 s18, s58, 0x40000
	s_addc_u32 s19, s59, 0
	s_mov_b32 m0, s66
	v_lshl_add_u64 v[232:233], s[18:19], 0, v[138:139]
	ds_read_b128 v[196:199], v173 offset:32768
	ds_read_b128 v[200:203], v173 offset:33792
	ds_read_b128 v[204:207], v173 offset:34816
	ds_read_b128 v[208:211], v173 offset:35840
	ds_read_b128 v[212:215], v173 offset:36864
	ds_read_b128 v[216:219], v173 offset:37888
	ds_read_b128 v[220:223], v173 offset:38912
	ds_read_b128 v[224:227], v173 offset:39936
	global_load_lds_dwordx4 v[232:233], off
	v_lshl_add_u64 v[232:233], s[18:19], 0, v[142:143]
	s_mov_b32 m0, s67
	s_nop 0
	global_load_lds_dwordx4 v[232:233], off
	s_waitcnt vmcnt(8)
	s_waitcnt lgkmcnt(0)
	s_barrier
	s_setprio 1
	s_waitcnt lgkmcnt(0)
	v_mfma_f32_16x16x32_bf16 v[126:129], v[130:133], v[196:199], v[126:129]
	v_mfma_f32_16x16x32_bf16 v[122:125], v[160:163], v[196:199], v[122:125]
	v_mfma_f32_16x16x32_bf16 v[110:113], v[130:133], v[204:207], v[110:113]
	v_mfma_f32_16x16x32_bf16 v[106:109], v[160:163], v[204:207], v[106:109]
	v_mfma_f32_16x16x32_bf16 v[94:97], v[130:133], v[212:215], v[94:97]
	v_mfma_f32_16x16x32_bf16 v[90:93], v[160:163], v[212:215], v[90:93]
	v_mfma_f32_16x16x32_bf16 v[78:81], v[130:133], v[220:223], v[78:81]
	v_mfma_f32_16x16x32_bf16 v[74:77], v[160:163], v[220:223], v[74:77]
	v_mfma_f32_16x16x32_bf16 v[126:129], v[134:137], v[200:203], v[126:129]
	v_mfma_f32_16x16x32_bf16 v[122:125], v[164:167], v[200:203], v[122:125]
	v_mfma_f32_16x16x32_bf16 v[110:113], v[134:137], v[208:211], v[110:113]
	v_mfma_f32_16x16x32_bf16 v[106:109], v[164:167], v[208:211], v[106:109]
	v_mfma_f32_16x16x32_bf16 v[94:97], v[134:137], v[216:219], v[94:97]
	v_mfma_f32_16x16x32_bf16 v[90:93], v[164:167], v[216:219], v[90:93]
	v_mfma_f32_16x16x32_bf16 v[78:81], v[134:137], v[224:227], v[78:81]
	v_mfma_f32_16x16x32_bf16 v[74:77], v[164:167], v[224:227], v[74:77]
	s_setprio 0
	s_setprio 1
	v_mfma_f32_16x16x32_bf16 v[118:121], v[176:179], v[196:199], v[118:121]
	v_mfma_f32_16x16x32_bf16 v[114:117], v[184:187], v[196:199], v[114:117]
	v_mfma_f32_16x16x32_bf16 v[102:105], v[176:179], v[204:207], v[102:105]
	v_mfma_f32_16x16x32_bf16 v[98:101], v[184:187], v[204:207], v[98:101]
	v_mfma_f32_16x16x32_bf16 v[86:89], v[176:179], v[212:215], v[86:89]
	v_mfma_f32_16x16x32_bf16 v[82:85], v[184:187], v[212:215], v[82:85]
	v_mfma_f32_16x16x32_bf16 v[70:73], v[176:179], v[220:223], v[70:73]
	v_mfma_f32_16x16x32_bf16 v[66:69], v[184:187], v[220:223], v[66:69]
	v_mfma_f32_16x16x32_bf16 v[118:121], v[180:183], v[200:203], v[118:121]
	v_mfma_f32_16x16x32_bf16 v[114:117], v[192:195], v[200:203], v[114:117]
	v_mfma_f32_16x16x32_bf16 v[102:105], v[180:183], v[208:211], v[102:105]
	v_mfma_f32_16x16x32_bf16 v[98:101], v[192:195], v[208:211], v[98:101]
	v_mfma_f32_16x16x32_bf16 v[86:89], v[180:183], v[216:219], v[86:89]
	v_mfma_f32_16x16x32_bf16 v[82:85], v[192:195], v[216:219], v[82:85]
	v_mfma_f32_16x16x32_bf16 v[70:73], v[180:183], v[224:227], v[70:73]
	v_mfma_f32_16x16x32_bf16 v[66:69], v[192:195], v[224:227], v[66:69]
	s_setprio 0
	s_barrier
; #define PG8_STAGE(bufoff, gbase, voff) do { _Pragma("unroll") for (int _i = 0; _i < 2; ++_i) \
;         __builtin_amdgcn_global_load_lds((const unsigned*)((const char*)(gbase) + (voff)[_i]), (PG8_LAS unsigned*)(lds + (bufoff) + ldsw + _i * 8192), 16, 0, 0); } while (0)
; #define PG8_LDA(dst, b, h) do { _Pragma("unroll") for (int m = 0; m < 4; ++m) _Pragma("unroll") for (int k = 0; k < 2; ++k) dst[m][k] = *(const PG8_LAS bf16x8*)(lds + PG8_SA(b, h) + aoff + m * 2048 + k * 1024); } while (0)
; #define PG8_MMA(ai, bj, At, Bt) do { __builtin_amdgcn_s_setprio(1); _Pragma("unroll") for (int m = 0; m < 4; ++m) _Pragma("unroll") for (int n = 0; n < 2; ++n) _Pragma("unroll") for (int k = 0; k < 2; ++k) \
;         acc[ai][bj][m][n] = __builtin_amdgcn_mfma_f32_16x16x32_bf16(Bt[n][k], At[m][k], acc[ai][bj][m][n], 0, 0, 0); __builtin_amdgcn_s_setprio(0); } while (0)
; #define PG8_WAIT_V(n) asm volatile("s_waitcnt vmcnt(" #n ")" ::: "memory")
; #define PG8_WAIT_L(n) asm volatile("s_waitcnt lgkmcnt(" #n ")" ::: "memory")
; #define PG8_BAR __builtin_amdgcn_s_barrier()
; #define PG8_SCHED __builtin_amdgcn_sched_barrier(0)
; template <class Epi, class Sched, bool ALIGN_EPI = false, bool SP2 = false>
; __device__ __forceinline__ void gemm_phase(PG8_LAS unsigned char* lds, const Gemm g, const Sched& S, const Epi& E, const int tid) {
;     ...
;             PG8_LDA(At, 1, 1); PG8_STAGE(PG8_SB(1, 0), b3, voffB); PG8_STAGE(PG8_SB(1, 1), b3 + hstep, voffB); PG8_STAGE(PG8_SA(1, 0), a3, voffA);
;             PG8_WAIT_V(8); PG8_WAIT_L(0); PG8_BAR; PG8_MMA(1, 0, At, B0); PG8_MMA(1, 1, At, B1); PG8_BAR; PG8_SCHED;
	s_add_i32 s15, s15, s63
	v_lshl_add_u64 v[168:169], v[168:169], 0, s[42:43]
	s_mov_b32 m0, s15
	ds_read_b128 v[196:199], v173 offset:49152
	ds_read_b128 v[200:203], v173 offset:50176
	ds_read_b128 v[204:207], v173 offset:51200
	ds_read_b128 v[208:211], v173 offset:52224
	ds_read_b128 v[212:215], v173 offset:53248
	ds_read_b128 v[216:219], v173 offset:54272
	ds_read_b128 v[220:223], v173 offset:55296
	ds_read_b128 v[224:227], v173 offset:56320
	global_load_lds_dwordx4 v[168:169], off
	s_add_i32 m0, s15, 0x2000
	s_add_u32 s18, s56, 0x40080
	v_lshl_add_u64 v[168:169], v[188:189], 0, s[42:43]
	s_addc_u32 s19, s57, 0
	s_add_i32 s15, s60, s63
	global_load_lds_dwordx4 v[168:169], off
	v_lshl_add_u64 v[168:169], s[18:19], 0, v[140:141]
	s_mov_b32 m0, s15
	s_nop 0
	global_load_lds_dwordx4 v[168:169], off
	v_lshl_add_u64 v[168:169], s[18:19], 0, v[144:145]
	s_add_i32 m0, s15, 0x2000
	s_nop 0
	global_load_lds_dwordx4 v[168:169], off
	v_lshl_add_u64 v[168:169], v[228:229], 0, s[42:43]
	s_mov_b32 m0, s74
	s_nop 0
	global_load_lds_dwordx4 v[168:169], off
	v_lshl_add_u64 v[168:169], v[230:231], 0, s[42:43]
	s_mov_b32 m0, s75
	s_nop 0
	global_load_lds_dwordx4 v[168:169], off
	s_waitcnt vmcnt(8)
	s_waitcnt lgkmcnt(0)
	s_barrier
	s_setprio 1
	s_waitcnt lgkmcnt(0)
	v_mfma_f32_16x16x32_bf16 v[62:65], v[130:133], v[196:199], v[62:65]
	v_mfma_f32_16x16x32_bf16 v[58:61], v[160:163], v[196:199], v[58:61]
	v_mfma_f32_16x16x32_bf16 v[46:49], v[130:133], v[204:207], v[46:49]
	v_mfma_f32_16x16x32_bf16 v[42:45], v[160:163], v[204:207], v[42:45]
	v_mfma_f32_16x16x32_bf16 v[30:33], v[130:133], v[212:215], v[30:33]
	v_mfma_f32_16x16x32_bf16 v[26:29], v[160:163], v[212:215], v[26:29]
	v_mfma_f32_16x16x32_bf16 v[14:17], v[130:133], v[220:223], v[14:17]
	v_mfma_f32_16x16x32_bf16 v[10:13], v[160:163], v[220:223], v[10:13]
	v_mfma_f32_16x16x32_bf16 v[62:65], v[134:137], v[200:203], v[62:65]
	v_mfma_f32_16x16x32_bf16 v[58:61], v[164:167], v[200:203], v[58:61]
	v_mfma_f32_16x16x32_bf16 v[46:49], v[134:137], v[208:211], v[46:49]
	v_mfma_f32_16x16x32_bf16 v[42:45], v[164:167], v[208:211], v[42:45]
	v_mfma_f32_16x16x32_bf16 v[30:33], v[134:137], v[216:219], v[30:33]
	v_mfma_f32_16x16x32_bf16 v[26:29], v[164:167], v[216:219], v[26:29]
	v_mfma_f32_16x16x32_bf16 v[14:17], v[134:137], v[224:227], v[14:17]
	v_mfma_f32_16x16x32_bf16 v[10:13], v[164:167], v[224:227], v[10:13]
	s_setprio 0
	s_setprio 1
	v_mfma_f32_16x16x32_bf16 v[54:57], v[176:179], v[196:199], v[54:57]
	v_mfma_f32_16x16x32_bf16 v[50:53], v[184:187], v[196:199], v[50:53]
	v_mfma_f32_16x16x32_bf16 v[38:41], v[176:179], v[204:207], v[38:41]
	v_mfma_f32_16x16x32_bf16 v[34:37], v[184:187], v[204:207], v[34:37]
	v_mfma_f32_16x16x32_bf16 v[22:25], v[176:179], v[212:215], v[22:25]
	v_mfma_f32_16x16x32_bf16 v[18:21], v[184:187], v[212:215], v[18:21]
	v_mfma_f32_16x16x32_bf16 v[6:9], v[176:179], v[220:223], v[6:9]
	v_mfma_f32_16x16x32_bf16 v[2:5], v[184:187], v[220:223], v[2:5]
	v_mfma_f32_16x16x32_bf16 v[54:57], v[180:183], v[200:203], v[54:57]
	v_mfma_f32_16x16x32_bf16 v[50:53], v[192:195], v[200:203], v[50:53]
	v_mfma_f32_16x16x32_bf16 v[38:41], v[180:183], v[208:211], v[38:41]
	v_mfma_f32_16x16x32_bf16 v[34:37], v[192:195], v[208:211], v[34:37]
	v_mfma_f32_16x16x32_bf16 v[22:25], v[180:183], v[216:219], v[22:25]
	v_mfma_f32_16x16x32_bf16 v[18:21], v[192:195], v[216:219], v[18:21]
	v_mfma_f32_16x16x32_bf16 v[6:9], v[180:183], v[224:227], v[6:9]
	v_mfma_f32_16x16x32_bf16 v[2:5], v[192:195], v[224:227], v[2:5]
	s_setprio 0
	s_barrier
	s_add_i32 s49, s49, 2
	s_add_u32 s5, s5, 0x100
	s_addc_u32 s47, s47, 0
	s_add_u32 s54, s54, 0x100
	s_addc_u32 s55, s55, 0
